# removed per-phase s_setprio flips in the four GEMM K-loops
# speedup vs baseline: 1.0216x; 1.0089x over previous
; #define PG8_STAGE(bufoff, gbase, voff) do { _Pragma("unroll") for (int _i = 0; _i < 2; ++_i) \
;         __builtin_amdgcn_global_load_lds((const unsigned*)((const char*)(gbase) + (voff)[_i]), (LAS unsigned*)(lds + (bufoff) + ldsw + _i * 8192), 16, 0, 0); } while (0)
; #define PG8_LDA(dst, b, h) do { _Pragma("unroll") for (int m = 0; m < 4; ++m) _Pragma("unroll") for (int k = 0; k < 2; ++k) dst[m][k] = *(const LAS bf16x8*)(lds + PG8_SA(b, h) + aoff + m * 2048 + k * 1024); } while (0)
; #define PG8_LDB(dst, b, h) do { _Pragma("unroll") for (int n = 0; n < 2; ++n) _Pragma("unroll") for (int k = 0; k < 2; ++k) dst[n][k] = *(const LAS bf16x8*)(lds + PG8_SB(b, h) + boff + n * 2048 + k * 1024); } while (0)
; #define PG8_MMA(ai, bj, At, Bt) do { __builtin_amdgcn_s_setprio(1); _Pragma("unroll") for (int m = 0; m < 4; ++m) _Pragma("unroll") for (int n = 0; n < 2; ++n) _Pragma("unroll") for (int k = 0; k < 2; ++k) \
;         acc[ai][bj][m][n] = __builtin_amdgcn_mfma_f32_16x16x32_bf16(Bt[n][k], At[m][k], acc[ai][bj][m][n], 0, 0, 0); __builtin_amdgcn_s_setprio(0); } while (0)
; #define PG8_WAIT_L(n) asm volatile("s_waitcnt lgkmcnt(" #n ")" ::: "memory")
; #define PG8_BAR __builtin_amdgcn_s_barrier()
; #define PG8_SCHED __builtin_amdgcn_sched_barrier(0)
; template <class Epi>
; DI void gemm_phase(LAS unsigned char* lds, const Gemm g, const StaticOrder& S, const Epi& E) {
;     ...
;             PG8_LDB(B0, 0, 0); PG8_SCHED; PG8_LDA(At, 0, 0); PG8_STAGE(PG8_SA(1, 1), a1 + hstep, voffA);
;             PG8_WAIT_L(8); PG8_BAR; PG8_WAIT_L(0); PG8_MMA(0, 0, At, B0); PG8_BAR; PG8_SCHED;
;             PG8_LDB(B1, 0, 1); PG8_STAGE(PG8_SB(0, 0), b2, voffB);
;             PG8_BAR; PG8_WAIT_L(0); PG8_MMA(0, 1, At, B1); PG8_BAR;
;             PG8_LDA(At, 0, 1); PG8_STAGE(PG8_SA(0, 0), a2, voffA);
;             PG8_BAR; PG8_WAIT_L(0); PG8_MMA(1, 0, At, B0); PG8_BAR; PG8_SCHED;
.LBB0_211:
	ds_read_b128 v[150:153], v147
	ds_read_b128 v[154:157], v147 offset:1024
	ds_read_b128 v[158:161], v147 offset:2048
	ds_read_b128 v[162:165], v147 offset:3072
	s_add_u32 s38, s24, 0xfffc0080
	s_addc_u32 s39, s25, -1
	s_cmp_eq_u32 s80, 12
	s_cselect_b32 s41, s17, s39
	s_cselect_b32 s40, s76, s38
	s_cselect_b32 s39, s15, s79
	s_cselect_b32 s38, s77, s78
	v_lshl_add_u64 v[178:179], s[24:25], 0, v[136:137]
	s_add_i32 m0, s13, 0xc000
	ds_read_b128 v[166:169], v148
	ds_read_b128 v[170:173], v148 offset:1024
	ds_read_b128 v[174:177], v148 offset:2048
	ds_read_b128 v[182:185], v148 offset:3072
	ds_read_b128 v[186:189], v148 offset:4096
	ds_read_b128 v[190:193], v148 offset:5120
	ds_read_b128 v[194:197], v148 offset:6144
	ds_read_b128 v[198:201], v148 offset:7168
	global_load_lds_dwordx4 v[178:179], off
	v_lshl_add_u64 v[178:179], s[24:25], 0, v[138:139]
	s_add_i32 m0, s13, 0xe000
	s_nop 0
	global_load_lds_dwordx4 v[178:179], off
	s_waitcnt lgkmcnt(8)
	s_barrier
	s_waitcnt lgkmcnt(0)
	s_waitcnt lgkmcnt(0)
	v_mfma_f32_16x16x32_bf16 v[124:127], v[150:153], v[166:169], v[124:127]
	v_mfma_f32_16x16x32_bf16 v[120:123], v[158:161], v[166:169], v[120:123]
	v_mfma_f32_16x16x32_bf16 v[116:119], v[150:153], v[174:177], v[116:119]
	v_mfma_f32_16x16x32_bf16 v[112:115], v[158:161], v[174:177], v[112:115]
	v_mfma_f32_16x16x32_bf16 v[100:103], v[150:153], v[186:189], v[100:103]
	v_mfma_f32_16x16x32_bf16 v[96:99], v[158:161], v[186:189], v[96:99]
	v_mfma_f32_16x16x32_bf16 v[84:87], v[150:153], v[194:197], v[84:87]
	v_mfma_f32_16x16x32_bf16 v[80:83], v[158:161], v[194:197], v[80:83]
	v_mfma_f32_16x16x32_bf16 v[124:127], v[154:157], v[170:173], v[124:127]
	v_mfma_f32_16x16x32_bf16 v[120:123], v[162:165], v[170:173], v[120:123]
	v_mfma_f32_16x16x32_bf16 v[116:119], v[154:157], v[182:185], v[116:119]
	v_mfma_f32_16x16x32_bf16 v[112:115], v[162:165], v[182:185], v[112:115]
	v_mfma_f32_16x16x32_bf16 v[100:103], v[154:157], v[190:193], v[100:103]
	v_mfma_f32_16x16x32_bf16 v[96:99], v[162:165], v[190:193], v[96:99]
	v_mfma_f32_16x16x32_bf16 v[84:87], v[154:157], v[198:201], v[84:87]
	v_mfma_f32_16x16x32_bf16 v[80:83], v[162:165], v[198:201], v[80:83]
	s_barrier
	s_add_i32 s81, s71, s45
	v_lshl_add_u64 v[178:179], s[38:39], 0, v[132:133]
	s_mov_b32 m0, s81
	ds_read_b128 v[202:205], v149
	ds_read_b128 v[206:209], v149 offset:1024
	ds_read_b128 v[210:213], v149 offset:2048
	ds_read_b128 v[214:217], v149 offset:3072
	global_load_lds_dwordx4 v[178:179], off
	v_lshl_add_u64 v[218:219], s[38:39], 0, v[128:129]
	s_add_i32 m0, s81, 0x2000
	s_nop 0
	global_load_lds_dwordx4 v[218:219], off
	s_barrier
	s_waitcnt lgkmcnt(0)
	s_waitcnt lgkmcnt(0)
	v_mfma_f32_16x16x32_bf16 v[108:111], v[202:205], v[166:169], v[108:111]
	v_mfma_f32_16x16x32_bf16 v[104:107], v[210:213], v[166:169], v[104:107]
	v_mfma_f32_16x16x32_bf16 v[92:95], v[202:205], v[174:177], v[92:95]
	v_mfma_f32_16x16x32_bf16 v[88:91], v[210:213], v[174:177], v[88:91]
	v_mfma_f32_16x16x32_bf16 v[76:79], v[202:205], v[186:189], v[76:79]
	v_mfma_f32_16x16x32_bf16 v[72:75], v[210:213], v[186:189], v[72:75]
	v_mfma_f32_16x16x32_bf16 v[68:71], v[202:205], v[194:197], v[68:71]
	v_mfma_f32_16x16x32_bf16 v[64:67], v[210:213], v[194:197], v[64:67]
	v_mfma_f32_16x16x32_bf16 v[108:111], v[206:209], v[170:173], v[108:111]
	v_mfma_f32_16x16x32_bf16 v[104:107], v[214:217], v[170:173], v[104:107]
	v_mfma_f32_16x16x32_bf16 v[92:95], v[206:209], v[182:185], v[92:95]
	v_mfma_f32_16x16x32_bf16 v[88:91], v[214:217], v[182:185], v[88:91]
	v_mfma_f32_16x16x32_bf16 v[76:79], v[206:209], v[190:193], v[76:79]
	v_mfma_f32_16x16x32_bf16 v[72:75], v[214:217], v[190:193], v[72:75]
	v_mfma_f32_16x16x32_bf16 v[68:71], v[206:209], v[198:201], v[68:71]
	v_mfma_f32_16x16x32_bf16 v[64:67], v[214:217], v[198:201], v[64:67]
	s_mov_b32 m0, s13
	v_lshl_add_u64 v[220:221], s[40:41], 0, v[134:135]
	s_barrier
	ds_read_b128 v[166:169], v148 offset:16384
	ds_read_b128 v[170:173], v148 offset:17408
	ds_read_b128 v[174:177], v148 offset:18432
	ds_read_b128 v[182:185], v148 offset:19456
	ds_read_b128 v[186:189], v148 offset:20480
	ds_read_b128 v[190:193], v148 offset:21504
	ds_read_b128 v[194:197], v148 offset:22528
	ds_read_b128 v[198:201], v148 offset:23552
	global_load_lds_dwordx4 v[220:221], off
	v_lshl_add_u64 v[222:223], s[40:41], 0, v[130:131]
	s_mov_b32 m0, s48
	s_nop 0
	global_load_lds_dwordx4 v[222:223], off
	s_barrier
	s_waitcnt lgkmcnt(0)
	s_waitcnt lgkmcnt(0)
	v_mfma_f32_16x16x32_bf16 v[60:63], v[150:153], v[166:169], v[60:63]
	v_mfma_f32_16x16x32_bf16 v[56:59], v[158:161], v[166:169], v[56:59]
	v_mfma_f32_16x16x32_bf16 v[52:55], v[150:153], v[174:177], v[52:55]
	v_mfma_f32_16x16x32_bf16 v[48:51], v[158:161], v[174:177], v[48:51]
	v_mfma_f32_16x16x32_bf16 v[36:39], v[150:153], v[186:189], v[36:39]
	v_mfma_f32_16x16x32_bf16 v[32:35], v[158:161], v[186:189], v[32:35]
	v_mfma_f32_16x16x32_bf16 v[20:23], v[150:153], v[194:197], v[20:23]
	v_mfma_f32_16x16x32_bf16 v[16:19], v[158:161], v[194:197], v[16:19]
	v_mfma_f32_16x16x32_bf16 v[60:63], v[154:157], v[170:173], v[60:63]
	v_mfma_f32_16x16x32_bf16 v[56:59], v[162:165], v[170:173], v[56:59]
	v_mfma_f32_16x16x32_bf16 v[52:55], v[154:157], v[182:185], v[52:55]
	v_mfma_f32_16x16x32_bf16 v[48:51], v[162:165], v[182:185], v[48:51]
	v_mfma_f32_16x16x32_bf16 v[36:39], v[154:157], v[190:193], v[36:39]
	v_mfma_f32_16x16x32_bf16 v[32:35], v[162:165], v[190:193], v[32:35]
	v_mfma_f32_16x16x32_bf16 v[20:23], v[154:157], v[198:201], v[20:23]
	v_mfma_f32_16x16x32_bf16 v[16:19], v[162:165], v[198:201], v[16:19]
	s_barrier
; #define PG8_STAGE(bufoff, gbase, voff) do { _Pragma("unroll") for (int _i = 0; _i < 2; ++_i) \
;         __builtin_amdgcn_global_load_lds((const unsigned*)((const char*)(gbase) + (voff)[_i]), (LAS unsigned*)(lds + (bufoff) + ldsw + _i * 8192), 16, 0, 0); } while (0)
; #define PG8_LDA(dst, b, h) do { _Pragma("unroll") for (int m = 0; m < 4; ++m) _Pragma("unroll") for (int k = 0; k < 2; ++k) dst[m][k] = *(const LAS bf16x8*)(lds + PG8_SA(b, h) + aoff + m * 2048 + k * 1024); } while (0)
; #define PG8_LDB(dst, b, h) do { _Pragma("unroll") for (int n = 0; n < 2; ++n) _Pragma("unroll") for (int k = 0; k < 2; ++k) dst[n][k] = *(const LAS bf16x8*)(lds + PG8_SB(b, h) + boff + n * 2048 + k * 1024); } while (0)
; #define PG8_MMA(ai, bj, At, Bt) do { __builtin_amdgcn_s_setprio(1); _Pragma("unroll") for (int m = 0; m < 4; ++m) _Pragma("unroll") for (int n = 0; n < 2; ++n) _Pragma("unroll") for (int k = 0; k < 2; ++k) \
;         acc[ai][bj][m][n] = __builtin_amdgcn_mfma_f32_16x16x32_bf16(Bt[n][k], At[m][k], acc[ai][bj][m][n], 0, 0, 0); __builtin_amdgcn_s_setprio(0); } while (0)
; #define PG8_WAIT_V(n) asm volatile("s_waitcnt vmcnt(" #n ")" ::: "memory")
; #define PG8_WAIT_L(n) asm volatile("s_waitcnt lgkmcnt(" #n ")" ::: "memory")
; #define PG8_BAR __builtin_amdgcn_s_barrier()
; #define PG8_SCHED __builtin_amdgcn_sched_barrier(0)
; template <class Epi>
; DI void gemm_phase(LAS unsigned char* lds, const Gemm g, const StaticOrder& S, const Epi& E) {
;     ...
;             PG8_STAGE(PG8_SB(0, 1), b2 + hstep, voffB);
;             PG8_WAIT_V(6); PG8_BAR; PG8_MMA(1, 1, At, B1); PG8_BAR;
;             PG8_LDB(B0, 1, 0); PG8_SCHED; PG8_LDA(At, 1, 0); PG8_STAGE(PG8_SA(0, 1), a2 + hstep, voffA);
;             PG8_WAIT_L(8); PG8_BAR; PG8_WAIT_L(0); PG8_MMA(0, 0, At, B0); PG8_BAR; PG8_SCHED;
;             PG8_LDB(B1, 1, 1); PG8_STAGE(PG8_SB(1, 0), b3, voffB);
;             PG8_BAR; PG8_WAIT_L(0); PG8_MMA(0, 1, At, B1); PG8_BAR;
;             PG8_LDA(At, 1, 1); PG8_STAGE(PG8_SA(1, 0), a3, voffA);
	s_add_u32 s82, s38, 0x40000
	s_addc_u32 s83, s39, 0
	s_add_i32 s81, s72, s45
	v_lshl_add_u64 v[150:151], s[82:83], 0, v[132:133]
	s_mov_b32 m0, s81
	s_nop 0
	global_load_lds_dwordx4 v[150:151], off
	v_lshl_add_u64 v[150:151], s[82:83], 0, v[128:129]
	s_add_i32 m0, s81, 0x2000
	s_nop 0
	global_load_lds_dwordx4 v[150:151], off
	s_waitcnt vmcnt(6)
	s_barrier
	v_mfma_f32_16x16x32_bf16 v[44:47], v[202:205], v[166:169], v[44:47]
	v_mfma_f32_16x16x32_bf16 v[40:43], v[210:213], v[166:169], v[40:43]
	v_mfma_f32_16x16x32_bf16 v[28:31], v[202:205], v[174:177], v[28:31]
	v_mfma_f32_16x16x32_bf16 v[24:27], v[210:213], v[174:177], v[24:27]
	v_mfma_f32_16x16x32_bf16 v[12:15], v[202:205], v[186:189], v[12:15]
	v_mfma_f32_16x16x32_bf16 v[8:11], v[210:213], v[186:189], v[8:11]
	v_mfma_f32_16x16x32_bf16 v[4:7], v[202:205], v[194:197], v[4:7]
	v_mfma_f32_16x16x32_bf16 v[0:3], v[210:213], v[194:197], v[0:3]
	v_mfma_f32_16x16x32_bf16 v[44:47], v[206:209], v[170:173], v[44:47]
	v_mfma_f32_16x16x32_bf16 v[40:43], v[214:217], v[170:173], v[40:43]
	v_mfma_f32_16x16x32_bf16 v[28:31], v[206:209], v[182:185], v[28:31]
	v_mfma_f32_16x16x32_bf16 v[24:27], v[214:217], v[182:185], v[24:27]
	v_mfma_f32_16x16x32_bf16 v[12:15], v[206:209], v[190:193], v[12:15]
	v_mfma_f32_16x16x32_bf16 v[8:11], v[214:217], v[190:193], v[8:11]
	v_mfma_f32_16x16x32_bf16 v[4:7], v[206:209], v[198:201], v[4:7]
	v_mfma_f32_16x16x32_bf16 v[0:3], v[214:217], v[198:201], v[0:3]
	s_add_i32 s81, 0, 0x18000
	v_add_u32_e32 v162, s81, v145
	s_barrier
	ds_read_b128 v[150:153], v162
	ds_read_b128 v[154:157], v162 offset:1024
	ds_read_b128 v[158:161], v162 offset:2048
	ds_read_b128 v[162:165], v162 offset:3072
	s_add_u32 s40, s40, 0x40000
	s_addc_u32 s41, s41, 0
	s_mov_b32 m0, s49
	v_lshl_add_u64 v[202:203], s[40:41], 0, v[134:135]
	ds_read_b128 v[166:169], v148 offset:32768
	ds_read_b128 v[170:173], v148 offset:33792
	ds_read_b128 v[174:177], v148 offset:34816
	ds_read_b128 v[182:185], v148 offset:35840
	ds_read_b128 v[186:189], v148 offset:36864
	ds_read_b128 v[190:193], v148 offset:37888
	ds_read_b128 v[194:197], v148 offset:38912
	ds_read_b128 v[198:201], v148 offset:39936
	global_load_lds_dwordx4 v[202:203], off
	v_lshl_add_u64 v[202:203], s[40:41], 0, v[130:131]
	s_mov_b32 m0, s50
	s_nop 0
	global_load_lds_dwordx4 v[202:203], off
	s_waitcnt lgkmcnt(8)
	s_barrier
	s_waitcnt lgkmcnt(0)
	s_waitcnt lgkmcnt(0)
	v_mfma_f32_16x16x32_bf16 v[124:127], v[150:153], v[166:169], v[124:127]
	v_mfma_f32_16x16x32_bf16 v[120:123], v[158:161], v[166:169], v[120:123]
	v_mfma_f32_16x16x32_bf16 v[116:119], v[150:153], v[174:177], v[116:119]
	v_mfma_f32_16x16x32_bf16 v[112:115], v[158:161], v[174:177], v[112:115]
	v_mfma_f32_16x16x32_bf16 v[100:103], v[150:153], v[186:189], v[100:103]
	v_mfma_f32_16x16x32_bf16 v[96:99], v[158:161], v[186:189], v[96:99]
	v_mfma_f32_16x16x32_bf16 v[84:87], v[150:153], v[194:197], v[84:87]
	v_mfma_f32_16x16x32_bf16 v[80:83], v[158:161], v[194:197], v[80:83]
	v_mfma_f32_16x16x32_bf16 v[124:127], v[154:157], v[170:173], v[124:127]
	v_mfma_f32_16x16x32_bf16 v[120:123], v[162:165], v[170:173], v[120:123]
	v_mfma_f32_16x16x32_bf16 v[116:119], v[154:157], v[182:185], v[116:119]
	v_mfma_f32_16x16x32_bf16 v[112:115], v[162:165], v[182:185], v[112:115]
	v_mfma_f32_16x16x32_bf16 v[100:103], v[154:157], v[190:193], v[100:103]
	v_mfma_f32_16x16x32_bf16 v[96:99], v[162:165], v[190:193], v[96:99]
	v_mfma_f32_16x16x32_bf16 v[84:87], v[154:157], v[198:201], v[84:87]
	v_mfma_f32_16x16x32_bf16 v[80:83], v[162:165], v[198:201], v[80:83]
	s_barrier
	s_add_i32 s40, 0, 0x1c000
	s_add_i32 s41, s81, s45
	v_add_u32_e32 v214, s40, v145
	v_lshl_add_u64 v[178:179], v[178:179], 0, s[8:9]
	s_mov_b32 m0, s41
	ds_read_b128 v[202:205], v214
	ds_read_b128 v[206:209], v214 offset:1024
	ds_read_b128 v[210:213], v214 offset:2048
	ds_read_b128 v[214:217], v214 offset:3072
	global_load_lds_dwordx4 v[178:179], off
	v_lshl_add_u64 v[178:179], v[218:219], 0, s[8:9]
	s_add_i32 m0, s41, 0x2000
	s_nop 0
	global_load_lds_dwordx4 v[178:179], off
	s_barrier
	s_waitcnt lgkmcnt(0)
	s_waitcnt lgkmcnt(0)
	v_mfma_f32_16x16x32_bf16 v[108:111], v[202:205], v[166:169], v[108:111]
	v_mfma_f32_16x16x32_bf16 v[104:107], v[210:213], v[166:169], v[104:107]
	v_mfma_f32_16x16x32_bf16 v[92:95], v[202:205], v[174:177], v[92:95]
	v_mfma_f32_16x16x32_bf16 v[88:91], v[210:213], v[174:177], v[88:91]
	v_mfma_f32_16x16x32_bf16 v[76:79], v[202:205], v[186:189], v[76:79]
	v_mfma_f32_16x16x32_bf16 v[72:75], v[210:213], v[186:189], v[72:75]
	v_mfma_f32_16x16x32_bf16 v[68:71], v[202:205], v[194:197], v[68:71]
	v_mfma_f32_16x16x32_bf16 v[64:67], v[210:213], v[194:197], v[64:67]
	v_mfma_f32_16x16x32_bf16 v[108:111], v[206:209], v[170:173], v[108:111]
	v_mfma_f32_16x16x32_bf16 v[104:107], v[214:217], v[170:173], v[104:107]
	v_mfma_f32_16x16x32_bf16 v[92:95], v[206:209], v[182:185], v[92:95]
	v_mfma_f32_16x16x32_bf16 v[88:91], v[214:217], v[182:185], v[88:91]
	v_mfma_f32_16x16x32_bf16 v[76:79], v[206:209], v[190:193], v[76:79]
	v_mfma_f32_16x16x32_bf16 v[72:75], v[214:217], v[190:193], v[72:75]
	v_mfma_f32_16x16x32_bf16 v[68:71], v[206:209], v[198:201], v[68:71]
	v_mfma_f32_16x16x32_bf16 v[64:67], v[214:217], v[198:201], v[64:67]
	s_mov_b32 m0, s66
	v_lshl_add_u64 v[178:179], v[220:221], 0, s[8:9]
	s_barrier
	ds_read_b128 v[166:169], v148 offset:49152
	ds_read_b128 v[170:173], v148 offset:50176
	ds_read_b128 v[174:177], v148 offset:51200
	ds_read_b128 v[182:185], v148 offset:52224
	ds_read_b128 v[186:189], v148 offset:53248
	ds_read_b128 v[190:193], v148 offset:54272
	ds_read_b128 v[194:197], v148 offset:55296
	ds_read_b128 v[198:201], v148 offset:56320
	global_load_lds_dwordx4 v[178:179], off
	v_lshl_add_u64 v[178:179], v[222:223], 0, s[8:9]
	s_mov_b32 m0, s67
	s_nop 0
	global_load_lds_dwordx4 v[178:179], off
	s_barrier
; #define PG8_STAGE(bufoff, gbase, voff) do { _Pragma("unroll") for (int _i = 0; _i < 2; ++_i) \
;         __builtin_amdgcn_global_load_lds((const unsigned*)((const char*)(gbase) + (voff)[_i]), (LAS unsigned*)(lds + (bufoff) + ldsw + _i * 8192), 16, 0, 0); } while (0)
; #define PG8_MMA(ai, bj, At, Bt) do { __builtin_amdgcn_s_setprio(1); _Pragma("unroll") for (int m = 0; m < 4; ++m) _Pragma("unroll") for (int n = 0; n < 2; ++n) _Pragma("unroll") for (int k = 0; k < 2; ++k) \
;         acc[ai][bj][m][n] = __builtin_amdgcn_mfma_f32_16x16x32_bf16(Bt[n][k], At[m][k], acc[ai][bj][m][n], 0, 0, 0); __builtin_amdgcn_s_setprio(0); } while (0)
; #define PG8_WAIT_V(n) asm volatile("s_waitcnt vmcnt(" #n ")" ::: "memory")
; #define PG8_WAIT_L(n) asm volatile("s_waitcnt lgkmcnt(" #n ")" ::: "memory")
; #define PG8_BAR __builtin_amdgcn_s_barrier()
; #define PG8_SCHED __builtin_amdgcn_sched_barrier(0)
; template <class Epi>
; DI void gemm_phase(LAS unsigned char* lds, const Gemm g, const StaticOrder& S, const Epi& E) {
;     ...
;             PG8_BAR; PG8_WAIT_L(0); PG8_MMA(1, 0, At, B0); PG8_BAR; PG8_SCHED;
;             PG8_STAGE(PG8_SB(1, 1), b3 + hstep, voffB);
;             PG8_WAIT_V(6); PG8_BAR; PG8_MMA(1, 1, At, B1); PG8_BAR;
	s_waitcnt lgkmcnt(0)
	s_waitcnt lgkmcnt(0)
	v_mfma_f32_16x16x32_bf16 v[60:63], v[150:153], v[166:169], v[60:63]
	v_mfma_f32_16x16x32_bf16 v[56:59], v[158:161], v[166:169], v[56:59]
	v_mfma_f32_16x16x32_bf16 v[52:55], v[150:153], v[174:177], v[52:55]
	v_mfma_f32_16x16x32_bf16 v[48:51], v[158:161], v[174:177], v[48:51]
	v_mfma_f32_16x16x32_bf16 v[36:39], v[150:153], v[186:189], v[36:39]
	v_mfma_f32_16x16x32_bf16 v[32:35], v[158:161], v[186:189], v[32:35]
	v_mfma_f32_16x16x32_bf16 v[20:23], v[150:153], v[194:197], v[20:23]
	v_mfma_f32_16x16x32_bf16 v[16:19], v[158:161], v[194:197], v[16:19]
	v_mfma_f32_16x16x32_bf16 v[60:63], v[154:157], v[170:173], v[60:63]
	v_mfma_f32_16x16x32_bf16 v[56:59], v[162:165], v[170:173], v[56:59]
	v_mfma_f32_16x16x32_bf16 v[52:55], v[154:157], v[182:185], v[52:55]
	v_mfma_f32_16x16x32_bf16 v[48:51], v[162:165], v[182:185], v[48:51]
	v_mfma_f32_16x16x32_bf16 v[36:39], v[154:157], v[190:193], v[36:39]
	v_mfma_f32_16x16x32_bf16 v[32:35], v[162:165], v[190:193], v[32:35]
	v_mfma_f32_16x16x32_bf16 v[20:23], v[154:157], v[198:201], v[20:23]
	v_mfma_f32_16x16x32_bf16 v[16:19], v[162:165], v[198:201], v[16:19]
	s_barrier
	s_add_u32 s38, s38, 0x40080
	s_addc_u32 s39, s39, 0
	s_add_i32 s40, s40, s45
	v_lshl_add_u64 v[150:151], s[38:39], 0, v[132:133]
	s_mov_b32 m0, s40
	s_nop 0
	global_load_lds_dwordx4 v[150:151], off
	v_lshl_add_u64 v[150:151], s[38:39], 0, v[128:129]
	s_add_i32 m0, s40, 0x2000
	s_nop 0
	global_load_lds_dwordx4 v[150:151], off
	s_waitcnt vmcnt(6)
	s_barrier
	v_mfma_f32_16x16x32_bf16 v[44:47], v[202:205], v[166:169], v[44:47]
	v_mfma_f32_16x16x32_bf16 v[40:43], v[210:213], v[166:169], v[40:43]
	v_mfma_f32_16x16x32_bf16 v[28:31], v[202:205], v[174:177], v[28:31]
	v_mfma_f32_16x16x32_bf16 v[24:27], v[210:213], v[174:177], v[24:27]
	v_mfma_f32_16x16x32_bf16 v[12:15], v[202:205], v[186:189], v[12:15]
	v_mfma_f32_16x16x32_bf16 v[8:11], v[210:213], v[186:189], v[8:11]
	v_mfma_f32_16x16x32_bf16 v[4:7], v[202:205], v[194:197], v[4:7]
	v_mfma_f32_16x16x32_bf16 v[0:3], v[210:213], v[194:197], v[0:3]
	v_mfma_f32_16x16x32_bf16 v[44:47], v[206:209], v[170:173], v[44:47]
	v_mfma_f32_16x16x32_bf16 v[40:43], v[214:217], v[170:173], v[40:43]
	v_mfma_f32_16x16x32_bf16 v[28:31], v[206:209], v[182:185], v[28:31]
	v_mfma_f32_16x16x32_bf16 v[24:27], v[214:217], v[182:185], v[24:27]
	v_mfma_f32_16x16x32_bf16 v[12:15], v[206:209], v[190:193], v[12:15]
	v_mfma_f32_16x16x32_bf16 v[8:11], v[214:217], v[190:193], v[8:11]
	v_mfma_f32_16x16x32_bf16 v[4:7], v[206:209], v[198:201], v[4:7]
	v_mfma_f32_16x16x32_bf16 v[0:3], v[214:217], v[198:201], v[0:3]
	s_add_i32 s80, s80, 2
	s_add_u32 s24, s24, 0x100
	s_addc_u32 s25, s25, 0
	s_add_u32 s78, s78, 0x100
	s_addc_u32 s79, s79, 0
	s_cmp_gt_u32 s80, 13
	s_barrier
	s_cbranch_scc0 .LBB0_211
; DI unsigned pk2(float a, float b) { f32x2 v = {a, b}; bf16x2_t r = __builtin_convertvector(v, bf16x2_t); return __builtin_bit_cast(unsigned, r); }
;     DI void operator()(const f32x4 (&acc)[2][2][4][2], const Unit& u, int wr, int wc, int fr, int fq) const {
;         const bool first = u.pn < 6; const int ldc = first ? P1W : P2W;
;         const int row0 = u.pm * BM + wr * 64 + fr, col0 = (first ? u.pn : u.pn - 6) * BM + wc * 32 + 8 * fq;
;         bf16_t* O = first ? O1 : O2;
; #pragma unroll
;         for (int ai = 0; ai < 2; ++ai)
; #pragma unroll
;             for (int m = 0; m < 4; ++m) { bf16_t* rowp = O + (size_t)(row0 + ai * HALF + m * 16) * ldc + col0;
; #pragma unroll
;                 for (int bj = 0; bj < 2; ++bj) { const f32x4 v0 = acc[ai][bj][m][0], v1 = acc[ai][bj][m][1];
;                     u32x4 w; w.x = pk2(v0[0], v0[1]); w.y = pk2(v0[2], v0[3]); w.z = pk2(v1[0], v1[1]); w.w = pk2(v1[2], v1[3]);
;                     *(u32x4*)(rowp + bj * HALF) = w; } }
	s_lshl_b32 s15, s75, 8
	s_add_i32 s17, s15, 0xfffffa00
	s_cmp_lt_i32 s75, 6
	v_lshl_add_u32 v154, s12, 8, v144
	s_cselect_b32 s12, s15, s17
	v_or_b32_e32 v150, s12, v146
	s_cselect_b32 s12, s74, 0x1ef76000
	s_cselect_b32 s38, s73, 0xa00
	s_add_u32 s24, s30, s12
	s_addc_u32 s25, s31, 0
	v_ashrrev_i32_e32 v151, 31, v150
	v_lshl_add_u64 v[150:151], v[150:151], 1, s[24:25]
	v_mad_i64_i32 v[152:153], s[24:25], s38, v154, 0
	v_cvt_pk_bf16_f32 v108, v108, v109
	v_cvt_pk_bf16_f32 v109, v110, v111
	v_cvt_pk_bf16_f32 v110, v104, v105
	v_or_b32_e32 v104, 16, v154
	v_lshl_add_u64 v[152:153], v[152:153], 1, v[150:151]
	v_cvt_pk_bf16_f32 v111, v106, v107
	v_mad_i64_i32 v[104:105], s[24:25], s38, v104, 0
	v_cvt_pk_bf16_f32 v92, v92, v93
	v_cvt_pk_bf16_f32 v93, v94, v95
	v_cvt_pk_bf16_f32 v94, v88, v89
	v_or_b32_e32 v88, 32, v154
	v_cvt_pk_bf16_f32 v124, v124, v125
	v_cvt_pk_bf16_f32 v125, v126, v127
	v_cvt_pk_bf16_f32 v126, v120, v121
	v_cvt_pk_bf16_f32 v127, v122, v123
	global_store_dwordx4 v[152:153], v[108:111], off offset:256
	v_cvt_pk_bf16_f32 v95, v90, v91
	v_mad_i64_i32 v[88:89], s[24:25], s38, v88, 0
	v_lshl_add_u64 v[108:109], v[104:105], 1, v[150:151]
	v_cvt_pk_bf16_f32 v76, v76, v77
	v_cvt_pk_bf16_f32 v77, v78, v79
	v_cvt_pk_bf16_f32 v78, v72, v73
	v_or_b32_e32 v72, 48, v154
	v_cvt_pk_bf16_f32 v68, v68, v69
	v_cvt_pk_bf16_f32 v69, v70, v71
	v_cvt_pk_bf16_f32 v70, v64, v65
	v_add_u32_e32 v64, 0x80, v154
	global_store_dwordx4 v[152:153], v[124:127], off
	v_cvt_pk_bf16_f32 v104, v116, v117
	v_cvt_pk_bf16_f32 v105, v118, v119
	v_cvt_pk_bf16_f32 v106, v112, v113
	v_cvt_pk_bf16_f32 v107, v114, v115
	global_store_dwordx4 v[108:109], v[92:95], off offset:256
	v_cvt_pk_bf16_f32 v79, v74, v75
	v_mad_i64_i32 v[72:73], s[24:25], s38, v72, 0
	v_lshl_add_u64 v[92:93], v[88:89], 1, v[150:151]
	v_mad_i64_i32 v[64:65], s[24:25], s38, v64, 0
	v_cvt_pk_bf16_f32 v44, v44, v45
	v_cvt_pk_bf16_f32 v45, v46, v47
	v_cvt_pk_bf16_f32 v46, v40, v41
	v_add_u32_e32 v40, 0x90, v154
	global_store_dwordx4 v[108:109], v[104:107], off
	v_cvt_pk_bf16_f32 v88, v100, v101
	v_cvt_pk_bf16_f32 v89, v102, v103
	v_cvt_pk_bf16_f32 v90, v96, v97
	v_cvt_pk_bf16_f32 v91, v98, v99
	global_store_dwordx4 v[92:93], v[76:79], off offset:256
	v_cvt_pk_bf16_f32 v74, v80, v81
	v_cvt_pk_bf16_f32 v75, v82, v83
	v_lshl_add_u64 v[76:77], v[72:73], 1, v[150:151]
	v_cvt_pk_bf16_f32 v72, v84, v85
	v_cvt_pk_bf16_f32 v73, v86, v87
	v_cvt_pk_bf16_f32 v71, v66, v67
	v_lshl_add_u64 v[64:65], v[64:65], 1, v[150:151]
	v_cvt_pk_bf16_f32 v47, v42, v43
	v_mad_i64_i32 v[40:41], s[24:25], s38, v40, 0
	v_cvt_pk_bf16_f32 v28, v28, v29
	v_cvt_pk_bf16_f32 v29, v30, v31
	v_cvt_pk_bf16_f32 v30, v24, v25
	v_add_u32_e32 v24, 0xa0, v154
	global_store_dwordx4 v[92:93], v[88:91], off
	global_store_dwordx4 v[76:77], v[72:75], off
	global_store_dwordx4 v[76:77], v[68:71], off offset:256
	v_cvt_pk_bf16_f32 v60, v60, v61
	v_cvt_pk_bf16_f32 v61, v62, v63
	v_cvt_pk_bf16_f32 v62, v56, v57
	v_cvt_pk_bf16_f32 v63, v58, v59
	global_store_dwordx4 v[64:65], v[44:47], off offset:256
	v_cvt_pk_bf16_f32 v31, v26, v27
	v_mad_i64_i32 v[24:25], s[24:25], s38, v24, 0
	v_lshl_add_u64 v[44:45], v[40:41], 1, v[150:151]
	v_cvt_pk_bf16_f32 v12, v12, v13
	v_cvt_pk_bf16_f32 v13, v14, v15
	v_cvt_pk_bf16_f32 v14, v8, v9
	v_add_u32_e32 v8, 0xb0, v154
	global_store_dwordx4 v[64:65], v[60:63], off
	v_cvt_pk_bf16_f32 v40, v52, v53
	v_cvt_pk_bf16_f32 v41, v54, v55
	v_cvt_pk_bf16_f32 v42, v48, v49
	v_cvt_pk_bf16_f32 v43, v50, v51
	global_store_dwordx4 v[44:45], v[28:31], off offset:256
	v_cvt_pk_bf16_f32 v15, v10, v11
	v_mad_i64_i32 v[8:9], s[24:25], s38, v8, 0
	v_lshl_add_u64 v[28:29], v[24:25], 1, v[150:151]
	global_store_dwordx4 v[44:45], v[40:43], off
	v_cvt_pk_bf16_f32 v24, v36, v37
	v_cvt_pk_bf16_f32 v25, v38, v39
	v_cvt_pk_bf16_f32 v26, v32, v33
	v_cvt_pk_bf16_f32 v27, v34, v35
	global_store_dwordx4 v[28:29], v[12:15], off offset:256
	v_cvt_pk_bf16_f32 v10, v16, v17
	v_cvt_pk_bf16_f32 v11, v18, v19
	v_lshl_add_u64 v[12:13], v[8:9], 1, v[150:151]
	v_cvt_pk_bf16_f32 v8, v20, v21
	v_cvt_pk_bf16_f32 v9, v22, v23
	v_cvt_pk_bf16_f32 v4, v4, v5
	v_cvt_pk_bf16_f32 v5, v6, v7
	v_cvt_pk_bf16_f32 v6, v0, v1
	v_cvt_pk_bf16_f32 v7, v2, v3
	s_and_b64 vcc, exec, s[4:5]
	s_mov_b32 s75, s14
	s_mov_b32 s12, s16
	s_mov_b64 s[38:39], s[22:23]
	s_mov_b64 s[24:25], s[18:19]
	global_store_dwordx4 v[28:29], v[24:27], off
	global_store_dwordx4 v[12:13], v[8:11], off
	global_store_dwordx4 v[12:13], v[4:7], off offset:256
	s_cbranch_vccz .LBB0_208
	s_waitcnt vmcnt(0)
	s_cmpk_gt_u32 s42, 0xff
	s_cbranch_scc1 .LBB0_215
	s_barrier

; #define PG8_STAGE(bufoff, gbase, voff) do { _Pragma("unroll") for (int _i = 0; _i < 2; ++_i) \
;         __builtin_amdgcn_global_load_lds((const unsigned*)((const char*)(gbase) + (voff)[_i]), (LAS unsigned*)(lds + (bufoff) + ldsw + _i * 8192), 16, 0, 0); } while (0)
; #define PG8_LDA(dst, b, h) do { _Pragma("unroll") for (int m = 0; m < 4; ++m) _Pragma("unroll") for (int k = 0; k < 2; ++k) dst[m][k] = *(const LAS bf16x8*)(lds + PG8_SA(b, h) + aoff + m * 2048 + k * 1024); } while (0)
; #define PG8_LDB(dst, b, h) do { _Pragma("unroll") for (int n = 0; n < 2; ++n) _Pragma("unroll") for (int k = 0; k < 2; ++k) dst[n][k] = *(const LAS bf16x8*)(lds + PG8_SB(b, h) + boff + n * 2048 + k * 1024); } while (0)
; #define PG8_MMA(ai, bj, At, Bt) do { __builtin_amdgcn_s_setprio(1); _Pragma("unroll") for (int m = 0; m < 4; ++m) _Pragma("unroll") for (int n = 0; n < 2; ++n) _Pragma("unroll") for (int k = 0; k < 2; ++k) \
;         acc[ai][bj][m][n] = __builtin_amdgcn_mfma_f32_16x16x32_bf16(Bt[n][k], At[m][k], acc[ai][bj][m][n], 0, 0, 0); __builtin_amdgcn_s_setprio(0); } while (0)
; #define PG8_WAIT_L(n) asm volatile("s_waitcnt lgkmcnt(" #n ")" ::: "memory")
; #define PG8_BAR __builtin_amdgcn_s_barrier()
; #define PG8_SCHED __builtin_amdgcn_sched_barrier(0)
; template <class Epi>
; DI void gemm_phase(LAS unsigned char* lds, const Gemm g, const StaticOrder& S, const Epi& E) {
;     ...
;             PG8_LDB(B0, 0, 0); PG8_SCHED; PG8_LDA(At, 0, 0); PG8_STAGE(PG8_SA(1, 1), a1 + hstep, voffA);
;             PG8_WAIT_L(8); PG8_BAR; PG8_WAIT_L(0); PG8_MMA(0, 0, At, B0); PG8_BAR; PG8_SCHED;
;             PG8_LDB(B1, 0, 1); PG8_STAGE(PG8_SB(0, 0), b2, voffB);
;             PG8_BAR; PG8_WAIT_L(0); PG8_MMA(0, 1, At, B1); PG8_BAR;
;             PG8_LDA(At, 0, 1); PG8_STAGE(PG8_SA(0, 0), a2, voffA);
;             PG8_BAR; PG8_WAIT_L(0); PG8_MMA(1, 0, At, B0); PG8_BAR; PG8_SCHED;
.LBB0_724:
	ds_read_b128 v[128:131], v165
	ds_read_b128 v[132:135], v165 offset:1024
	ds_read_b128 v[136:139], v165 offset:2048
	ds_read_b128 v[140:143], v165 offset:3072
	s_add_u32 s48, s46, 0xfffc0080
	s_addc_u32 s49, s47, -1
	s_cmp_eq_u32 s77, 12
	s_cselect_b32 s51, s39, s49
	s_cselect_b32 s50, s73, s48
	s_cselect_b32 s49, s25, s76
	s_cselect_b32 s48, s74, s75
	v_lshl_add_u64 v[160:161], s[46:47], 0, v[152:153]
	s_add_i32 m0, s45, 0xc000
	ds_read_b128 v[168:171], v166
	ds_read_b128 v[172:175], v166 offset:1024
	ds_read_b128 v[176:179], v166 offset:2048
	ds_read_b128 v[182:185], v166 offset:3072
	ds_read_b128 v[186:189], v166 offset:4096
	ds_read_b128 v[190:193], v166 offset:5120
	ds_read_b128 v[194:197], v166 offset:6144
	ds_read_b128 v[198:201], v166 offset:7168
	global_load_lds_dwordx4 v[160:161], off
	v_lshl_add_u64 v[160:161], s[46:47], 0, v[154:155]
	s_add_i32 m0, s45, 0xe000
	s_nop 0
	global_load_lds_dwordx4 v[160:161], off
	s_waitcnt lgkmcnt(8)
	s_barrier
	s_waitcnt lgkmcnt(0)
	s_waitcnt lgkmcnt(0)
	v_mfma_f32_16x16x32_bf16 v[124:127], v[128:131], v[168:171], v[124:127]
	v_mfma_f32_16x16x32_bf16 v[120:123], v[136:139], v[168:171], v[120:123]
	v_mfma_f32_16x16x32_bf16 v[108:111], v[128:131], v[176:179], v[108:111]
	v_mfma_f32_16x16x32_bf16 v[104:107], v[136:139], v[176:179], v[104:107]
	v_mfma_f32_16x16x32_bf16 v[92:95], v[128:131], v[186:189], v[92:95]
	v_mfma_f32_16x16x32_bf16 v[88:91], v[136:139], v[186:189], v[88:91]
	v_mfma_f32_16x16x32_bf16 v[76:79], v[128:131], v[194:197], v[76:79]
	v_mfma_f32_16x16x32_bf16 v[72:75], v[136:139], v[194:197], v[72:75]
	v_mfma_f32_16x16x32_bf16 v[124:127], v[132:135], v[172:175], v[124:127]
	v_mfma_f32_16x16x32_bf16 v[120:123], v[140:143], v[172:175], v[120:123]
	v_mfma_f32_16x16x32_bf16 v[108:111], v[132:135], v[182:185], v[108:111]
	v_mfma_f32_16x16x32_bf16 v[104:107], v[140:143], v[182:185], v[104:107]
	v_mfma_f32_16x16x32_bf16 v[92:95], v[132:135], v[190:193], v[92:95]
	v_mfma_f32_16x16x32_bf16 v[88:91], v[140:143], v[190:193], v[88:91]
	v_mfma_f32_16x16x32_bf16 v[76:79], v[132:135], v[198:201], v[76:79]
	v_mfma_f32_16x16x32_bf16 v[72:75], v[140:143], v[198:201], v[72:75]
	s_barrier
	s_add_i32 s78, s70, s58
	v_lshl_add_u64 v[160:161], s[48:49], 0, v[146:147]
	s_mov_b32 m0, s78
	ds_read_b128 v[202:205], v167
	ds_read_b128 v[206:209], v167 offset:1024
	ds_read_b128 v[210:213], v167 offset:2048
	ds_read_b128 v[214:217], v167 offset:3072
	global_load_lds_dwordx4 v[160:161], off
	v_lshl_add_u64 v[218:219], s[48:49], 0, v[150:151]
	s_add_i32 m0, s78, 0x2000
	s_nop 0
	global_load_lds_dwordx4 v[218:219], off
	s_barrier
	s_waitcnt lgkmcnt(0)
	s_waitcnt lgkmcnt(0)
	v_mfma_f32_16x16x32_bf16 v[116:119], v[202:205], v[168:171], v[116:119]
	v_mfma_f32_16x16x32_bf16 v[112:115], v[210:213], v[168:171], v[112:115]
	v_mfma_f32_16x16x32_bf16 v[100:103], v[202:205], v[176:179], v[100:103]
	v_mfma_f32_16x16x32_bf16 v[96:99], v[210:213], v[176:179], v[96:99]
	v_mfma_f32_16x16x32_bf16 v[84:87], v[202:205], v[186:189], v[84:87]
	v_mfma_f32_16x16x32_bf16 v[80:83], v[210:213], v[186:189], v[80:83]
	v_mfma_f32_16x16x32_bf16 v[68:71], v[202:205], v[194:197], v[68:71]
	v_mfma_f32_16x16x32_bf16 v[64:67], v[210:213], v[194:197], v[64:67]
	v_mfma_f32_16x16x32_bf16 v[116:119], v[206:209], v[172:175], v[116:119]
	v_mfma_f32_16x16x32_bf16 v[112:115], v[214:217], v[172:175], v[112:115]
	v_mfma_f32_16x16x32_bf16 v[100:103], v[206:209], v[182:185], v[100:103]
	v_mfma_f32_16x16x32_bf16 v[96:99], v[214:217], v[182:185], v[96:99]
	v_mfma_f32_16x16x32_bf16 v[84:87], v[206:209], v[190:193], v[84:87]
	v_mfma_f32_16x16x32_bf16 v[80:83], v[214:217], v[190:193], v[80:83]
	v_mfma_f32_16x16x32_bf16 v[68:71], v[206:209], v[198:201], v[68:71]
	v_mfma_f32_16x16x32_bf16 v[64:67], v[214:217], v[198:201], v[64:67]
	s_mov_b32 m0, s45
	v_lshl_add_u64 v[220:221], s[50:51], 0, v[144:145]
	s_barrier
	ds_read_b128 v[168:171], v166 offset:16384
	ds_read_b128 v[172:175], v166 offset:17408
	ds_read_b128 v[176:179], v166 offset:18432
	ds_read_b128 v[182:185], v166 offset:19456
	ds_read_b128 v[186:189], v166 offset:20480
	ds_read_b128 v[190:193], v166 offset:21504
	ds_read_b128 v[194:197], v166 offset:22528
	ds_read_b128 v[198:201], v166 offset:23552
	global_load_lds_dwordx4 v[220:221], off
	v_lshl_add_u64 v[222:223], s[50:51], 0, v[148:149]
	s_mov_b32 m0, s59
	s_nop 0
	global_load_lds_dwordx4 v[222:223], off
	s_barrier
	s_waitcnt lgkmcnt(0)
	s_waitcnt lgkmcnt(0)
	v_mfma_f32_16x16x32_bf16 v[60:63], v[128:131], v[168:171], v[60:63]
	v_mfma_f32_16x16x32_bf16 v[56:59], v[136:139], v[168:171], v[56:59]
	v_mfma_f32_16x16x32_bf16 v[44:47], v[128:131], v[176:179], v[44:47]
	v_mfma_f32_16x16x32_bf16 v[40:43], v[136:139], v[176:179], v[40:43]
	v_mfma_f32_16x16x32_bf16 v[28:31], v[128:131], v[186:189], v[28:31]
	v_mfma_f32_16x16x32_bf16 v[24:27], v[136:139], v[186:189], v[24:27]
	v_mfma_f32_16x16x32_bf16 v[12:15], v[128:131], v[194:197], v[12:15]
	v_mfma_f32_16x16x32_bf16 v[8:11], v[136:139], v[194:197], v[8:11]
	v_mfma_f32_16x16x32_bf16 v[60:63], v[132:135], v[172:175], v[60:63]
	v_mfma_f32_16x16x32_bf16 v[56:59], v[140:143], v[172:175], v[56:59]
	v_mfma_f32_16x16x32_bf16 v[44:47], v[132:135], v[182:185], v[44:47]
	v_mfma_f32_16x16x32_bf16 v[40:43], v[140:143], v[182:185], v[40:43]
	v_mfma_f32_16x16x32_bf16 v[28:31], v[132:135], v[190:193], v[28:31]
	v_mfma_f32_16x16x32_bf16 v[24:27], v[140:143], v[190:193], v[24:27]
	v_mfma_f32_16x16x32_bf16 v[12:15], v[132:135], v[198:201], v[12:15]
	v_mfma_f32_16x16x32_bf16 v[8:11], v[140:143], v[198:201], v[8:11]
	s_barrier
; #define PG8_STAGE(bufoff, gbase, voff) do { _Pragma("unroll") for (int _i = 0; _i < 2; ++_i) \
;         __builtin_amdgcn_global_load_lds((const unsigned*)((const char*)(gbase) + (voff)[_i]), (LAS unsigned*)(lds + (bufoff) + ldsw + _i * 8192), 16, 0, 0); } while (0)
; #define PG8_LDA(dst, b, h) do { _Pragma("unroll") for (int m = 0; m < 4; ++m) _Pragma("unroll") for (int k = 0; k < 2; ++k) dst[m][k] = *(const LAS bf16x8*)(lds + PG8_SA(b, h) + aoff + m * 2048 + k * 1024); } while (0)
; #define PG8_LDB(dst, b, h) do { _Pragma("unroll") for (int n = 0; n < 2; ++n) _Pragma("unroll") for (int k = 0; k < 2; ++k) dst[n][k] = *(const LAS bf16x8*)(lds + PG8_SB(b, h) + boff + n * 2048 + k * 1024); } while (0)
; #define PG8_MMA(ai, bj, At, Bt) do { __builtin_amdgcn_s_setprio(1); _Pragma("unroll") for (int m = 0; m < 4; ++m) _Pragma("unroll") for (int n = 0; n < 2; ++n) _Pragma("unroll") for (int k = 0; k < 2; ++k) \
;         acc[ai][bj][m][n] = __builtin_amdgcn_mfma_f32_16x16x32_bf16(Bt[n][k], At[m][k], acc[ai][bj][m][n], 0, 0, 0); __builtin_amdgcn_s_setprio(0); } while (0)
; #define PG8_WAIT_V(n) asm volatile("s_waitcnt vmcnt(" #n ")" ::: "memory")
; #define PG8_WAIT_L(n) asm volatile("s_waitcnt lgkmcnt(" #n ")" ::: "memory")
; #define PG8_BAR __builtin_amdgcn_s_barrier()
; #define PG8_SCHED __builtin_amdgcn_sched_barrier(0)
; template <class Epi>
; DI void gemm_phase(LAS unsigned char* lds, const Gemm g, const StaticOrder& S, const Epi& E) {
;     ...
;             PG8_STAGE(PG8_SB(0, 1), b2 + hstep, voffB);
;             PG8_WAIT_V(6); PG8_BAR; PG8_MMA(1, 1, At, B1); PG8_BAR;
;             PG8_LDB(B0, 1, 0); PG8_SCHED; PG8_LDA(At, 1, 0); PG8_STAGE(PG8_SA(0, 1), a2 + hstep, voffA);
;             PG8_WAIT_L(8); PG8_BAR; PG8_WAIT_L(0); PG8_MMA(0, 0, At, B0); PG8_BAR; PG8_SCHED;
;             PG8_LDB(B1, 1, 1); PG8_STAGE(PG8_SB(1, 0), b3, voffB);
;             PG8_BAR; PG8_WAIT_L(0); PG8_MMA(0, 1, At, B1); PG8_BAR;
	s_add_u32 s78, s48, 0x40000
	s_addc_u32 s79, s49, 0
	s_add_i32 s80, s71, s58
	v_lshl_add_u64 v[128:129], s[78:79], 0, v[146:147]
	s_mov_b32 m0, s80
	s_nop 0
	global_load_lds_dwordx4 v[128:129], off
	v_lshl_add_u64 v[128:129], s[78:79], 0, v[150:151]
	s_add_i32 m0, s80, 0x2000
	s_nop 0
	global_load_lds_dwordx4 v[128:129], off
	s_lshl_b32 s84, s44, 20
	s_lshl_b32 s85, s72, 10
	s_add_u32 s84, s84, s85
	s_add_i32 s85, s77, 2
	s_lshl_b32 s85, s85, 13
	s_add_u32 s84, s84, s85
	s_add_u32 s84, s36, s84
	s_addc_u32 s85, s37, 0
	s_waitcnt vmcnt(6)
	global_load_dword v249, v248, s[84:85]
	s_barrier
	v_mfma_f32_16x16x32_bf16 v[52:55], v[202:205], v[168:171], v[52:55]
	v_mfma_f32_16x16x32_bf16 v[48:51], v[210:213], v[168:171], v[48:51]
	v_mfma_f32_16x16x32_bf16 v[36:39], v[202:205], v[176:179], v[36:39]
	v_mfma_f32_16x16x32_bf16 v[32:35], v[210:213], v[176:179], v[32:35]
	v_mfma_f32_16x16x32_bf16 v[20:23], v[202:205], v[186:189], v[20:23]
	v_mfma_f32_16x16x32_bf16 v[16:19], v[210:213], v[186:189], v[16:19]
	v_mfma_f32_16x16x32_bf16 v[4:7], v[202:205], v[194:197], v[4:7]
	v_mfma_f32_16x16x32_bf16 v[0:3], v[210:213], v[194:197], v[0:3]
	v_mfma_f32_16x16x32_bf16 v[52:55], v[206:209], v[172:175], v[52:55]
	v_mfma_f32_16x16x32_bf16 v[48:51], v[214:217], v[172:175], v[48:51]
	v_mfma_f32_16x16x32_bf16 v[36:39], v[206:209], v[182:185], v[36:39]
	v_mfma_f32_16x16x32_bf16 v[32:35], v[214:217], v[182:185], v[32:35]
	v_mfma_f32_16x16x32_bf16 v[20:23], v[206:209], v[190:193], v[20:23]
	v_mfma_f32_16x16x32_bf16 v[16:19], v[214:217], v[190:193], v[16:19]
	v_mfma_f32_16x16x32_bf16 v[4:7], v[206:209], v[198:201], v[4:7]
	v_mfma_f32_16x16x32_bf16 v[0:3], v[214:217], v[198:201], v[0:3]
	s_add_i32 s78, 0, 0x18000
	v_add_u32_e32 v140, s78, v163
	s_barrier
	ds_read_b128 v[128:131], v140
	ds_read_b128 v[132:135], v140 offset:1024
	ds_read_b128 v[136:139], v140 offset:2048
	ds_read_b128 v[140:143], v140 offset:3072
	s_add_u32 s50, s50, 0x40000
	s_addc_u32 s51, s51, 0
	s_mov_b32 m0, s60
	v_lshl_add_u64 v[202:203], s[50:51], 0, v[144:145]
	ds_read_b128 v[168:171], v166 offset:32768
	ds_read_b128 v[172:175], v166 offset:33792
	ds_read_b128 v[176:179], v166 offset:34816
	ds_read_b128 v[182:185], v166 offset:35840
	ds_read_b128 v[186:189], v166 offset:36864
	ds_read_b128 v[190:193], v166 offset:37888
	ds_read_b128 v[194:197], v166 offset:38912
	ds_read_b128 v[198:201], v166 offset:39936
	global_load_lds_dwordx4 v[202:203], off
	v_lshl_add_u64 v[202:203], s[50:51], 0, v[148:149]
	s_mov_b32 m0, s61
	s_nop 0
	global_load_lds_dwordx4 v[202:203], off
	s_waitcnt lgkmcnt(8)
	s_barrier
	s_waitcnt lgkmcnt(0)
	s_waitcnt lgkmcnt(0)
	v_mfma_f32_16x16x32_bf16 v[124:127], v[128:131], v[168:171], v[124:127]
	v_mfma_f32_16x16x32_bf16 v[120:123], v[136:139], v[168:171], v[120:123]
	v_mfma_f32_16x16x32_bf16 v[108:111], v[128:131], v[176:179], v[108:111]
	v_mfma_f32_16x16x32_bf16 v[104:107], v[136:139], v[176:179], v[104:107]
	v_mfma_f32_16x16x32_bf16 v[92:95], v[128:131], v[186:189], v[92:95]
	v_mfma_f32_16x16x32_bf16 v[88:91], v[136:139], v[186:189], v[88:91]
	v_mfma_f32_16x16x32_bf16 v[76:79], v[128:131], v[194:197], v[76:79]
	v_mfma_f32_16x16x32_bf16 v[72:75], v[136:139], v[194:197], v[72:75]
	v_mfma_f32_16x16x32_bf16 v[124:127], v[132:135], v[172:175], v[124:127]
	v_mfma_f32_16x16x32_bf16 v[120:123], v[140:143], v[172:175], v[120:123]
	v_mfma_f32_16x16x32_bf16 v[108:111], v[132:135], v[182:185], v[108:111]
	v_mfma_f32_16x16x32_bf16 v[104:107], v[140:143], v[182:185], v[104:107]
	v_mfma_f32_16x16x32_bf16 v[92:95], v[132:135], v[190:193], v[92:95]
	v_mfma_f32_16x16x32_bf16 v[88:91], v[140:143], v[190:193], v[88:91]
	v_mfma_f32_16x16x32_bf16 v[76:79], v[132:135], v[198:201], v[76:79]
	v_mfma_f32_16x16x32_bf16 v[72:75], v[140:143], v[198:201], v[72:75]
	s_barrier
	s_add_i32 s50, 0, 0x1c000
	s_add_i32 s51, s78, s58
	v_add_u32_e32 v214, s50, v163
	v_lshl_add_u64 v[160:161], v[160:161], 0, s[12:13]
	s_mov_b32 m0, s51
	ds_read_b128 v[202:205], v214
	ds_read_b128 v[206:209], v214 offset:1024
	ds_read_b128 v[210:213], v214 offset:2048
	ds_read_b128 v[214:217], v214 offset:3072
	global_load_lds_dwordx4 v[160:161], off
	v_lshl_add_u64 v[160:161], v[218:219], 0, s[12:13]
	s_add_i32 m0, s51, 0x2000
	s_nop 0
	global_load_lds_dwordx4 v[160:161], off
	s_barrier
	s_waitcnt lgkmcnt(0)
	s_waitcnt lgkmcnt(0)
	v_mfma_f32_16x16x32_bf16 v[116:119], v[202:205], v[168:171], v[116:119]
	v_mfma_f32_16x16x32_bf16 v[112:115], v[210:213], v[168:171], v[112:115]
	v_mfma_f32_16x16x32_bf16 v[100:103], v[202:205], v[176:179], v[100:103]
	v_mfma_f32_16x16x32_bf16 v[96:99], v[210:213], v[176:179], v[96:99]
	v_mfma_f32_16x16x32_bf16 v[84:87], v[202:205], v[186:189], v[84:87]
	v_mfma_f32_16x16x32_bf16 v[80:83], v[210:213], v[186:189], v[80:83]
	v_mfma_f32_16x16x32_bf16 v[68:71], v[202:205], v[194:197], v[68:71]
	v_mfma_f32_16x16x32_bf16 v[64:67], v[210:213], v[194:197], v[64:67]
	v_mfma_f32_16x16x32_bf16 v[116:119], v[206:209], v[172:175], v[116:119]
	v_mfma_f32_16x16x32_bf16 v[112:115], v[214:217], v[172:175], v[112:115]
	v_mfma_f32_16x16x32_bf16 v[100:103], v[206:209], v[182:185], v[100:103]
	v_mfma_f32_16x16x32_bf16 v[96:99], v[214:217], v[182:185], v[96:99]
	v_mfma_f32_16x16x32_bf16 v[84:87], v[206:209], v[190:193], v[84:87]
	v_mfma_f32_16x16x32_bf16 v[80:83], v[214:217], v[190:193], v[80:83]
	v_mfma_f32_16x16x32_bf16 v[68:71], v[206:209], v[198:201], v[68:71]
	v_mfma_f32_16x16x32_bf16 v[64:67], v[214:217], v[198:201], v[64:67]
	s_mov_b32 m0, s65
	v_lshl_add_u64 v[160:161], v[220:221], 0, s[12:13]
	s_barrier
; DI unsigned pk2(float a, float b) { f32x2 v = {a, b}; bf16x2_t r = __builtin_convertvector(v, bf16x2_t); return __builtin_bit_cast(unsigned, r); }
; #define PG8_STAGE(bufoff, gbase, voff) do { _Pragma("unroll") for (int _i = 0; _i < 2; ++_i) \
;         __builtin_amdgcn_global_load_lds((const unsigned*)((const char*)(gbase) + (voff)[_i]), (LAS unsigned*)(lds + (bufoff) + ldsw + _i * 8192), 16, 0, 0); } while (0)
; #define PG8_LDA(dst, b, h) do { _Pragma("unroll") for (int m = 0; m < 4; ++m) _Pragma("unroll") for (int k = 0; k < 2; ++k) dst[m][k] = *(const LAS bf16x8*)(lds + PG8_SA(b, h) + aoff + m * 2048 + k * 1024); } while (0)
; #define PG8_WAIT_V(n) asm volatile("s_waitcnt vmcnt(" #n ")" ::: "memory")
; #define PG8_WAIT_L(n) asm volatile("s_waitcnt lgkmcnt(" #n ")" ::: "memory")
; #define PG8_BAR __builtin_amdgcn_s_barrier()
; template <class Epi>
; DI void gemm_phase(LAS unsigned char* lds, const Gemm g, const StaticOrder& S, const Epi& E) {
;     ...
;             PG8_LDA(At, 1, 1); PG8_STAGE(PG8_SA(1, 0), a3, voffA);
;             PG8_BAR; PG8_WAIT_L(0); PG8_MMA(1, 0, At, B0); PG8_BAR; PG8_SCHED;
;             PG8_STAGE(PG8_SB(1, 1), b3 + hstep, voffB);
;             PG8_WAIT_V(6); PG8_BAR; PG8_MMA(1, 1, At, B1); PG8_BAR;
;     DI void operator()(const f32x4 (&acc)[2][2][4][2], const Unit& u, int wr, int wc, int fr, int fq) const {
;         const int row0 = u.pm * BM + wr * 64 + fr, col0 = u.pn * BM + wc * 32 + 8 * fq;
;         const float* gp = gate + (size_t)((u.pm * BM) >> 12) * NMODC + col0;
;         f32x4 gv[2][2];
; #pragma unroll
;         for (int bj = 0; bj < 2; ++bj)
; #pragma unroll
;             for (int n = 0; n < 2; ++n) gv[bj][n] = *(const f32x4*)(gp + bj * HALF + n * 4);
; #pragma unroll
;         for (int ai = 0; ai < 2; ++ai)
; #pragma unroll
;             for (int m = 0; m < 4; ++m) { const size_t ro = (size_t)(row0 + ai * HALF + m * 16) * DM + col0;
; #pragma unroll
;                 for (int bj = 0; bj < 2; ++bj) {
;                     const f32x4 x0 = *(const f32x4*)(base + ro + bj * HALF) + gv[bj][0] * acc[ai][bj][m][0], x1 = *(const f32x4*)(base + ro + bj * HALF + 4) + gv[bj][1] * acc[ai][bj][m][1];
;                     u32x4 w; w.x = pk2(x0.x, x0.y); w.y = pk2(x0.z, x0.w); w.z = pk2(x1.x, x1.y); w.w = pk2(x1.z, x1.w);
;                     *(u32x4*)(outb + ro + bj * HALF) = w; } }
	ds_read_b128 v[168:171], v166 offset:49152
	ds_read_b128 v[172:175], v166 offset:50176
	ds_read_b128 v[176:179], v166 offset:51200
	ds_read_b128 v[182:185], v166 offset:52224
	ds_read_b128 v[186:189], v166 offset:53248
	ds_read_b128 v[190:193], v166 offset:54272
	ds_read_b128 v[194:197], v166 offset:55296
	ds_read_b128 v[198:201], v166 offset:56320
	global_load_lds_dwordx4 v[160:161], off
	v_lshl_add_u64 v[160:161], v[222:223], 0, s[12:13]
	s_mov_b32 m0, s66
	s_nop 0
	global_load_lds_dwordx4 v[160:161], off
	s_barrier
	s_waitcnt lgkmcnt(0)
	s_waitcnt lgkmcnt(0)
	v_mfma_f32_16x16x32_bf16 v[60:63], v[128:131], v[168:171], v[60:63]
	v_mfma_f32_16x16x32_bf16 v[56:59], v[136:139], v[168:171], v[56:59]
	v_mfma_f32_16x16x32_bf16 v[44:47], v[128:131], v[176:179], v[44:47]
	v_mfma_f32_16x16x32_bf16 v[40:43], v[136:139], v[176:179], v[40:43]
	v_mfma_f32_16x16x32_bf16 v[28:31], v[128:131], v[186:189], v[28:31]
	v_mfma_f32_16x16x32_bf16 v[24:27], v[136:139], v[186:189], v[24:27]
	v_mfma_f32_16x16x32_bf16 v[12:15], v[128:131], v[194:197], v[12:15]
	v_mfma_f32_16x16x32_bf16 v[8:11], v[136:139], v[194:197], v[8:11]
	v_mfma_f32_16x16x32_bf16 v[60:63], v[132:135], v[172:175], v[60:63]
	v_mfma_f32_16x16x32_bf16 v[56:59], v[140:143], v[172:175], v[56:59]
	v_mfma_f32_16x16x32_bf16 v[44:47], v[132:135], v[182:185], v[44:47]
	v_mfma_f32_16x16x32_bf16 v[40:43], v[140:143], v[182:185], v[40:43]
	v_mfma_f32_16x16x32_bf16 v[28:31], v[132:135], v[190:193], v[28:31]
	v_mfma_f32_16x16x32_bf16 v[24:27], v[140:143], v[190:193], v[24:27]
	v_mfma_f32_16x16x32_bf16 v[12:15], v[132:135], v[198:201], v[12:15]
	v_mfma_f32_16x16x32_bf16 v[8:11], v[140:143], v[198:201], v[8:11]
	s_barrier
	s_add_u32 s48, s48, 0x40080
	s_addc_u32 s49, s49, 0
	s_add_i32 s50, s50, s58
	v_lshl_add_u64 v[128:129], s[48:49], 0, v[146:147]
	s_mov_b32 m0, s50
	s_nop 0
	global_load_lds_dwordx4 v[128:129], off
	v_lshl_add_u64 v[128:129], s[48:49], 0, v[150:151]
	s_add_i32 m0, s50, 0x2000
	s_nop 0
	global_load_lds_dwordx4 v[128:129], off
	s_waitcnt vmcnt(6)
	s_barrier
	v_mfma_f32_16x16x32_bf16 v[52:55], v[202:205], v[168:171], v[52:55]
	v_mfma_f32_16x16x32_bf16 v[48:51], v[210:213], v[168:171], v[48:51]
	v_mfma_f32_16x16x32_bf16 v[36:39], v[202:205], v[176:179], v[36:39]
	v_mfma_f32_16x16x32_bf16 v[32:35], v[210:213], v[176:179], v[32:35]
	v_mfma_f32_16x16x32_bf16 v[20:23], v[202:205], v[186:189], v[20:23]
	v_mfma_f32_16x16x32_bf16 v[16:19], v[210:213], v[186:189], v[16:19]
	v_mfma_f32_16x16x32_bf16 v[4:7], v[202:205], v[194:197], v[4:7]
	v_mfma_f32_16x16x32_bf16 v[0:3], v[210:213], v[194:197], v[0:3]
	v_mfma_f32_16x16x32_bf16 v[52:55], v[206:209], v[172:175], v[52:55]
	v_mfma_f32_16x16x32_bf16 v[48:51], v[214:217], v[172:175], v[48:51]
	v_mfma_f32_16x16x32_bf16 v[36:39], v[206:209], v[182:185], v[36:39]
	v_mfma_f32_16x16x32_bf16 v[32:35], v[214:217], v[182:185], v[32:35]
	v_mfma_f32_16x16x32_bf16 v[20:23], v[206:209], v[190:193], v[20:23]
	v_mfma_f32_16x16x32_bf16 v[16:19], v[214:217], v[190:193], v[16:19]
	v_mfma_f32_16x16x32_bf16 v[4:7], v[206:209], v[198:201], v[4:7]
	v_mfma_f32_16x16x32_bf16 v[0:3], v[214:217], v[198:201], v[0:3]
	s_add_i32 s77, s77, 2
	s_add_u32 s46, s46, 0x100
	s_addc_u32 s47, s47, 0
	s_add_u32 s75, s75, 0x100
	s_addc_u32 s76, s76, 0
	s_cmp_gt_u32 s77, 13
	s_barrier
	s_cbranch_scc0 .LBB0_724
	v_lshl_add_u32 v171, s44, 8, v162
	v_lshl_or_b32 v172, s72, 8, v164
	s_ashr_i32 s25, s44, 4
	s_mul_hi_i32 s39, s25, 0x6000
	s_mulk_i32 s25, 0x6000
	s_add_u32 s46, s63, s25
	s_addc_u32 s47, s64, s39
	v_lshlrev_b32_e32 v168, 2, v172
	v_lshlrev_b32_e32 v160, 12, v171
	v_lshlrev_b32_e32 v161, 11, v171
	global_load_dwordx4 v[128:131], v168, s[46:47]
	global_load_dwordx4 v[132:135], v168, s[46:47] offset:16
	global_load_dwordx4 v[136:139], v168, s[46:47] offset:512
	global_load_dwordx4 v[140:143], v168, s[46:47] offset:528
	v_lshl_add_u32 v160, v172, 2, v160
	v_lshl_add_u32 v161, v172, 1, v161
	s_mov_b32 s72, s24
	s_mov_b32 s44, s38
	s_mov_b64 s[48:49], s[42:43]
	s_mov_b64 s[46:47], s[40:41]
	global_load_dwordx4 v[184:187], v160, s[36:37]
	global_load_dwordx4 v[188:191], v160, s[36:37] offset:16
	global_load_dwordx4 v[192:195], v160, s[36:37] offset:512
	global_load_dwordx4 v[196:199], v160, s[36:37] offset:528
	v_add_u32_e32 v169, 0x10000, v160
	global_load_dwordx4 v[200:203], v169, s[36:37]
	global_load_dwordx4 v[204:207], v169, s[36:37] offset:16
	v_add_u32_e32 v169, 0x10000, v160
	global_load_dwordx4 v[208:211], v169, s[36:37] offset:512
	global_load_dwordx4 v[212:215], v169, s[36:37] offset:528
	v_add_u32_e32 v169, 0x20000, v160
	global_load_dwordx4 v[216:219], v169, s[36:37]
	global_load_dwordx4 v[220:223], v169, s[36:37] offset:16
	v_add_u32_e32 v169, 0x20000, v160
	global_load_dwordx4 v[224:227], v169, s[36:37] offset:512
	global_load_dwordx4 v[228:231], v169, s[36:37] offset:528
	v_add_u32_e32 v169, 0x30000, v160
	global_load_dwordx4 v[232:235], v169, s[36:37]
	global_load_dwordx4 v[236:239], v169, s[36:37] offset:16
	v_add_u32_e32 v169, 0x30000, v160
	global_load_dwordx4 v[240:243], v169, s[36:37] offset:512
	global_load_dwordx4 v[244:247], v169, s[36:37] offset:528
	s_waitcnt vmcnt(14)
	v_pk_fma_f32 v[124:125], v[124:125], v[128:129], v[184:185]
	v_pk_fma_f32 v[126:127], v[126:127], v[130:131], v[186:187]
	v_pk_fma_f32 v[120:121], v[120:121], v[132:133], v[188:189]
	v_pk_fma_f32 v[122:123], v[122:123], v[134:135], v[190:191]
	v_add_u32_e32 v169, 0x80000, v160
	global_load_dwordx4 v[184:187], v169, s[36:37]
	global_load_dwordx4 v[188:191], v169, s[36:37] offset:16
	v_cvt_pk_bf16_f32 v124, v124, v125
	v_cvt_pk_bf16_f32 v125, v126, v127
	v_cvt_pk_bf16_f32 v126, v120, v121
	v_cvt_pk_bf16_f32 v127, v122, v123
	global_store_dwordx4 v161, v[124:127], s[8:9]
	s_waitcnt vmcnt(15)
; DI unsigned pk2(float a, float b) { f32x2 v = {a, b}; bf16x2_t r = __builtin_convertvector(v, bf16x2_t); return __builtin_bit_cast(unsigned, r); }
;     DI void operator()(const f32x4 (&acc)[2][2][4][2], const Unit& u, int wr, int wc, int fr, int fq) const {
;     ...
; #pragma unroll
;         for (int ai = 0; ai < 2; ++ai)
; #pragma unroll
;             for (int m = 0; m < 4; ++m) { const size_t ro = (size_t)(row0 + ai * HALF + m * 16) * DM + col0;
; #pragma unroll
;                 for (int bj = 0; bj < 2; ++bj) {
;                     const f32x4 x0 = *(const f32x4*)(base + ro + bj * HALF) + gv[bj][0] * acc[ai][bj][m][0], x1 = *(const f32x4*)(base + ro + bj * HALF + 4) + gv[bj][1] * acc[ai][bj][m][1];
;                     u32x4 w; w.x = pk2(x0.x, x0.y); w.y = pk2(x0.z, x0.w); w.z = pk2(x1.x, x1.y); w.w = pk2(x1.z, x1.w);
;                     *(u32x4*)(outb + ro + bj * HALF) = w; } }
	v_pk_fma_f32 v[116:117], v[116:117], v[136:137], v[192:193]
	v_pk_fma_f32 v[118:119], v[118:119], v[138:139], v[194:195]
	v_pk_fma_f32 v[112:113], v[112:113], v[140:141], v[196:197]
	v_pk_fma_f32 v[114:115], v[114:115], v[142:143], v[198:199]
	v_add_u32_e32 v169, 0x80000, v160
	global_load_dwordx4 v[192:195], v169, s[36:37] offset:512
	global_load_dwordx4 v[196:199], v169, s[36:37] offset:528
	v_cvt_pk_bf16_f32 v116, v116, v117
	v_cvt_pk_bf16_f32 v117, v118, v119
	v_cvt_pk_bf16_f32 v118, v112, v113
	v_cvt_pk_bf16_f32 v119, v114, v115
	global_store_dwordx4 v161, v[116:119], s[8:9] offset:256
	s_waitcnt vmcnt(16)
	v_pk_fma_f32 v[108:109], v[108:109], v[128:129], v[200:201]
	v_pk_fma_f32 v[110:111], v[110:111], v[130:131], v[202:203]
	v_pk_fma_f32 v[104:105], v[104:105], v[132:133], v[204:205]
	v_pk_fma_f32 v[106:107], v[106:107], v[134:135], v[206:207]
	v_add_u32_e32 v169, 0x90000, v160
	global_load_dwordx4 v[200:203], v169, s[36:37]
	global_load_dwordx4 v[204:207], v169, s[36:37] offset:16
	v_cvt_pk_bf16_f32 v108, v108, v109
	v_cvt_pk_bf16_f32 v109, v110, v111
	v_cvt_pk_bf16_f32 v110, v104, v105
	v_cvt_pk_bf16_f32 v111, v106, v107
	v_add_u32_e32 v170, 0x8000, v161
	global_store_dwordx4 v170, v[108:111], s[8:9]
	s_waitcnt vmcnt(17)
	v_pk_fma_f32 v[100:101], v[100:101], v[136:137], v[208:209]
	v_pk_fma_f32 v[102:103], v[102:103], v[138:139], v[210:211]
	v_pk_fma_f32 v[96:97], v[96:97], v[140:141], v[212:213]
	v_pk_fma_f32 v[98:99], v[98:99], v[142:143], v[214:215]
	v_add_u32_e32 v169, 0x90000, v160
	global_load_dwordx4 v[208:211], v169, s[36:37] offset:512
	global_load_dwordx4 v[212:215], v169, s[36:37] offset:528
	v_cvt_pk_bf16_f32 v100, v100, v101
	v_cvt_pk_bf16_f32 v101, v102, v103
	v_cvt_pk_bf16_f32 v102, v96, v97
	v_cvt_pk_bf16_f32 v103, v98, v99
	v_add_u32_e32 v170, 0x8000, v161
	global_store_dwordx4 v170, v[100:103], s[8:9] offset:256
	s_waitcnt vmcnt(18)
	v_pk_fma_f32 v[92:93], v[92:93], v[128:129], v[216:217]
	v_pk_fma_f32 v[94:95], v[94:95], v[130:131], v[218:219]
	v_pk_fma_f32 v[88:89], v[88:89], v[132:133], v[220:221]
	v_pk_fma_f32 v[90:91], v[90:91], v[134:135], v[222:223]
	v_add_u32_e32 v169, 0xa0000, v160
	global_load_dwordx4 v[216:219], v169, s[36:37]
	global_load_dwordx4 v[220:223], v169, s[36:37] offset:16
	v_cvt_pk_bf16_f32 v92, v92, v93
	v_cvt_pk_bf16_f32 v93, v94, v95
	v_cvt_pk_bf16_f32 v94, v88, v89
	v_cvt_pk_bf16_f32 v95, v90, v91
	v_add_u32_e32 v170, 0x10000, v161
	global_store_dwordx4 v170, v[92:95], s[8:9]
	s_waitcnt vmcnt(19)
	v_pk_fma_f32 v[84:85], v[84:85], v[136:137], v[224:225]
	v_pk_fma_f32 v[86:87], v[86:87], v[138:139], v[226:227]
	v_pk_fma_f32 v[80:81], v[80:81], v[140:141], v[228:229]
	v_pk_fma_f32 v[82:83], v[82:83], v[142:143], v[230:231]
	v_add_u32_e32 v169, 0xa0000, v160
	global_load_dwordx4 v[224:227], v169, s[36:37] offset:512
	global_load_dwordx4 v[228:231], v169, s[36:37] offset:528
	v_cvt_pk_bf16_f32 v84, v84, v85
	v_cvt_pk_bf16_f32 v85, v86, v87
	v_cvt_pk_bf16_f32 v86, v80, v81
	v_cvt_pk_bf16_f32 v87, v82, v83
	v_add_u32_e32 v170, 0x10000, v161
	global_store_dwordx4 v170, v[84:87], s[8:9] offset:256
	s_waitcnt vmcnt(20)
	v_pk_fma_f32 v[76:77], v[76:77], v[128:129], v[232:233]
	v_pk_fma_f32 v[78:79], v[78:79], v[130:131], v[234:235]
	v_pk_fma_f32 v[72:73], v[72:73], v[132:133], v[236:237]
	v_pk_fma_f32 v[74:75], v[74:75], v[134:135], v[238:239]
	v_add_u32_e32 v169, 0xb0000, v160
	global_load_dwordx4 v[232:235], v169, s[36:37]
	global_load_dwordx4 v[236:239], v169, s[36:37] offset:16
	v_cvt_pk_bf16_f32 v76, v76, v77
	v_cvt_pk_bf16_f32 v77, v78, v79
	v_cvt_pk_bf16_f32 v78, v72, v73
	v_cvt_pk_bf16_f32 v79, v74, v75
	v_add_u32_e32 v170, 0x18000, v161
	global_store_dwordx4 v170, v[76:79], s[8:9]
	s_waitcnt vmcnt(21)
	v_pk_fma_f32 v[68:69], v[68:69], v[136:137], v[240:241]
	v_pk_fma_f32 v[70:71], v[70:71], v[138:139], v[242:243]
	v_pk_fma_f32 v[64:65], v[64:65], v[140:141], v[244:245]
	v_pk_fma_f32 v[66:67], v[66:67], v[142:143], v[246:247]
	v_add_u32_e32 v169, 0xb0000, v160
	global_load_dwordx4 v[240:243], v169, s[36:37] offset:512
	global_load_dwordx4 v[244:247], v169, s[36:37] offset:528
	v_cvt_pk_bf16_f32 v68, v68, v69
	v_cvt_pk_bf16_f32 v69, v70, v71
	v_cvt_pk_bf16_f32 v70, v64, v65
	v_cvt_pk_bf16_f32 v71, v66, v67
	v_add_u32_e32 v170, 0x18000, v161
	global_store_dwordx4 v170, v[68:71], s[8:9] offset:256
	s_waitcnt vmcnt(22)
; DI unsigned pk2(float a, float b) { f32x2 v = {a, b}; bf16x2_t r = __builtin_convertvector(v, bf16x2_t); return __builtin_bit_cast(unsigned, r); }
;     DI void operator()(const f32x4 (&acc)[2][2][4][2], const Unit& u, int wr, int wc, int fr, int fq) const {
;     ...
; #pragma unroll
;         for (int ai = 0; ai < 2; ++ai)
; #pragma unroll
;             for (int m = 0; m < 4; ++m) { const size_t ro = (size_t)(row0 + ai * HALF + m * 16) * DM + col0;
; #pragma unroll
;                 for (int bj = 0; bj < 2; ++bj) {
;                     const f32x4 x0 = *(const f32x4*)(base + ro + bj * HALF) + gv[bj][0] * acc[ai][bj][m][0], x1 = *(const f32x4*)(base + ro + bj * HALF + 4) + gv[bj][1] * acc[ai][bj][m][1];
;                     u32x4 w; w.x = pk2(x0.x, x0.y); w.y = pk2(x0.z, x0.w); w.z = pk2(x1.x, x1.y); w.w = pk2(x1.z, x1.w);
;                     *(u32x4*)(outb + ro + bj * HALF) = w; } }
	v_pk_fma_f32 v[60:61], v[60:61], v[128:129], v[184:185]
	v_pk_fma_f32 v[62:63], v[62:63], v[130:131], v[186:187]
	v_pk_fma_f32 v[56:57], v[56:57], v[132:133], v[188:189]
	v_pk_fma_f32 v[58:59], v[58:59], v[134:135], v[190:191]
	v_cvt_pk_bf16_f32 v60, v60, v61
	v_cvt_pk_bf16_f32 v61, v62, v63
	v_cvt_pk_bf16_f32 v62, v56, v57
	v_cvt_pk_bf16_f32 v63, v58, v59
	v_add_u32_e32 v170, 0x40000, v161
	global_store_dwordx4 v170, v[60:63], s[8:9]
	s_waitcnt vmcnt(20)
	v_pk_fma_f32 v[52:53], v[52:53], v[136:137], v[192:193]
	v_pk_fma_f32 v[54:55], v[54:55], v[138:139], v[194:195]
	v_pk_fma_f32 v[48:49], v[48:49], v[140:141], v[196:197]
	v_pk_fma_f32 v[50:51], v[50:51], v[142:143], v[198:199]
	v_cvt_pk_bf16_f32 v52, v52, v53
	v_cvt_pk_bf16_f32 v53, v54, v55
	v_cvt_pk_bf16_f32 v54, v48, v49
	v_cvt_pk_bf16_f32 v55, v50, v51
	v_add_u32_e32 v170, 0x40000, v161
	global_store_dwordx4 v170, v[52:55], s[8:9] offset:256
	s_waitcnt vmcnt(18)
	v_pk_fma_f32 v[44:45], v[44:45], v[128:129], v[200:201]
	v_pk_fma_f32 v[46:47], v[46:47], v[130:131], v[202:203]
	v_pk_fma_f32 v[40:41], v[40:41], v[132:133], v[204:205]
	v_pk_fma_f32 v[42:43], v[42:43], v[134:135], v[206:207]
	v_cvt_pk_bf16_f32 v44, v44, v45
	v_cvt_pk_bf16_f32 v45, v46, v47
	v_cvt_pk_bf16_f32 v46, v40, v41
	v_cvt_pk_bf16_f32 v47, v42, v43
	v_add_u32_e32 v170, 0x48000, v161
	global_store_dwordx4 v170, v[44:47], s[8:9]
	s_waitcnt vmcnt(16)
	v_pk_fma_f32 v[36:37], v[36:37], v[136:137], v[208:209]
	v_pk_fma_f32 v[38:39], v[38:39], v[138:139], v[210:211]
	v_pk_fma_f32 v[32:33], v[32:33], v[140:141], v[212:213]
	v_pk_fma_f32 v[34:35], v[34:35], v[142:143], v[214:215]
	v_cvt_pk_bf16_f32 v36, v36, v37
	v_cvt_pk_bf16_f32 v37, v38, v39
	v_cvt_pk_bf16_f32 v38, v32, v33
	v_cvt_pk_bf16_f32 v39, v34, v35
	v_add_u32_e32 v170, 0x48000, v161
	global_store_dwordx4 v170, v[36:39], s[8:9] offset:256
	s_waitcnt vmcnt(14)
	v_pk_fma_f32 v[28:29], v[28:29], v[128:129], v[216:217]
	v_pk_fma_f32 v[30:31], v[30:31], v[130:131], v[218:219]
	v_pk_fma_f32 v[24:25], v[24:25], v[132:133], v[220:221]
	v_pk_fma_f32 v[26:27], v[26:27], v[134:135], v[222:223]
	v_cvt_pk_bf16_f32 v28, v28, v29
	v_cvt_pk_bf16_f32 v29, v30, v31
	v_cvt_pk_bf16_f32 v30, v24, v25
	v_cvt_pk_bf16_f32 v31, v26, v27
	v_add_u32_e32 v170, 0x50000, v161
	global_store_dwordx4 v170, v[28:31], s[8:9]
	s_waitcnt vmcnt(12)
	v_pk_fma_f32 v[20:21], v[20:21], v[136:137], v[224:225]
	v_pk_fma_f32 v[22:23], v[22:23], v[138:139], v[226:227]
	v_pk_fma_f32 v[16:17], v[16:17], v[140:141], v[228:229]
	v_pk_fma_f32 v[18:19], v[18:19], v[142:143], v[230:231]
	v_cvt_pk_bf16_f32 v20, v20, v21
	v_cvt_pk_bf16_f32 v21, v22, v23
	v_cvt_pk_bf16_f32 v22, v16, v17
	v_cvt_pk_bf16_f32 v23, v18, v19
	v_add_u32_e32 v170, 0x50000, v161
	global_store_dwordx4 v170, v[20:23], s[8:9] offset:256
	s_waitcnt vmcnt(10)
	v_pk_fma_f32 v[12:13], v[12:13], v[128:129], v[232:233]
	v_pk_fma_f32 v[14:15], v[14:15], v[130:131], v[234:235]
	v_pk_fma_f32 v[8:9], v[8:9], v[132:133], v[236:237]
	v_pk_fma_f32 v[10:11], v[10:11], v[134:135], v[238:239]
	v_cvt_pk_bf16_f32 v12, v12, v13
	v_cvt_pk_bf16_f32 v13, v14, v15
	v_cvt_pk_bf16_f32 v14, v8, v9
	v_cvt_pk_bf16_f32 v15, v10, v11
	v_add_u32_e32 v170, 0x58000, v161
	global_store_dwordx4 v170, v[12:15], s[8:9]
	s_waitcnt vmcnt(8)
	v_pk_fma_f32 v[4:5], v[4:5], v[136:137], v[240:241]
	v_pk_fma_f32 v[6:7], v[6:7], v[138:139], v[242:243]
	v_pk_fma_f32 v[0:1], v[0:1], v[140:141], v[244:245]
	v_pk_fma_f32 v[2:3], v[2:3], v[142:143], v[246:247]
	v_cvt_pk_bf16_f32 v4, v4, v5
	v_cvt_pk_bf16_f32 v5, v6, v7
	v_cvt_pk_bf16_f32 v6, v0, v1
	v_cvt_pk_bf16_f32 v7, v2, v3
	v_add_u32_e32 v170, 0x58000, v161
	global_store_dwordx4 v170, v[4:7], s[8:9] offset:256
	s_and_b64 vcc, exec, s[4:5]
	s_cbranch_vccz .LBB0_717
	s_waitcnt vmcnt(0)
	s_cmpk_gt_u32 s52, 0xff
	s_cbranch_scc1 .LBB0_728
	s_barrier

; #define PG8_STAGE(bufoff, gbase, voff) do { _Pragma("unroll") for (int _i = 0; _i < 2; ++_i) \
;         __builtin_amdgcn_global_load_lds((const unsigned*)((const char*)(gbase) + (voff)[_i]), (LAS unsigned*)(lds + (bufoff) + ldsw + _i * 8192), 16, 0, 0); } while (0)
; #define PG8_LDA(dst, b, h) do { _Pragma("unroll") for (int m = 0; m < 4; ++m) _Pragma("unroll") for (int k = 0; k < 2; ++k) dst[m][k] = *(const LAS bf16x8*)(lds + PG8_SA(b, h) + aoff + m * 2048 + k * 1024); } while (0)
; #define PG8_LDB(dst, b, h) do { _Pragma("unroll") for (int n = 0; n < 2; ++n) _Pragma("unroll") for (int k = 0; k < 2; ++k) dst[n][k] = *(const LAS bf16x8*)(lds + PG8_SB(b, h) + boff + n * 2048 + k * 1024); } while (0)
; #define PG8_MMA(ai, bj, At, Bt) do { __builtin_amdgcn_s_setprio(1); _Pragma("unroll") for (int m = 0; m < 4; ++m) _Pragma("unroll") for (int n = 0; n < 2; ++n) _Pragma("unroll") for (int k = 0; k < 2; ++k) \
;         acc[ai][bj][m][n] = __builtin_amdgcn_mfma_f32_16x16x32_bf16(Bt[n][k], At[m][k], acc[ai][bj][m][n], 0, 0, 0); __builtin_amdgcn_s_setprio(0); } while (0)
; #define PG8_WAIT_L(n) asm volatile("s_waitcnt lgkmcnt(" #n ")" ::: "memory")
; #define PG8_BAR __builtin_amdgcn_s_barrier()
; #define PG8_SCHED __builtin_amdgcn_sched_barrier(0)
; template <class Epi>
; DI void gemm_phase(LAS unsigned char* lds, const Gemm g, const StaticOrder& S, const Epi& E) {
;     ...
;             PG8_LDB(B0, 0, 0); PG8_SCHED; PG8_LDA(At, 0, 0); PG8_STAGE(PG8_SA(1, 1), a1 + hstep, voffA);
;             PG8_WAIT_L(8); PG8_BAR; PG8_WAIT_L(0); PG8_MMA(0, 0, At, B0); PG8_BAR; PG8_SCHED;
;             PG8_LDB(B1, 0, 1); PG8_STAGE(PG8_SB(0, 0), b2, voffB);
;             PG8_BAR; PG8_WAIT_L(0); PG8_MMA(0, 1, At, B1); PG8_BAR;
;             PG8_LDA(At, 0, 1); PG8_STAGE(PG8_SA(0, 0), a2, voffA);
;             PG8_BAR; PG8_WAIT_L(0); PG8_MMA(1, 0, At, B0); PG8_BAR; PG8_SCHED;
.LBB0_849:
	ds_read_b128 v[152:155], v149
	ds_read_b128 v[156:159], v149 offset:1024
	ds_read_b128 v[160:163], v149 offset:2048
	ds_read_b128 v[164:167], v149 offset:3072
	s_add_u32 s36, s24, 0xfffc0080
	s_addc_u32 s37, s25, -1
	s_cmp_eq_u32 s63, 12
	s_cselect_b32 s39, s17, s37
	s_cselect_b32 s38, s59, s36
	s_cselect_b32 s37, s15, s62
	s_cselect_b32 s36, s60, s61
	v_lshl_add_u64 v[144:145], s[24:25], 0, v[136:137]
	s_add_i32 m0, s23, 0xc000
	ds_read_b128 v[168:171], v150
	ds_read_b128 v[172:175], v150 offset:1024
	ds_read_b128 v[176:179], v150 offset:2048
	ds_read_b128 v[182:185], v150 offset:3072
	ds_read_b128 v[186:189], v150 offset:4096
	ds_read_b128 v[190:193], v150 offset:5120
	ds_read_b128 v[194:197], v150 offset:6144
	ds_read_b128 v[198:201], v150 offset:7168
	global_load_lds_dwordx4 v[144:145], off
	v_lshl_add_u64 v[144:145], s[24:25], 0, v[138:139]
	s_add_i32 m0, s23, 0xe000
	s_nop 0
	global_load_lds_dwordx4 v[144:145], off
	s_waitcnt lgkmcnt(8)
	s_barrier
	s_waitcnt lgkmcnt(0)
	s_waitcnt lgkmcnt(0)
	v_mfma_f32_16x16x32_bf16 v[124:127], v[152:155], v[168:171], v[124:127]
	v_mfma_f32_16x16x32_bf16 v[120:123], v[160:163], v[168:171], v[120:123]
	v_mfma_f32_16x16x32_bf16 v[108:111], v[152:155], v[176:179], v[108:111]
	v_mfma_f32_16x16x32_bf16 v[104:107], v[160:163], v[176:179], v[104:107]
	v_mfma_f32_16x16x32_bf16 v[92:95], v[152:155], v[186:189], v[92:95]
	v_mfma_f32_16x16x32_bf16 v[88:91], v[160:163], v[186:189], v[88:91]
	v_mfma_f32_16x16x32_bf16 v[76:79], v[152:155], v[194:197], v[76:79]
	v_mfma_f32_16x16x32_bf16 v[72:75], v[160:163], v[194:197], v[72:75]
	v_mfma_f32_16x16x32_bf16 v[124:127], v[156:159], v[172:175], v[124:127]
	v_mfma_f32_16x16x32_bf16 v[120:123], v[164:167], v[172:175], v[120:123]
	v_mfma_f32_16x16x32_bf16 v[108:111], v[156:159], v[182:185], v[108:111]
	v_mfma_f32_16x16x32_bf16 v[104:107], v[164:167], v[182:185], v[104:107]
	v_mfma_f32_16x16x32_bf16 v[92:95], v[156:159], v[190:193], v[92:95]
	v_mfma_f32_16x16x32_bf16 v[88:91], v[164:167], v[190:193], v[88:91]
	v_mfma_f32_16x16x32_bf16 v[76:79], v[156:159], v[198:201], v[76:79]
	v_mfma_f32_16x16x32_bf16 v[72:75], v[164:167], v[198:201], v[72:75]
	s_barrier
	s_add_i32 s64, s55, s45
	v_lshl_add_u64 v[144:145], s[36:37], 0, v[132:133]
	s_mov_b32 m0, s64
	ds_read_b128 v[202:205], v151
	ds_read_b128 v[206:209], v151 offset:1024
	ds_read_b128 v[210:213], v151 offset:2048
	ds_read_b128 v[214:217], v151 offset:3072
	global_load_lds_dwordx4 v[144:145], off
	v_lshl_add_u64 v[218:219], s[36:37], 0, v[128:129]
	s_add_i32 m0, s64, 0x2000
	s_nop 0
	global_load_lds_dwordx4 v[218:219], off
	s_barrier
	s_waitcnt lgkmcnt(0)
	s_waitcnt lgkmcnt(0)
	v_mfma_f32_16x16x32_bf16 v[116:119], v[202:205], v[168:171], v[116:119]
	v_mfma_f32_16x16x32_bf16 v[112:115], v[210:213], v[168:171], v[112:115]
	v_mfma_f32_16x16x32_bf16 v[100:103], v[202:205], v[176:179], v[100:103]
	v_mfma_f32_16x16x32_bf16 v[96:99], v[210:213], v[176:179], v[96:99]
	v_mfma_f32_16x16x32_bf16 v[84:87], v[202:205], v[186:189], v[84:87]
	v_mfma_f32_16x16x32_bf16 v[80:83], v[210:213], v[186:189], v[80:83]
	v_mfma_f32_16x16x32_bf16 v[68:71], v[202:205], v[194:197], v[68:71]
	v_mfma_f32_16x16x32_bf16 v[64:67], v[210:213], v[194:197], v[64:67]
	v_mfma_f32_16x16x32_bf16 v[116:119], v[206:209], v[172:175], v[116:119]
	v_mfma_f32_16x16x32_bf16 v[112:115], v[214:217], v[172:175], v[112:115]
	v_mfma_f32_16x16x32_bf16 v[100:103], v[206:209], v[182:185], v[100:103]
	v_mfma_f32_16x16x32_bf16 v[96:99], v[214:217], v[182:185], v[96:99]
	v_mfma_f32_16x16x32_bf16 v[84:87], v[206:209], v[190:193], v[84:87]
	v_mfma_f32_16x16x32_bf16 v[80:83], v[214:217], v[190:193], v[80:83]
	v_mfma_f32_16x16x32_bf16 v[68:71], v[206:209], v[198:201], v[68:71]
	v_mfma_f32_16x16x32_bf16 v[64:67], v[214:217], v[198:201], v[64:67]
	s_mov_b32 m0, s23
	v_lshl_add_u64 v[220:221], s[38:39], 0, v[134:135]
	s_barrier
	ds_read_b128 v[168:171], v150 offset:16384
	ds_read_b128 v[172:175], v150 offset:17408
	ds_read_b128 v[176:179], v150 offset:18432
	ds_read_b128 v[182:185], v150 offset:19456
	ds_read_b128 v[186:189], v150 offset:20480
	ds_read_b128 v[190:193], v150 offset:21504
	ds_read_b128 v[194:197], v150 offset:22528
	ds_read_b128 v[198:201], v150 offset:23552
	global_load_lds_dwordx4 v[220:221], off
	v_lshl_add_u64 v[222:223], s[38:39], 0, v[130:131]
	s_mov_b32 m0, s48
	s_nop 0
	global_load_lds_dwordx4 v[222:223], off
	s_barrier
	s_waitcnt lgkmcnt(0)
	s_waitcnt lgkmcnt(0)
	v_mfma_f32_16x16x32_bf16 v[60:63], v[152:155], v[168:171], v[60:63]
	v_mfma_f32_16x16x32_bf16 v[56:59], v[160:163], v[168:171], v[56:59]
	v_mfma_f32_16x16x32_bf16 v[44:47], v[152:155], v[176:179], v[44:47]
	v_mfma_f32_16x16x32_bf16 v[40:43], v[160:163], v[176:179], v[40:43]
	v_mfma_f32_16x16x32_bf16 v[28:31], v[152:155], v[186:189], v[28:31]
	v_mfma_f32_16x16x32_bf16 v[24:27], v[160:163], v[186:189], v[24:27]
	v_mfma_f32_16x16x32_bf16 v[12:15], v[152:155], v[194:197], v[12:15]
	v_mfma_f32_16x16x32_bf16 v[8:11], v[160:163], v[194:197], v[8:11]
	v_mfma_f32_16x16x32_bf16 v[60:63], v[156:159], v[172:175], v[60:63]
	v_mfma_f32_16x16x32_bf16 v[56:59], v[164:167], v[172:175], v[56:59]
	v_mfma_f32_16x16x32_bf16 v[44:47], v[156:159], v[182:185], v[44:47]
	v_mfma_f32_16x16x32_bf16 v[40:43], v[164:167], v[182:185], v[40:43]
	v_mfma_f32_16x16x32_bf16 v[28:31], v[156:159], v[190:193], v[28:31]
	v_mfma_f32_16x16x32_bf16 v[24:27], v[164:167], v[190:193], v[24:27]
	v_mfma_f32_16x16x32_bf16 v[12:15], v[156:159], v[198:201], v[12:15]
	v_mfma_f32_16x16x32_bf16 v[8:11], v[164:167], v[198:201], v[8:11]
	s_barrier
; #define PG8_STAGE(bufoff, gbase, voff) do { _Pragma("unroll") for (int _i = 0; _i < 2; ++_i) \
;         __builtin_amdgcn_global_load_lds((const unsigned*)((const char*)(gbase) + (voff)[_i]), (LAS unsigned*)(lds + (bufoff) + ldsw + _i * 8192), 16, 0, 0); } while (0)
; #define PG8_LDA(dst, b, h) do { _Pragma("unroll") for (int m = 0; m < 4; ++m) _Pragma("unroll") for (int k = 0; k < 2; ++k) dst[m][k] = *(const LAS bf16x8*)(lds + PG8_SA(b, h) + aoff + m * 2048 + k * 1024); } while (0)
; #define PG8_LDB(dst, b, h) do { _Pragma("unroll") for (int n = 0; n < 2; ++n) _Pragma("unroll") for (int k = 0; k < 2; ++k) dst[n][k] = *(const LAS bf16x8*)(lds + PG8_SB(b, h) + boff + n * 2048 + k * 1024); } while (0)
; #define PG8_MMA(ai, bj, At, Bt) do { __builtin_amdgcn_s_setprio(1); _Pragma("unroll") for (int m = 0; m < 4; ++m) _Pragma("unroll") for (int n = 0; n < 2; ++n) _Pragma("unroll") for (int k = 0; k < 2; ++k) \
;         acc[ai][bj][m][n] = __builtin_amdgcn_mfma_f32_16x16x32_bf16(Bt[n][k], At[m][k], acc[ai][bj][m][n], 0, 0, 0); __builtin_amdgcn_s_setprio(0); } while (0)
; #define PG8_WAIT_V(n) asm volatile("s_waitcnt vmcnt(" #n ")" ::: "memory")
; #define PG8_WAIT_L(n) asm volatile("s_waitcnt lgkmcnt(" #n ")" ::: "memory")
; #define PG8_BAR __builtin_amdgcn_s_barrier()
; #define PG8_SCHED __builtin_amdgcn_sched_barrier(0)
; template <class Epi>
; DI void gemm_phase(LAS unsigned char* lds, const Gemm g, const StaticOrder& S, const Epi& E) {
;     ...
;             PG8_STAGE(PG8_SB(0, 1), b2 + hstep, voffB);
;             PG8_WAIT_V(6); PG8_BAR; PG8_MMA(1, 1, At, B1); PG8_BAR;
;             PG8_LDB(B0, 1, 0); PG8_SCHED; PG8_LDA(At, 1, 0); PG8_STAGE(PG8_SA(0, 1), a2 + hstep, voffA);
;             PG8_WAIT_L(8); PG8_BAR; PG8_WAIT_L(0); PG8_MMA(0, 0, At, B0); PG8_BAR; PG8_SCHED;
;             PG8_LDB(B1, 1, 1); PG8_STAGE(PG8_SB(1, 0), b3, voffB);
;             PG8_BAR; PG8_WAIT_L(0); PG8_MMA(0, 1, At, B1); PG8_BAR;
;             PG8_LDA(At, 1, 1); PG8_STAGE(PG8_SA(1, 0), a3, voffA);
	s_add_u32 s64, s36, 0x40000
	s_addc_u32 s65, s37, 0
	s_add_i32 s66, s56, s45
	v_lshl_add_u64 v[152:153], s[64:65], 0, v[132:133]
	s_mov_b32 m0, s66
	s_nop 0
	global_load_lds_dwordx4 v[152:153], off
	v_lshl_add_u64 v[152:153], s[64:65], 0, v[128:129]
	s_add_i32 m0, s66, 0x2000
	s_nop 0
	global_load_lds_dwordx4 v[152:153], off
	s_waitcnt vmcnt(6)
	s_barrier
	v_mfma_f32_16x16x32_bf16 v[52:55], v[202:205], v[168:171], v[52:55]
	v_mfma_f32_16x16x32_bf16 v[48:51], v[210:213], v[168:171], v[48:51]
	v_mfma_f32_16x16x32_bf16 v[36:39], v[202:205], v[176:179], v[36:39]
	v_mfma_f32_16x16x32_bf16 v[32:35], v[210:213], v[176:179], v[32:35]
	v_mfma_f32_16x16x32_bf16 v[20:23], v[202:205], v[186:189], v[20:23]
	v_mfma_f32_16x16x32_bf16 v[16:19], v[210:213], v[186:189], v[16:19]
	v_mfma_f32_16x16x32_bf16 v[4:7], v[202:205], v[194:197], v[4:7]
	v_mfma_f32_16x16x32_bf16 v[0:3], v[210:213], v[194:197], v[0:3]
	v_mfma_f32_16x16x32_bf16 v[52:55], v[206:209], v[172:175], v[52:55]
	v_mfma_f32_16x16x32_bf16 v[48:51], v[214:217], v[172:175], v[48:51]
	v_mfma_f32_16x16x32_bf16 v[36:39], v[206:209], v[182:185], v[36:39]
	v_mfma_f32_16x16x32_bf16 v[32:35], v[214:217], v[182:185], v[32:35]
	v_mfma_f32_16x16x32_bf16 v[20:23], v[206:209], v[190:193], v[20:23]
	v_mfma_f32_16x16x32_bf16 v[16:19], v[214:217], v[190:193], v[16:19]
	v_mfma_f32_16x16x32_bf16 v[4:7], v[206:209], v[198:201], v[4:7]
	v_mfma_f32_16x16x32_bf16 v[0:3], v[214:217], v[198:201], v[0:3]
	s_add_i32 s64, 0, 0x18000
	v_add_u32_e32 v164, s64, v147
	s_barrier
	ds_read_b128 v[152:155], v164
	ds_read_b128 v[156:159], v164 offset:1024
	ds_read_b128 v[160:163], v164 offset:2048
	ds_read_b128 v[164:167], v164 offset:3072
	s_add_u32 s38, s38, 0x40000
	s_addc_u32 s39, s39, 0
	s_mov_b32 m0, s49
	v_lshl_add_u64 v[202:203], s[38:39], 0, v[134:135]
	ds_read_b128 v[168:171], v150 offset:32768
	ds_read_b128 v[172:175], v150 offset:33792
	ds_read_b128 v[176:179], v150 offset:34816
	ds_read_b128 v[182:185], v150 offset:35840
	ds_read_b128 v[186:189], v150 offset:36864
	ds_read_b128 v[190:193], v150 offset:37888
	ds_read_b128 v[194:197], v150 offset:38912
	ds_read_b128 v[198:201], v150 offset:39936
	global_load_lds_dwordx4 v[202:203], off
	v_lshl_add_u64 v[202:203], s[38:39], 0, v[130:131]
	s_mov_b32 m0, s50
	s_nop 0
	global_load_lds_dwordx4 v[202:203], off
	s_waitcnt lgkmcnt(8)
	s_barrier
	s_waitcnt lgkmcnt(0)
	s_waitcnt lgkmcnt(0)
	v_mfma_f32_16x16x32_bf16 v[124:127], v[152:155], v[168:171], v[124:127]
	v_mfma_f32_16x16x32_bf16 v[120:123], v[160:163], v[168:171], v[120:123]
	v_mfma_f32_16x16x32_bf16 v[108:111], v[152:155], v[176:179], v[108:111]
	v_mfma_f32_16x16x32_bf16 v[104:107], v[160:163], v[176:179], v[104:107]
	v_mfma_f32_16x16x32_bf16 v[92:95], v[152:155], v[186:189], v[92:95]
	v_mfma_f32_16x16x32_bf16 v[88:91], v[160:163], v[186:189], v[88:91]
	v_mfma_f32_16x16x32_bf16 v[76:79], v[152:155], v[194:197], v[76:79]
	v_mfma_f32_16x16x32_bf16 v[72:75], v[160:163], v[194:197], v[72:75]
	v_mfma_f32_16x16x32_bf16 v[124:127], v[156:159], v[172:175], v[124:127]
	v_mfma_f32_16x16x32_bf16 v[120:123], v[164:167], v[172:175], v[120:123]
	v_mfma_f32_16x16x32_bf16 v[108:111], v[156:159], v[182:185], v[108:111]
	v_mfma_f32_16x16x32_bf16 v[104:107], v[164:167], v[182:185], v[104:107]
	v_mfma_f32_16x16x32_bf16 v[92:95], v[156:159], v[190:193], v[92:95]
	v_mfma_f32_16x16x32_bf16 v[88:91], v[164:167], v[190:193], v[88:91]
	v_mfma_f32_16x16x32_bf16 v[76:79], v[156:159], v[198:201], v[76:79]
	v_mfma_f32_16x16x32_bf16 v[72:75], v[164:167], v[198:201], v[72:75]
	s_barrier
	s_add_i32 s38, 0, 0x1c000
	s_add_i32 s39, s64, s45
	v_add_u32_e32 v214, s38, v147
	v_lshl_add_u64 v[144:145], v[144:145], 0, s[12:13]
	s_mov_b32 m0, s39
	ds_read_b128 v[202:205], v214
	ds_read_b128 v[206:209], v214 offset:1024
	ds_read_b128 v[210:213], v214 offset:2048
	ds_read_b128 v[214:217], v214 offset:3072
	global_load_lds_dwordx4 v[144:145], off
	v_lshl_add_u64 v[144:145], v[218:219], 0, s[12:13]
	s_add_i32 m0, s39, 0x2000
	s_nop 0
	global_load_lds_dwordx4 v[144:145], off
	s_barrier
	s_waitcnt lgkmcnt(0)
	s_waitcnt lgkmcnt(0)
	v_mfma_f32_16x16x32_bf16 v[116:119], v[202:205], v[168:171], v[116:119]
	v_mfma_f32_16x16x32_bf16 v[112:115], v[210:213], v[168:171], v[112:115]
	v_mfma_f32_16x16x32_bf16 v[100:103], v[202:205], v[176:179], v[100:103]
	v_mfma_f32_16x16x32_bf16 v[96:99], v[210:213], v[176:179], v[96:99]
	v_mfma_f32_16x16x32_bf16 v[84:87], v[202:205], v[186:189], v[84:87]
	v_mfma_f32_16x16x32_bf16 v[80:83], v[210:213], v[186:189], v[80:83]
	v_mfma_f32_16x16x32_bf16 v[68:71], v[202:205], v[194:197], v[68:71]
	v_mfma_f32_16x16x32_bf16 v[64:67], v[210:213], v[194:197], v[64:67]
	v_mfma_f32_16x16x32_bf16 v[116:119], v[206:209], v[172:175], v[116:119]
	v_mfma_f32_16x16x32_bf16 v[112:115], v[214:217], v[172:175], v[112:115]
	v_mfma_f32_16x16x32_bf16 v[100:103], v[206:209], v[182:185], v[100:103]
	v_mfma_f32_16x16x32_bf16 v[96:99], v[214:217], v[182:185], v[96:99]
	v_mfma_f32_16x16x32_bf16 v[84:87], v[206:209], v[190:193], v[84:87]
	v_mfma_f32_16x16x32_bf16 v[80:83], v[214:217], v[190:193], v[80:83]
	v_mfma_f32_16x16x32_bf16 v[68:71], v[206:209], v[198:201], v[68:71]
	v_mfma_f32_16x16x32_bf16 v[64:67], v[214:217], v[198:201], v[64:67]
	s_mov_b32 m0, s52
	v_lshl_add_u64 v[144:145], v[220:221], 0, s[12:13]
	s_barrier
	ds_read_b128 v[168:171], v150 offset:49152
	ds_read_b128 v[172:175], v150 offset:50176
	ds_read_b128 v[176:179], v150 offset:51200
	ds_read_b128 v[182:185], v150 offset:52224
	ds_read_b128 v[186:189], v150 offset:53248
	ds_read_b128 v[190:193], v150 offset:54272
	ds_read_b128 v[194:197], v150 offset:55296
	ds_read_b128 v[198:201], v150 offset:56320
	global_load_lds_dwordx4 v[144:145], off
	v_lshl_add_u64 v[144:145], v[222:223], 0, s[12:13]
	s_mov_b32 m0, s53
	s_nop 0
	global_load_lds_dwordx4 v[144:145], off
	s_barrier
; DI unsigned pk2(float a, float b) { f32x2 v = {a, b}; bf16x2_t r = __builtin_convertvector(v, bf16x2_t); return __builtin_bit_cast(unsigned, r); }
; DI float siluf_(float x) { return x * __builtin_amdgcn_rcpf(1.f + __expf(-x)); }
; #define PG8_STAGE(bufoff, gbase, voff) do { _Pragma("unroll") for (int _i = 0; _i < 2; ++_i) \
;         __builtin_amdgcn_global_load_lds((const unsigned*)((const char*)(gbase) + (voff)[_i]), (LAS unsigned*)(lds + (bufoff) + ldsw + _i * 8192), 16, 0, 0); } while (0)
; #define PG8_MMA(ai, bj, At, Bt) do { __builtin_amdgcn_s_setprio(1); _Pragma("unroll") for (int m = 0; m < 4; ++m) _Pragma("unroll") for (int n = 0; n < 2; ++n) _Pragma("unroll") for (int k = 0; k < 2; ++k) \
;         acc[ai][bj][m][n] = __builtin_amdgcn_mfma_f32_16x16x32_bf16(Bt[n][k], At[m][k], acc[ai][bj][m][n], 0, 0, 0); __builtin_amdgcn_s_setprio(0); } while (0)
; #define PG8_WAIT_V(n) asm volatile("s_waitcnt vmcnt(" #n ")" ::: "memory")
; #define PG8_WAIT_L(n) asm volatile("s_waitcnt lgkmcnt(" #n ")" ::: "memory")
; #define PG8_BAR __builtin_amdgcn_s_barrier()
; #define PG8_SCHED __builtin_amdgcn_sched_barrier(0)
; template <class Epi>
; DI void gemm_phase(LAS unsigned char* lds, const Gemm g, const StaticOrder& S, const Epi& E) {
;     ...
;             PG8_BAR; PG8_WAIT_L(0); PG8_MMA(1, 0, At, B0); PG8_BAR; PG8_SCHED;
;             PG8_STAGE(PG8_SB(1, 1), b3 + hstep, voffB);
;             PG8_WAIT_V(6); PG8_BAR; PG8_MMA(1, 1, At, B1); PG8_BAR;
;     DI void operator()(const f32x4 (&acc)[2][2][4][2], const Unit& u, int wr, int wc, int fr, int fq) const {
;         const int row0 = u.pm * BM + wr * 64 + fr, col0 = u.pn * HALF + wc * 32 + 8 * fq;
; #pragma unroll
;         for (int ai = 0; ai < 2; ++ai)
; #pragma unroll
;             for (int m = 0; m < 4; ++m) { bf16_t* rowp = O + (size_t)(row0 + ai * HALF + m * 16) * DFF + col0;
;                 f32x4 v0, v1;
; #pragma unroll
;                 for (int j = 0; j < 4; ++j) { v0[j] = siluf_(acc[ai][0][m][0][j]) * acc[ai][1][m][0][j]; v1[j] = siluf_(acc[ai][0][m][1][j]) * acc[ai][1][m][1][j]; }
;                 u32x4 w; w.x = pk2(v0[0], v0[1]); w.y = pk2(v0[2], v0[3]); w.z = pk2(v1[0], v1[1]); w.w = pk2(v1[2], v1[3]);
;                 *(u32x4*)rowp = w; }
	s_waitcnt lgkmcnt(0)
	s_waitcnt lgkmcnt(0)
	v_mfma_f32_16x16x32_bf16 v[60:63], v[152:155], v[168:171], v[60:63]
	v_mfma_f32_16x16x32_bf16 v[56:59], v[160:163], v[168:171], v[56:59]
	v_mfma_f32_16x16x32_bf16 v[44:47], v[152:155], v[176:179], v[44:47]
	v_mfma_f32_16x16x32_bf16 v[40:43], v[160:163], v[176:179], v[40:43]
	v_mfma_f32_16x16x32_bf16 v[28:31], v[152:155], v[186:189], v[28:31]
	v_mfma_f32_16x16x32_bf16 v[24:27], v[160:163], v[186:189], v[24:27]
	v_mfma_f32_16x16x32_bf16 v[12:15], v[152:155], v[194:197], v[12:15]
	v_mfma_f32_16x16x32_bf16 v[8:11], v[160:163], v[194:197], v[8:11]
	v_mfma_f32_16x16x32_bf16 v[60:63], v[156:159], v[172:175], v[60:63]
	v_mfma_f32_16x16x32_bf16 v[56:59], v[164:167], v[172:175], v[56:59]
	v_mfma_f32_16x16x32_bf16 v[44:47], v[156:159], v[182:185], v[44:47]
	v_mfma_f32_16x16x32_bf16 v[40:43], v[164:167], v[182:185], v[40:43]
	v_mfma_f32_16x16x32_bf16 v[28:31], v[156:159], v[190:193], v[28:31]
	v_mfma_f32_16x16x32_bf16 v[24:27], v[164:167], v[190:193], v[24:27]
	v_mfma_f32_16x16x32_bf16 v[12:15], v[156:159], v[198:201], v[12:15]
	v_mfma_f32_16x16x32_bf16 v[8:11], v[164:167], v[198:201], v[8:11]
	s_barrier
	s_add_u32 s36, s36, 0x40080
	s_addc_u32 s37, s37, 0
	s_add_i32 s38, s38, s45
	v_lshl_add_u64 v[144:145], s[36:37], 0, v[132:133]
	s_mov_b32 m0, s38
	s_nop 0
	global_load_lds_dwordx4 v[144:145], off
	v_lshl_add_u64 v[144:145], s[36:37], 0, v[128:129]
	s_add_i32 m0, s38, 0x2000
	s_nop 0
	global_load_lds_dwordx4 v[144:145], off
	s_waitcnt vmcnt(6)
	s_barrier
	v_mfma_f32_16x16x32_bf16 v[52:55], v[202:205], v[168:171], v[52:55]
	v_mfma_f32_16x16x32_bf16 v[48:51], v[210:213], v[168:171], v[48:51]
	v_mfma_f32_16x16x32_bf16 v[36:39], v[202:205], v[176:179], v[36:39]
	v_mfma_f32_16x16x32_bf16 v[32:35], v[210:213], v[176:179], v[32:35]
	v_mfma_f32_16x16x32_bf16 v[20:23], v[202:205], v[186:189], v[20:23]
	v_mfma_f32_16x16x32_bf16 v[16:19], v[210:213], v[186:189], v[16:19]
	v_mfma_f32_16x16x32_bf16 v[4:7], v[202:205], v[194:197], v[4:7]
	v_mfma_f32_16x16x32_bf16 v[0:3], v[210:213], v[194:197], v[0:3]
	v_mfma_f32_16x16x32_bf16 v[52:55], v[206:209], v[172:175], v[52:55]
	v_mfma_f32_16x16x32_bf16 v[48:51], v[214:217], v[172:175], v[48:51]
	v_mfma_f32_16x16x32_bf16 v[36:39], v[206:209], v[182:185], v[36:39]
	v_mfma_f32_16x16x32_bf16 v[32:35], v[214:217], v[182:185], v[32:35]
	v_mfma_f32_16x16x32_bf16 v[20:23], v[206:209], v[190:193], v[20:23]
	v_mfma_f32_16x16x32_bf16 v[16:19], v[214:217], v[190:193], v[16:19]
	v_mfma_f32_16x16x32_bf16 v[4:7], v[206:209], v[198:201], v[4:7]
	v_mfma_f32_16x16x32_bf16 v[0:3], v[214:217], v[198:201], v[0:3]
	s_add_i32 s63, s63, 2
	s_add_u32 s24, s24, 0x100
	s_addc_u32 s25, s25, 0
	s_add_u32 s61, s61, 0x100
	s_addc_u32 s62, s62, 0
	s_cmp_gt_u32 s63, 13
	s_barrier
	s_cbranch_scc0 .LBB0_849
	v_mul_f32_e32 v153, 0xbfb8aa3b, v124
	v_mul_f32_e32 v158, 0xbfb8aa3b, v120
	v_exp_f32_e32 v153, v153
	v_exp_f32_e32 v159, v158
	v_mul_f32_e32 v158, 0xbfb8aa3b, v125
	v_exp_f32_e32 v160, v158
	v_add_f32_e32 v153, 1.0, v153
	v_rcp_f32_e32 v158, v153
	v_add_f32_e32 v153, 1.0, v159
	v_add_f32_e32 v159, 1.0, v160
	v_rcp_f32_e32 v159, v159
	v_mul_f32_e32 v160, 0xbfb8aa3b, v121
	v_exp_f32_e32 v161, v160
	v_rcp_f32_e32 v160, v153
	v_pk_mul_f32 v[124:125], v[124:125], v[158:159]
	v_mul_f32_e32 v153, 0xbfb8aa3b, v127
	v_pk_mul_f32 v[116:117], v[124:125], v[116:117]
	v_add_f32_e32 v124, 1.0, v161
	v_mul_f32_e32 v125, 0xbfb8aa3b, v122
	v_rcp_f32_e32 v161, v124
	v_mul_f32_e32 v124, 0xbfb8aa3b, v126
	v_exp_f32_e32 v125, v125
	v_exp_f32_e32 v124, v124
	v_exp_f32_e32 v153, v153
	v_mul_f32_e32 v158, 0xbfb8aa3b, v123
	v_exp_f32_e32 v159, v158
	v_add_f32_e32 v125, 1.0, v125
	v_add_f32_e32 v124, 1.0, v124
	v_rcp_f32_e32 v158, v125
	v_add_f32_e32 v125, 1.0, v153
	v_rcp_f32_e32 v124, v124
	v_rcp_f32_e32 v125, v125
	v_add_f32_e32 v153, 1.0, v159
	v_rcp_f32_e32 v159, v153
	v_pk_mul_f32 v[120:121], v[120:121], v[160:161]
	v_lshl_or_b32 v154, s58, 7, v148
	v_pk_mul_f32 v[120:121], v[120:121], v[112:113]
	v_pk_mul_f32 v[112:113], v[126:127], v[124:125]
	v_lshl_add_u32 v152, s22, 8, v146
	v_ashrrev_i32_e32 v155, 31, v154
	v_mov_b64_e32 v[144:145], s[8:9]
	v_pk_mul_f32 v[118:119], v[112:113], v[118:119]
	v_pk_mul_f32 v[112:113], v[122:123], v[158:159]
	v_mad_i64_i32 v[156:157], s[24:25], v152, s57, v[144:145]
	v_pk_mul_f32 v[122:123], v[112:113], v[114:115]
	v_lshlrev_b64 v[112:113], 1, v[154:155]
	v_lshl_add_u64 v[124:125], v[156:157], 0, v[112:113]
	v_cvt_pk_bf16_f32 v114, v116, v117
	v_cvt_pk_bf16_f32 v115, v118, v119
	v_cvt_pk_bf16_f32 v116, v120, v121
	v_cvt_pk_bf16_f32 v117, v122, v123
	global_store_dwordx4 v[124:125], v[114:117], off
	v_mul_f32_e32 v118, 0xbfb8aa3b, v109
	v_exp_f32_e32 v118, v118
	v_mul_f32_e32 v116, 0xbfb8aa3b, v108
	v_mul_f32_e32 v117, 0xbfb8aa3b, v104
	v_exp_f32_e32 v116, v116
	v_exp_f32_e32 v117, v117
	v_or_b32_e32 v114, 16, v152
	v_mad_i64_i32 v[114:115], s[24:25], v114, s57, v[144:145]
	v_add_f32_e32 v116, 1.0, v116
	v_add_f32_e32 v119, 1.0, v117
	v_add_f32_e32 v117, 1.0, v118
	v_rcp_f32_e32 v116, v116
	v_rcp_f32_e32 v117, v117
	v_mul_f32_e32 v118, 0xbfb8aa3b, v105
	v_exp_f32_e32 v120, v118
	v_rcp_f32_e32 v118, v119
	v_pk_mul_f32 v[108:109], v[108:109], v[116:117]
	v_mul_f32_e32 v116, 0xbfb8aa3b, v111
	v_pk_mul_f32 v[100:101], v[108:109], v[100:101]
	v_add_f32_e32 v108, 1.0, v120
	v_rcp_f32_e32 v119, v108
	v_mul_f32_e32 v109, 0xbfb8aa3b, v106
	v_mul_f32_e32 v108, 0xbfb8aa3b, v110
	v_exp_f32_e32 v109, v109
	v_exp_f32_e32 v108, v108
	v_exp_f32_e32 v117, v116
	v_mul_f32_e32 v116, 0xbfb8aa3b, v107
	v_pk_mul_f32 v[104:105], v[104:105], v[118:119]
	v_exp_f32_e32 v118, v116
	v_add_f32_e32 v109, 1.0, v109
; DI unsigned pk2(float a, float b) { f32x2 v = {a, b}; bf16x2_t r = __builtin_convertvector(v, bf16x2_t); return __builtin_bit_cast(unsigned, r); }
; DI float siluf_(float x) { return x * __builtin_amdgcn_rcpf(1.f + __expf(-x)); }
;     DI void operator()(const f32x4 (&acc)[2][2][4][2], const Unit& u, int wr, int wc, int fr, int fq) const {
;         const int row0 = u.pm * BM + wr * 64 + fr, col0 = u.pn * HALF + wc * 32 + 8 * fq;
; #pragma unroll
;         for (int ai = 0; ai < 2; ++ai)
; #pragma unroll
;             for (int m = 0; m < 4; ++m) { bf16_t* rowp = O + (size_t)(row0 + ai * HALF + m * 16) * DFF + col0;
;                 f32x4 v0, v1;
; #pragma unroll
;                 for (int j = 0; j < 4; ++j) { v0[j] = siluf_(acc[ai][0][m][0][j]) * acc[ai][1][m][0][j]; v1[j] = siluf_(acc[ai][0][m][1][j]) * acc[ai][1][m][1][j]; }
;                 u32x4 w; w.x = pk2(v0[0], v0[1]); w.y = pk2(v0[2], v0[3]); w.z = pk2(v1[0], v1[1]); w.w = pk2(v1[2], v1[3]);
;                 *(u32x4*)rowp = w; }
	v_add_f32_e32 v108, 1.0, v108
	v_rcp_f32_e32 v116, v109
	v_add_f32_e32 v109, 1.0, v117
	v_rcp_f32_e32 v108, v108
	v_rcp_f32_e32 v109, v109
	v_add_f32_e32 v117, 1.0, v118
	v_rcp_f32_e32 v117, v117
	v_pk_mul_f32 v[104:105], v[104:105], v[96:97]
	v_pk_mul_f32 v[96:97], v[110:111], v[108:109]
	v_lshl_add_u64 v[108:109], v[114:115], 0, v[112:113]
	v_pk_mul_f32 v[102:103], v[96:97], v[102:103]
	v_pk_mul_f32 v[96:97], v[106:107], v[116:117]
	s_and_b64 vcc, exec, s[4:5]
	v_pk_mul_f32 v[106:107], v[96:97], v[98:99]
	v_cvt_pk_bf16_f32 v96, v100, v101
	v_cvt_pk_bf16_f32 v97, v102, v103
	v_cvt_pk_bf16_f32 v98, v104, v105
	v_cvt_pk_bf16_f32 v99, v106, v107
	global_store_dwordx4 v[108:109], v[96:99], off
	v_mul_f32_e32 v100, 0xbfb8aa3b, v93
	v_exp_f32_e32 v100, v100
	v_mul_f32_e32 v98, 0xbfb8aa3b, v92
	v_mul_f32_e32 v99, 0xbfb8aa3b, v88
	v_exp_f32_e32 v98, v98
	v_exp_f32_e32 v99, v99
	v_or_b32_e32 v96, 32, v152
	v_mad_i64_i32 v[96:97], s[24:25], v96, s57, v[144:145]
	v_add_f32_e32 v98, 1.0, v98
	v_add_f32_e32 v101, 1.0, v99
	v_add_f32_e32 v99, 1.0, v100
	v_rcp_f32_e32 v98, v98
	v_rcp_f32_e32 v99, v99
	v_mul_f32_e32 v100, 0xbfb8aa3b, v89
	v_exp_f32_e32 v102, v100
	v_rcp_f32_e32 v100, v101
	v_pk_mul_f32 v[92:93], v[92:93], v[98:99]
	v_mul_f32_e32 v98, 0xbfb8aa3b, v95
	v_pk_mul_f32 v[84:85], v[92:93], v[84:85]
	v_add_f32_e32 v92, 1.0, v102
	v_rcp_f32_e32 v101, v92
	v_mul_f32_e32 v93, 0xbfb8aa3b, v90
	v_mul_f32_e32 v92, 0xbfb8aa3b, v94
	v_exp_f32_e32 v93, v93
	v_exp_f32_e32 v92, v92
	v_exp_f32_e32 v99, v98
	v_mul_f32_e32 v98, 0xbfb8aa3b, v91
	v_pk_mul_f32 v[88:89], v[88:89], v[100:101]
	v_exp_f32_e32 v100, v98
	v_add_f32_e32 v93, 1.0, v93
	v_add_f32_e32 v92, 1.0, v92
	v_rcp_f32_e32 v98, v93
	v_add_f32_e32 v93, 1.0, v99
	v_rcp_f32_e32 v92, v92
	v_rcp_f32_e32 v93, v93
	v_add_f32_e32 v99, 1.0, v100
	v_rcp_f32_e32 v99, v99
	v_pk_mul_f32 v[88:89], v[88:89], v[80:81]
	v_pk_mul_f32 v[80:81], v[94:95], v[92:93]
	v_lshl_add_u64 v[92:93], v[96:97], 0, v[112:113]
	v_pk_mul_f32 v[86:87], v[80:81], v[86:87]
	v_pk_mul_f32 v[80:81], v[90:91], v[98:99]
	s_mov_b32 s58, s14
	v_pk_mul_f32 v[90:91], v[80:81], v[82:83]
	v_cvt_pk_bf16_f32 v80, v84, v85
	v_cvt_pk_bf16_f32 v81, v86, v87
	v_cvt_pk_bf16_f32 v82, v88, v89
	v_cvt_pk_bf16_f32 v83, v90, v91
	global_store_dwordx4 v[92:93], v[80:83], off
	v_mul_f32_e32 v84, 0xbfb8aa3b, v77
	v_exp_f32_e32 v84, v84
	v_mul_f32_e32 v82, 0xbfb8aa3b, v76
	v_mul_f32_e32 v83, 0xbfb8aa3b, v72
	v_exp_f32_e32 v82, v82
	v_exp_f32_e32 v83, v83
	v_or_b32_e32 v80, 48, v152
	v_mad_i64_i32 v[80:81], s[24:25], v80, s57, v[144:145]
	v_add_f32_e32 v82, 1.0, v82
	v_add_f32_e32 v85, 1.0, v83
	v_add_f32_e32 v83, 1.0, v84
	v_rcp_f32_e32 v82, v82
	v_rcp_f32_e32 v83, v83
	v_mul_f32_e32 v84, 0xbfb8aa3b, v73
	v_exp_f32_e32 v86, v84
	v_rcp_f32_e32 v84, v85
	v_pk_mul_f32 v[76:77], v[76:77], v[82:83]
	v_mul_f32_e32 v82, 0xbfb8aa3b, v79
	v_pk_mul_f32 v[68:69], v[76:77], v[68:69]
	v_add_f32_e32 v76, 1.0, v86
	v_rcp_f32_e32 v85, v76
	v_mul_f32_e32 v77, 0xbfb8aa3b, v74
	v_mul_f32_e32 v76, 0xbfb8aa3b, v78
	v_exp_f32_e32 v77, v77
	v_exp_f32_e32 v76, v76
	v_exp_f32_e32 v83, v82
	v_mul_f32_e32 v82, 0xbfb8aa3b, v75
	v_pk_mul_f32 v[72:73], v[72:73], v[84:85]
	v_exp_f32_e32 v84, v82
	v_add_f32_e32 v77, 1.0, v77
	v_add_f32_e32 v76, 1.0, v76
	v_rcp_f32_e32 v82, v77
	v_add_f32_e32 v77, 1.0, v83
	v_rcp_f32_e32 v76, v76
	v_rcp_f32_e32 v77, v77
	v_add_f32_e32 v83, 1.0, v84
	v_rcp_f32_e32 v83, v83
	v_pk_mul_f32 v[72:73], v[72:73], v[64:65]
	v_pk_mul_f32 v[64:65], v[78:79], v[76:77]
	v_lshl_add_u64 v[76:77], v[80:81], 0, v[112:113]
	v_pk_mul_f32 v[70:71], v[64:65], v[70:71]
	v_pk_mul_f32 v[64:65], v[74:75], v[82:83]
	s_mov_b32 s22, s16
	v_pk_mul_f32 v[74:75], v[64:65], v[66:67]
	v_cvt_pk_bf16_f32 v64, v68, v69
	v_cvt_pk_bf16_f32 v65, v70, v71
	v_cvt_pk_bf16_f32 v66, v72, v73
	v_cvt_pk_bf16_f32 v67, v74, v75
	global_store_dwordx4 v[76:77], v[64:67], off
	v_mul_f32_e32 v68, 0xbfb8aa3b, v61
	v_exp_f32_e32 v68, v68
	v_mul_f32_e32 v66, 0xbfb8aa3b, v60
	v_mul_f32_e32 v67, 0xbfb8aa3b, v56
	v_exp_f32_e32 v66, v66
	v_exp_f32_e32 v67, v67
	v_add_u32_e32 v64, 0x80, v152
	v_mad_i64_i32 v[64:65], s[24:25], v64, s57, v[144:145]
	v_add_f32_e32 v66, 1.0, v66
	v_add_f32_e32 v69, 1.0, v67
	v_add_f32_e32 v67, 1.0, v68
	v_rcp_f32_e32 v66, v66
	v_rcp_f32_e32 v67, v67
	v_mul_f32_e32 v68, 0xbfb8aa3b, v57
	v_exp_f32_e32 v70, v68
	v_rcp_f32_e32 v68, v69
	v_pk_mul_f32 v[60:61], v[60:61], v[66:67]
	v_mul_f32_e32 v66, 0xbfb8aa3b, v63
	v_pk_mul_f32 v[52:53], v[60:61], v[52:53]
	v_add_f32_e32 v60, 1.0, v70
	v_rcp_f32_e32 v69, v60
	v_mul_f32_e32 v61, 0xbfb8aa3b, v58
	v_mul_f32_e32 v60, 0xbfb8aa3b, v62
	v_exp_f32_e32 v61, v61
	v_exp_f32_e32 v60, v60
	v_exp_f32_e32 v67, v66
	v_mul_f32_e32 v66, 0xbfb8aa3b, v59
	v_pk_mul_f32 v[56:57], v[56:57], v[68:69]
	v_exp_f32_e32 v68, v66
	v_add_f32_e32 v61, 1.0, v61
	v_add_f32_e32 v60, 1.0, v60
	v_rcp_f32_e32 v66, v61
	v_add_f32_e32 v61, 1.0, v67
	v_rcp_f32_e32 v60, v60
	v_rcp_f32_e32 v61, v61
	v_add_f32_e32 v67, 1.0, v68
	v_rcp_f32_e32 v67, v67
	v_pk_mul_f32 v[56:57], v[56:57], v[48:49]
	v_pk_mul_f32 v[48:49], v[62:63], v[60:61]
	v_lshl_add_u64 v[60:61], v[64:65], 0, v[112:113]
; DI unsigned pk2(float a, float b) { f32x2 v = {a, b}; bf16x2_t r = __builtin_convertvector(v, bf16x2_t); return __builtin_bit_cast(unsigned, r); }
; DI float siluf_(float x) { return x * __builtin_amdgcn_rcpf(1.f + __expf(-x)); }
; #define PG8_WAIT_V(n) asm volatile("s_waitcnt vmcnt(" #n ")" ::: "memory")
; #define PG8_BAR __builtin_amdgcn_s_barrier()
; template <class Epi>
; DI void gemm_phase(LAS unsigned char* lds, const Gemm g, const StaticOrder& S, const Epi& E) {
;     ...
;         E(acc, cur, wr, wc, fr, fq);
;         if (!has_next) break;
; #pragma unroll
;         for (int a = 0; a < 2; ++a)
; #pragma unroll
;             for (int b = 0; b < 2; ++b)
; #pragma unroll
;                 for (int m = 0; m < 4; ++m)
; #pragma unroll
;                     for (int n = 0; n < 2; ++n) acc[a][b][m][n] = (f32x4){0.f, 0.f, 0.f, 0.f};
;         cur = nxt; cA = nA; cB = nB; ++ui;
;     }
;     PG8_WAIT_V(0);
;     if (wr == 0) PG8_BAR;
;     PG8_BAR;
;     DI void operator()(const f32x4 (&acc)[2][2][4][2], const Unit& u, int wr, int wc, int fr, int fq) const {
;     ...
;             for (int m = 0; m < 4; ++m) { bf16_t* rowp = O + (size_t)(row0 + ai * HALF + m * 16) * DFF + col0;
;                 f32x4 v0, v1;
; #pragma unroll
;                 for (int j = 0; j < 4; ++j) { v0[j] = siluf_(acc[ai][0][m][0][j]) * acc[ai][1][m][0][j]; v1[j] = siluf_(acc[ai][0][m][1][j]) * acc[ai][1][m][1][j]; }
;                 u32x4 w; w.x = pk2(v0[0], v0[1]); w.y = pk2(v0[2], v0[3]); w.z = pk2(v1[0], v1[1]); w.w = pk2(v1[2], v1[3]);
;                 *(u32x4*)rowp = w; }
	v_pk_mul_f32 v[54:55], v[48:49], v[54:55]
	v_pk_mul_f32 v[48:49], v[58:59], v[66:67]
	s_mov_b64 s[36:37], s[20:21]
	v_pk_mul_f32 v[58:59], v[48:49], v[50:51]
	v_cvt_pk_bf16_f32 v48, v52, v53
	v_cvt_pk_bf16_f32 v49, v54, v55
	v_cvt_pk_bf16_f32 v50, v56, v57
	v_cvt_pk_bf16_f32 v51, v58, v59
	global_store_dwordx4 v[60:61], v[48:51], off
	v_mul_f32_e32 v52, 0xbfb8aa3b, v45
	v_exp_f32_e32 v52, v52
	v_mul_f32_e32 v50, 0xbfb8aa3b, v44
	v_mul_f32_e32 v51, 0xbfb8aa3b, v40
	v_exp_f32_e32 v50, v50
	v_exp_f32_e32 v51, v51
	v_add_u32_e32 v48, 0x90, v152
	v_mad_i64_i32 v[48:49], s[24:25], v48, s57, v[144:145]
	v_add_f32_e32 v50, 1.0, v50
	v_add_f32_e32 v53, 1.0, v51
	v_add_f32_e32 v51, 1.0, v52
	v_rcp_f32_e32 v50, v50
	v_rcp_f32_e32 v51, v51
	v_mul_f32_e32 v52, 0xbfb8aa3b, v41
	v_exp_f32_e32 v54, v52
	v_rcp_f32_e32 v52, v53
	v_pk_mul_f32 v[44:45], v[44:45], v[50:51]
	v_mul_f32_e32 v50, 0xbfb8aa3b, v47
	v_pk_mul_f32 v[36:37], v[44:45], v[36:37]
	v_add_f32_e32 v44, 1.0, v54
	v_rcp_f32_e32 v53, v44
	v_mul_f32_e32 v45, 0xbfb8aa3b, v42
	v_mul_f32_e32 v44, 0xbfb8aa3b, v46
	v_exp_f32_e32 v45, v45
	v_exp_f32_e32 v44, v44
	v_exp_f32_e32 v51, v50
	v_mul_f32_e32 v50, 0xbfb8aa3b, v43
	v_pk_mul_f32 v[40:41], v[40:41], v[52:53]
	v_exp_f32_e32 v52, v50
	v_add_f32_e32 v45, 1.0, v45
	v_add_f32_e32 v44, 1.0, v44
	v_rcp_f32_e32 v50, v45
	v_add_f32_e32 v45, 1.0, v51
	v_rcp_f32_e32 v44, v44
	v_rcp_f32_e32 v45, v45
	v_add_f32_e32 v51, 1.0, v52
	v_rcp_f32_e32 v51, v51
	v_pk_mul_f32 v[40:41], v[40:41], v[32:33]
	v_pk_mul_f32 v[32:33], v[46:47], v[44:45]
	v_lshl_add_u64 v[44:45], v[48:49], 0, v[112:113]
	v_pk_mul_f32 v[38:39], v[32:33], v[38:39]
	v_pk_mul_f32 v[32:33], v[42:43], v[50:51]
	s_nop 0
	v_pk_mul_f32 v[42:43], v[32:33], v[34:35]
	v_cvt_pk_bf16_f32 v32, v36, v37
	v_cvt_pk_bf16_f32 v33, v38, v39
	v_cvt_pk_bf16_f32 v34, v40, v41
	v_cvt_pk_bf16_f32 v35, v42, v43
	global_store_dwordx4 v[44:45], v[32:35], off
	v_mul_f32_e32 v36, 0xbfb8aa3b, v29
	v_exp_f32_e32 v36, v36
	v_mul_f32_e32 v34, 0xbfb8aa3b, v28
	v_mul_f32_e32 v35, 0xbfb8aa3b, v24
	v_exp_f32_e32 v34, v34
	v_exp_f32_e32 v35, v35
	v_add_u32_e32 v32, 0xa0, v152
	v_mad_i64_i32 v[32:33], s[24:25], v32, s57, v[144:145]
	v_add_f32_e32 v34, 1.0, v34
	v_add_f32_e32 v37, 1.0, v35
	v_add_f32_e32 v35, 1.0, v36
	v_rcp_f32_e32 v34, v34
	v_rcp_f32_e32 v35, v35
	v_mul_f32_e32 v36, 0xbfb8aa3b, v25
	v_exp_f32_e32 v38, v36
	v_rcp_f32_e32 v36, v37
	v_pk_mul_f32 v[28:29], v[28:29], v[34:35]
	v_mul_f32_e32 v34, 0xbfb8aa3b, v31
	v_pk_mul_f32 v[20:21], v[28:29], v[20:21]
	v_add_f32_e32 v28, 1.0, v38
	v_rcp_f32_e32 v37, v28
	v_mul_f32_e32 v29, 0xbfb8aa3b, v26
	v_mul_f32_e32 v28, 0xbfb8aa3b, v30
	v_exp_f32_e32 v29, v29
	v_exp_f32_e32 v28, v28
	v_exp_f32_e32 v35, v34
	v_mul_f32_e32 v34, 0xbfb8aa3b, v27
	v_pk_mul_f32 v[24:25], v[24:25], v[36:37]
	v_exp_f32_e32 v36, v34
	v_add_f32_e32 v29, 1.0, v29
	v_add_f32_e32 v28, 1.0, v28
	v_rcp_f32_e32 v34, v29
	v_add_f32_e32 v29, 1.0, v35
	v_rcp_f32_e32 v28, v28
	v_rcp_f32_e32 v29, v29
	v_add_f32_e32 v35, 1.0, v36
	v_rcp_f32_e32 v35, v35
	v_pk_mul_f32 v[24:25], v[24:25], v[16:17]
	v_pk_mul_f32 v[16:17], v[30:31], v[28:29]
	v_lshl_add_u64 v[28:29], v[32:33], 0, v[112:113]
	v_pk_mul_f32 v[22:23], v[16:17], v[22:23]
	v_pk_mul_f32 v[16:17], v[26:27], v[34:35]
	s_nop 0
	v_pk_mul_f32 v[26:27], v[16:17], v[18:19]
	v_cvt_pk_bf16_f32 v16, v20, v21
	v_cvt_pk_bf16_f32 v17, v22, v23
	v_cvt_pk_bf16_f32 v18, v24, v25
	v_cvt_pk_bf16_f32 v19, v26, v27
	global_store_dwordx4 v[28:29], v[16:19], off
	v_mul_f32_e32 v20, 0xbfb8aa3b, v13
	v_exp_f32_e32 v20, v20
	v_mul_f32_e32 v18, 0xbfb8aa3b, v12
	v_mul_f32_e32 v19, 0xbfb8aa3b, v8
	v_exp_f32_e32 v18, v18
	v_exp_f32_e32 v19, v19
	v_add_u32_e32 v16, 0xb0, v152
	v_mad_i64_i32 v[16:17], s[24:25], v16, s57, v[144:145]
	v_add_f32_e32 v18, 1.0, v18
	v_add_f32_e32 v21, 1.0, v19
	v_add_f32_e32 v19, 1.0, v20
	v_rcp_f32_e32 v18, v18
	v_rcp_f32_e32 v19, v19
	v_mul_f32_e32 v20, 0xbfb8aa3b, v9
	v_exp_f32_e32 v22, v20
	v_rcp_f32_e32 v20, v21
	v_pk_mul_f32 v[12:13], v[12:13], v[18:19]
	v_mul_f32_e32 v18, 0xbfb8aa3b, v15
	v_pk_mul_f32 v[4:5], v[12:13], v[4:5]
	v_add_f32_e32 v12, 1.0, v22
	v_rcp_f32_e32 v21, v12
	v_mul_f32_e32 v13, 0xbfb8aa3b, v10
	v_mul_f32_e32 v12, 0xbfb8aa3b, v14
	v_exp_f32_e32 v13, v13
	v_exp_f32_e32 v12, v12
	v_exp_f32_e32 v19, v18
	v_mul_f32_e32 v18, 0xbfb8aa3b, v11
	v_pk_mul_f32 v[8:9], v[8:9], v[20:21]
	v_exp_f32_e32 v20, v18
	v_add_f32_e32 v13, 1.0, v13
	v_add_f32_e32 v12, 1.0, v12
	v_rcp_f32_e32 v18, v13
	v_add_f32_e32 v13, 1.0, v19
	v_rcp_f32_e32 v12, v12
	v_rcp_f32_e32 v13, v13
	v_add_f32_e32 v19, 1.0, v20
	v_rcp_f32_e32 v19, v19
	v_pk_mul_f32 v[8:9], v[8:9], v[0:1]
	v_pk_mul_f32 v[0:1], v[14:15], v[12:13]
	v_lshl_add_u64 v[12:13], v[16:17], 0, v[112:113]
	v_pk_mul_f32 v[6:7], v[0:1], v[6:7]
	v_pk_mul_f32 v[0:1], v[10:11], v[18:19]
	s_mov_b64 s[24:25], s[18:19]
	v_pk_mul_f32 v[10:11], v[0:1], v[2:3]
	v_cvt_pk_bf16_f32 v0, v4, v5
	v_cvt_pk_bf16_f32 v1, v6, v7
	v_cvt_pk_bf16_f32 v2, v8, v9
	v_cvt_pk_bf16_f32 v3, v10, v11
	global_store_dwordx4 v[12:13], v[0:3], off
	s_cbranch_vccz .LBB0_846
	s_waitcnt vmcnt(0)
	s_cmpk_gt_u32 s40, 0xff
	s_cbranch_scc1 .LBB0_853
	s_barrier

; #define PG8_STAGE(bufoff, gbase, voff) do { _Pragma("unroll") for (int _i = 0; _i < 2; ++_i) \
;         __builtin_amdgcn_global_load_lds((const unsigned*)((const char*)(gbase) + (voff)[_i]), (LAS unsigned*)(lds + (bufoff) + ldsw + _i * 8192), 16, 0, 0); } while (0)
; #define PG8_LDA(dst, b, h) do { _Pragma("unroll") for (int m = 0; m < 4; ++m) _Pragma("unroll") for (int k = 0; k < 2; ++k) dst[m][k] = *(const LAS bf16x8*)(lds + PG8_SA(b, h) + aoff + m * 2048 + k * 1024); } while (0)
; #define PG8_LDB(dst, b, h) do { _Pragma("unroll") for (int n = 0; n < 2; ++n) _Pragma("unroll") for (int k = 0; k < 2; ++k) dst[n][k] = *(const LAS bf16x8*)(lds + PG8_SB(b, h) + boff + n * 2048 + k * 1024); } while (0)
; #define PG8_MMA(ai, bj, At, Bt) do { __builtin_amdgcn_s_setprio(1); _Pragma("unroll") for (int m = 0; m < 4; ++m) _Pragma("unroll") for (int n = 0; n < 2; ++n) _Pragma("unroll") for (int k = 0; k < 2; ++k) \
;         acc[ai][bj][m][n] = __builtin_amdgcn_mfma_f32_16x16x32_bf16(Bt[n][k], At[m][k], acc[ai][bj][m][n], 0, 0, 0); __builtin_amdgcn_s_setprio(0); } while (0)
; #define PG8_WAIT_L(n) asm volatile("s_waitcnt lgkmcnt(" #n ")" ::: "memory")
; #define PG8_BAR __builtin_amdgcn_s_barrier()
; #define PG8_SCHED __builtin_amdgcn_sched_barrier(0)
; template <class Epi>
; DI void gemm_phase(LAS unsigned char* lds, const Gemm g, const StaticOrder& S, const Epi& E) {
;     ...
;             PG8_LDB(B0, 0, 0); PG8_SCHED; PG8_LDA(At, 0, 0); PG8_STAGE(PG8_SA(1, 1), a1 + hstep, voffA);
;             PG8_WAIT_L(8); PG8_BAR; PG8_WAIT_L(0); PG8_MMA(0, 0, At, B0); PG8_BAR; PG8_SCHED;
;             PG8_LDB(B1, 0, 1); PG8_STAGE(PG8_SB(0, 0), b2, voffB);
;             PG8_BAR; PG8_WAIT_L(0); PG8_MMA(0, 1, At, B1); PG8_BAR;
;             PG8_LDA(At, 0, 1); PG8_STAGE(PG8_SA(0, 0), a2, voffA);
;             PG8_BAR; PG8_WAIT_L(0); PG8_MMA(1, 0, At, B0); PG8_BAR; PG8_SCHED;
.LBB0_928:
	ds_read_b128 v[128:131], v173
	ds_read_b128 v[132:135], v173 offset:1024
	ds_read_b128 v[136:139], v173 offset:2048
	ds_read_b128 v[140:143], v173 offset:3072
	s_add_u32 s38, s36, 0xfff50080
	s_addc_u32 s39, s37, -1
	s_cmp_eq_u32 s73, 40
	s_cselect_b32 s41, s7, s39
	s_cselect_b32 s40, s6, s38
	s_cselect_b32 s39, s9, s72
	s_cselect_b32 s38, s8, s71
	v_lshl_add_u64 v[168:169], s[36:37], 0, v[156:157]
	s_add_i32 m0, s49, 0xc000
	ds_read_b128 v[144:147], v174
	ds_read_b128 v[164:167], v174 offset:1024
	ds_read_b128 v[176:179], v174 offset:2048
	ds_read_b128 v[182:185], v174 offset:3072
	ds_read_b128 v[186:189], v174 offset:4096
	ds_read_b128 v[190:193], v174 offset:5120
	ds_read_b128 v[194:197], v174 offset:6144
	ds_read_b128 v[198:201], v174 offset:7168
	global_load_lds_dwordx4 v[168:169], off
	v_lshl_add_u64 v[168:169], s[36:37], 0, v[158:159]
	s_add_i32 m0, s49, 0xe000
	s_nop 0
	global_load_lds_dwordx4 v[168:169], off
	s_waitcnt lgkmcnt(8)
	s_barrier
	s_waitcnt lgkmcnt(0)
	s_waitcnt lgkmcnt(0)
	v_mfma_f32_16x16x32_bf16 v[124:127], v[128:131], v[144:147], v[124:127]
	v_mfma_f32_16x16x32_bf16 v[120:123], v[136:139], v[144:147], v[120:123]
	v_mfma_f32_16x16x32_bf16 v[116:119], v[128:131], v[176:179], v[116:119]
	v_mfma_f32_16x16x32_bf16 v[108:111], v[136:139], v[176:179], v[108:111]
	v_mfma_f32_16x16x32_bf16 v[92:95], v[128:131], v[186:189], v[92:95]
	v_mfma_f32_16x16x32_bf16 v[88:91], v[136:139], v[186:189], v[88:91]
	v_mfma_f32_16x16x32_bf16 v[76:79], v[128:131], v[194:197], v[76:79]
	v_mfma_f32_16x16x32_bf16 v[72:75], v[136:139], v[194:197], v[72:75]
	v_mfma_f32_16x16x32_bf16 v[124:127], v[132:135], v[164:167], v[124:127]
	v_mfma_f32_16x16x32_bf16 v[120:123], v[140:143], v[164:167], v[120:123]
	v_mfma_f32_16x16x32_bf16 v[116:119], v[132:135], v[182:185], v[116:119]
	v_mfma_f32_16x16x32_bf16 v[108:111], v[140:143], v[182:185], v[108:111]
	v_mfma_f32_16x16x32_bf16 v[92:95], v[132:135], v[190:193], v[92:95]
	v_mfma_f32_16x16x32_bf16 v[88:91], v[140:143], v[190:193], v[88:91]
	v_mfma_f32_16x16x32_bf16 v[76:79], v[132:135], v[198:201], v[76:79]
	v_mfma_f32_16x16x32_bf16 v[72:75], v[140:143], v[198:201], v[72:75]
	s_barrier
	s_add_i32 s74, s59, s48
	v_lshl_add_u64 v[168:169], s[38:39], 0, v[150:151]
	s_mov_b32 m0, s74
	ds_read_b128 v[202:205], v175
	ds_read_b128 v[206:209], v175 offset:1024
	ds_read_b128 v[210:213], v175 offset:2048
	ds_read_b128 v[214:217], v175 offset:3072
	global_load_lds_dwordx4 v[168:169], off
	v_lshl_add_u64 v[218:219], s[38:39], 0, v[154:155]
	s_add_i32 m0, s74, 0x2000
	s_nop 0
	global_load_lds_dwordx4 v[218:219], off
	s_barrier
	s_waitcnt lgkmcnt(0)
	s_waitcnt lgkmcnt(0)
	v_mfma_f32_16x16x32_bf16 v[112:115], v[202:205], v[144:147], v[112:115]
	v_mfma_f32_16x16x32_bf16 v[104:107], v[210:213], v[144:147], v[104:107]
	v_mfma_f32_16x16x32_bf16 v[100:103], v[202:205], v[176:179], v[100:103]
	v_mfma_f32_16x16x32_bf16 v[96:99], v[210:213], v[176:179], v[96:99]
	v_mfma_f32_16x16x32_bf16 v[84:87], v[202:205], v[186:189], v[84:87]
	v_mfma_f32_16x16x32_bf16 v[80:83], v[210:213], v[186:189], v[80:83]
	v_mfma_f32_16x16x32_bf16 v[68:71], v[202:205], v[194:197], v[68:71]
	v_mfma_f32_16x16x32_bf16 v[64:67], v[210:213], v[194:197], v[64:67]
	v_mfma_f32_16x16x32_bf16 v[112:115], v[206:209], v[164:167], v[112:115]
	v_mfma_f32_16x16x32_bf16 v[104:107], v[214:217], v[164:167], v[104:107]
	v_mfma_f32_16x16x32_bf16 v[100:103], v[206:209], v[182:185], v[100:103]
	v_mfma_f32_16x16x32_bf16 v[96:99], v[214:217], v[182:185], v[96:99]
	v_mfma_f32_16x16x32_bf16 v[84:87], v[206:209], v[190:193], v[84:87]
	v_mfma_f32_16x16x32_bf16 v[80:83], v[214:217], v[190:193], v[80:83]
	v_mfma_f32_16x16x32_bf16 v[68:71], v[206:209], v[198:201], v[68:71]
	v_mfma_f32_16x16x32_bf16 v[64:67], v[214:217], v[198:201], v[64:67]
	s_mov_b32 m0, s49
	v_lshl_add_u64 v[220:221], s[40:41], 0, v[148:149]
	s_barrier
	ds_read_b128 v[144:147], v174 offset:16384
	ds_read_b128 v[164:167], v174 offset:17408
	ds_read_b128 v[176:179], v174 offset:18432
	ds_read_b128 v[182:185], v174 offset:19456
	ds_read_b128 v[186:189], v174 offset:20480
	ds_read_b128 v[190:193], v174 offset:21504
	ds_read_b128 v[194:197], v174 offset:22528
	ds_read_b128 v[198:201], v174 offset:23552
	global_load_lds_dwordx4 v[220:221], off
	v_lshl_add_u64 v[222:223], s[40:41], 0, v[152:153]
	s_mov_b32 m0, s50
	s_nop 0
	global_load_lds_dwordx4 v[222:223], off
	s_barrier
	s_waitcnt lgkmcnt(0)
	s_waitcnt lgkmcnt(0)
	v_mfma_f32_16x16x32_bf16 v[60:63], v[128:131], v[144:147], v[60:63]
	v_mfma_f32_16x16x32_bf16 v[56:59], v[136:139], v[144:147], v[56:59]
	v_mfma_f32_16x16x32_bf16 v[44:47], v[128:131], v[176:179], v[44:47]
	v_mfma_f32_16x16x32_bf16 v[40:43], v[136:139], v[176:179], v[40:43]
	v_mfma_f32_16x16x32_bf16 v[36:39], v[128:131], v[186:189], v[36:39]
	v_mfma_f32_16x16x32_bf16 v[32:35], v[136:139], v[186:189], v[32:35]
	v_mfma_f32_16x16x32_bf16 v[20:23], v[128:131], v[194:197], v[20:23]
	v_mfma_f32_16x16x32_bf16 v[16:19], v[136:139], v[194:197], v[16:19]
	v_mfma_f32_16x16x32_bf16 v[60:63], v[132:135], v[164:167], v[60:63]
	v_mfma_f32_16x16x32_bf16 v[56:59], v[140:143], v[164:167], v[56:59]
	v_mfma_f32_16x16x32_bf16 v[44:47], v[132:135], v[182:185], v[44:47]
	v_mfma_f32_16x16x32_bf16 v[40:43], v[140:143], v[182:185], v[40:43]
	v_mfma_f32_16x16x32_bf16 v[36:39], v[132:135], v[190:193], v[36:39]
	v_mfma_f32_16x16x32_bf16 v[32:35], v[140:143], v[190:193], v[32:35]
	v_mfma_f32_16x16x32_bf16 v[20:23], v[132:135], v[198:201], v[20:23]
	v_mfma_f32_16x16x32_bf16 v[16:19], v[140:143], v[198:201], v[16:19]
	s_barrier
; #define PG8_STAGE(bufoff, gbase, voff) do { _Pragma("unroll") for (int _i = 0; _i < 2; ++_i) \
;         __builtin_amdgcn_global_load_lds((const unsigned*)((const char*)(gbase) + (voff)[_i]), (LAS unsigned*)(lds + (bufoff) + ldsw + _i * 8192), 16, 0, 0); } while (0)
; #define PG8_LDA(dst, b, h) do { _Pragma("unroll") for (int m = 0; m < 4; ++m) _Pragma("unroll") for (int k = 0; k < 2; ++k) dst[m][k] = *(const LAS bf16x8*)(lds + PG8_SA(b, h) + aoff + m * 2048 + k * 1024); } while (0)
; #define PG8_LDB(dst, b, h) do { _Pragma("unroll") for (int n = 0; n < 2; ++n) _Pragma("unroll") for (int k = 0; k < 2; ++k) dst[n][k] = *(const LAS bf16x8*)(lds + PG8_SB(b, h) + boff + n * 2048 + k * 1024); } while (0)
; #define PG8_MMA(ai, bj, At, Bt) do { __builtin_amdgcn_s_setprio(1); _Pragma("unroll") for (int m = 0; m < 4; ++m) _Pragma("unroll") for (int n = 0; n < 2; ++n) _Pragma("unroll") for (int k = 0; k < 2; ++k) \
;         acc[ai][bj][m][n] = __builtin_amdgcn_mfma_f32_16x16x32_bf16(Bt[n][k], At[m][k], acc[ai][bj][m][n], 0, 0, 0); __builtin_amdgcn_s_setprio(0); } while (0)
; #define PG8_WAIT_V(n) asm volatile("s_waitcnt vmcnt(" #n ")" ::: "memory")
; #define PG8_WAIT_L(n) asm volatile("s_waitcnt lgkmcnt(" #n ")" ::: "memory")
; #define PG8_BAR __builtin_amdgcn_s_barrier()
; #define PG8_SCHED __builtin_amdgcn_sched_barrier(0)
; template <class Epi>
; DI void gemm_phase(LAS unsigned char* lds, const Gemm g, const StaticOrder& S, const Epi& E) {
;     ...
;             PG8_STAGE(PG8_SB(0, 1), b2 + hstep, voffB);
;             PG8_WAIT_V(6); PG8_BAR; PG8_MMA(1, 1, At, B1); PG8_BAR;
;             PG8_LDB(B0, 1, 0); PG8_SCHED; PG8_LDA(At, 1, 0); PG8_STAGE(PG8_SA(0, 1), a2 + hstep, voffA);
;             PG8_WAIT_L(8); PG8_BAR; PG8_WAIT_L(0); PG8_MMA(0, 0, At, B0); PG8_BAR; PG8_SCHED;
;             PG8_LDB(B1, 1, 1); PG8_STAGE(PG8_SB(1, 0), b3, voffB);
;             PG8_BAR; PG8_WAIT_L(0); PG8_MMA(0, 1, At, B1); PG8_BAR;
;             PG8_LDA(At, 1, 1); PG8_STAGE(PG8_SA(1, 0), a3, voffA);
	s_add_u32 s74, s38, 0xb0000
	s_addc_u32 s75, s39, 0
	s_add_i32 s76, s60, s48
	v_lshl_add_u64 v[128:129], s[74:75], 0, v[150:151]
	s_mov_b32 m0, s76
	s_nop 0
	global_load_lds_dwordx4 v[128:129], off
	v_lshl_add_u64 v[128:129], s[74:75], 0, v[154:155]
	s_add_i32 m0, s76, 0x2000
	s_nop 0
	global_load_lds_dwordx4 v[128:129], off
	s_waitcnt vmcnt(6)
	s_barrier
	v_mfma_f32_16x16x32_bf16 v[52:55], v[202:205], v[144:147], v[52:55]
	v_mfma_f32_16x16x32_bf16 v[48:51], v[210:213], v[144:147], v[48:51]
	v_mfma_f32_16x16x32_bf16 v[28:31], v[202:205], v[176:179], v[28:31]
	v_mfma_f32_16x16x32_bf16 v[24:27], v[210:213], v[176:179], v[24:27]
	v_mfma_f32_16x16x32_bf16 v[12:15], v[202:205], v[186:189], v[12:15]
	v_mfma_f32_16x16x32_bf16 v[8:11], v[210:213], v[186:189], v[8:11]
	v_mfma_f32_16x16x32_bf16 v[4:7], v[202:205], v[194:197], v[4:7]
	v_mfma_f32_16x16x32_bf16 v[0:3], v[210:213], v[194:197], v[0:3]
	v_mfma_f32_16x16x32_bf16 v[52:55], v[206:209], v[164:167], v[52:55]
	v_mfma_f32_16x16x32_bf16 v[48:51], v[214:217], v[164:167], v[48:51]
	v_mfma_f32_16x16x32_bf16 v[28:31], v[206:209], v[182:185], v[28:31]
	v_mfma_f32_16x16x32_bf16 v[24:27], v[214:217], v[182:185], v[24:27]
	v_mfma_f32_16x16x32_bf16 v[12:15], v[206:209], v[190:193], v[12:15]
	v_mfma_f32_16x16x32_bf16 v[8:11], v[214:217], v[190:193], v[8:11]
	v_mfma_f32_16x16x32_bf16 v[4:7], v[206:209], v[198:201], v[4:7]
	v_mfma_f32_16x16x32_bf16 v[0:3], v[214:217], v[198:201], v[0:3]
	s_add_i32 s74, 0, 0x18000
	v_add_u32_e32 v140, s74, v171
	s_barrier
	ds_read_b128 v[128:131], v140
	ds_read_b128 v[132:135], v140 offset:1024
	ds_read_b128 v[136:139], v140 offset:2048
	ds_read_b128 v[140:143], v140 offset:3072
	s_add_u32 s40, s40, 0xb0000
	s_addc_u32 s41, s41, 0
	s_mov_b32 m0, s51
	v_lshl_add_u64 v[202:203], s[40:41], 0, v[148:149]
	ds_read_b128 v[144:147], v174 offset:32768
	ds_read_b128 v[164:167], v174 offset:33792
	ds_read_b128 v[176:179], v174 offset:34816
	ds_read_b128 v[182:185], v174 offset:35840
	ds_read_b128 v[186:189], v174 offset:36864
	ds_read_b128 v[190:193], v174 offset:37888
	ds_read_b128 v[194:197], v174 offset:38912
	ds_read_b128 v[198:201], v174 offset:39936
	global_load_lds_dwordx4 v[202:203], off
	v_lshl_add_u64 v[202:203], s[40:41], 0, v[152:153]
	s_mov_b32 m0, s52
	s_nop 0
	global_load_lds_dwordx4 v[202:203], off
	s_waitcnt lgkmcnt(8)
	s_barrier
	s_waitcnt lgkmcnt(0)
	s_waitcnt lgkmcnt(0)
	v_mfma_f32_16x16x32_bf16 v[124:127], v[128:131], v[144:147], v[124:127]
	v_mfma_f32_16x16x32_bf16 v[120:123], v[136:139], v[144:147], v[120:123]
	v_mfma_f32_16x16x32_bf16 v[116:119], v[128:131], v[176:179], v[116:119]
	v_mfma_f32_16x16x32_bf16 v[108:111], v[136:139], v[176:179], v[108:111]
	v_mfma_f32_16x16x32_bf16 v[92:95], v[128:131], v[186:189], v[92:95]
	v_mfma_f32_16x16x32_bf16 v[88:91], v[136:139], v[186:189], v[88:91]
	v_mfma_f32_16x16x32_bf16 v[76:79], v[128:131], v[194:197], v[76:79]
	v_mfma_f32_16x16x32_bf16 v[72:75], v[136:139], v[194:197], v[72:75]
	v_mfma_f32_16x16x32_bf16 v[124:127], v[132:135], v[164:167], v[124:127]
	v_mfma_f32_16x16x32_bf16 v[120:123], v[140:143], v[164:167], v[120:123]
	v_mfma_f32_16x16x32_bf16 v[116:119], v[132:135], v[182:185], v[116:119]
	v_mfma_f32_16x16x32_bf16 v[108:111], v[140:143], v[182:185], v[108:111]
	v_mfma_f32_16x16x32_bf16 v[92:95], v[132:135], v[190:193], v[92:95]
	v_mfma_f32_16x16x32_bf16 v[88:91], v[140:143], v[190:193], v[88:91]
	v_mfma_f32_16x16x32_bf16 v[76:79], v[132:135], v[198:201], v[76:79]
	v_mfma_f32_16x16x32_bf16 v[72:75], v[140:143], v[198:201], v[72:75]
	s_barrier
	s_add_i32 s40, 0, 0x1c000
	s_add_i32 s41, s74, s48
	v_add_u32_e32 v214, s40, v171
	v_lshl_add_u64 v[168:169], v[168:169], 0, s[16:17]
	s_mov_b32 m0, s41
	ds_read_b128 v[202:205], v214
	ds_read_b128 v[206:209], v214 offset:1024
	ds_read_b128 v[210:213], v214 offset:2048
	ds_read_b128 v[214:217], v214 offset:3072
	global_load_lds_dwordx4 v[168:169], off
	v_lshl_add_u64 v[168:169], v[218:219], 0, s[16:17]
	s_add_i32 m0, s41, 0x2000
	s_nop 0
	global_load_lds_dwordx4 v[168:169], off
	s_barrier
	s_waitcnt lgkmcnt(0)
	s_waitcnt lgkmcnt(0)
	v_mfma_f32_16x16x32_bf16 v[112:115], v[202:205], v[144:147], v[112:115]
	v_mfma_f32_16x16x32_bf16 v[104:107], v[210:213], v[144:147], v[104:107]
	v_mfma_f32_16x16x32_bf16 v[100:103], v[202:205], v[176:179], v[100:103]
	v_mfma_f32_16x16x32_bf16 v[96:99], v[210:213], v[176:179], v[96:99]
	v_mfma_f32_16x16x32_bf16 v[84:87], v[202:205], v[186:189], v[84:87]
	v_mfma_f32_16x16x32_bf16 v[80:83], v[210:213], v[186:189], v[80:83]
	v_mfma_f32_16x16x32_bf16 v[68:71], v[202:205], v[194:197], v[68:71]
	v_mfma_f32_16x16x32_bf16 v[64:67], v[210:213], v[194:197], v[64:67]
	v_mfma_f32_16x16x32_bf16 v[112:115], v[206:209], v[164:167], v[112:115]
	v_mfma_f32_16x16x32_bf16 v[104:107], v[214:217], v[164:167], v[104:107]
	v_mfma_f32_16x16x32_bf16 v[100:103], v[206:209], v[182:185], v[100:103]
	v_mfma_f32_16x16x32_bf16 v[96:99], v[214:217], v[182:185], v[96:99]
	v_mfma_f32_16x16x32_bf16 v[84:87], v[206:209], v[190:193], v[84:87]
	v_mfma_f32_16x16x32_bf16 v[80:83], v[214:217], v[190:193], v[80:83]
	v_mfma_f32_16x16x32_bf16 v[68:71], v[206:209], v[198:201], v[68:71]
	v_mfma_f32_16x16x32_bf16 v[64:67], v[214:217], v[198:201], v[64:67]
	s_mov_b32 m0, s56
	v_lshl_add_u64 v[168:169], v[220:221], 0, s[16:17]
	s_barrier
	ds_read_b128 v[144:147], v174 offset:49152
	ds_read_b128 v[164:167], v174 offset:50176
	ds_read_b128 v[176:179], v174 offset:51200
	ds_read_b128 v[182:185], v174 offset:52224
	ds_read_b128 v[186:189], v174 offset:53248
	ds_read_b128 v[190:193], v174 offset:54272
	ds_read_b128 v[194:197], v174 offset:55296
	ds_read_b128 v[198:201], v174 offset:56320
	global_load_lds_dwordx4 v[168:169], off
	v_lshl_add_u64 v[168:169], v[222:223], 0, s[16:17]
	s_mov_b32 m0, s57
	s_nop 0
	global_load_lds_dwordx4 v[168:169], off
	s_barrier
; DI unsigned pk2(float a, float b) { f32x2 v = {a, b}; bf16x2_t r = __builtin_convertvector(v, bf16x2_t); return __builtin_bit_cast(unsigned, r); }
; DI float bflo(unsigned u) { return __uint_as_float(u << 16); }
; DI float bfhi(unsigned u) { return __uint_as_float(u & 0xffff0000u); }
; #define PG8_STAGE(bufoff, gbase, voff) do { _Pragma("unroll") for (int _i = 0; _i < 2; ++_i) \
;         __builtin_amdgcn_global_load_lds((const unsigned*)((const char*)(gbase) + (voff)[_i]), (LAS unsigned*)(lds + (bufoff) + ldsw + _i * 8192), 16, 0, 0); } while (0)
; #define PG8_WAIT_V(n) asm volatile("s_waitcnt vmcnt(" #n ")" ::: "memory")
; #define PG8_WAIT_L(n) asm volatile("s_waitcnt lgkmcnt(" #n ")" ::: "memory")
; #define PG8_BAR __builtin_amdgcn_s_barrier()
; #define PG8_SCHED __builtin_amdgcn_sched_barrier(0)
; template <class Epi>
; DI void gemm_phase(LAS unsigned char* lds, const Gemm g, const StaticOrder& S, const Epi& E) {
;     ...
;             PG8_BAR; PG8_WAIT_L(0); PG8_MMA(1, 0, At, B0); PG8_BAR; PG8_SCHED;
;             PG8_STAGE(PG8_SB(1, 1), b3 + hstep, voffB);
;             PG8_WAIT_V(6); PG8_BAR; PG8_MMA(1, 1, At, B1); PG8_BAR;
;     DI void operator()(const f32x4 (&acc)[2][2][4][2], const Unit& u, int wr, int wc, int fr, int fq) const {
;         const int row0 = u.pm * BM + wr * 64 + fr, col0 = u.pn * BM + wc * 32 + 8 * fq;
;         const float* gp = gate + (size_t)((u.pm * BM) >> 12) * NMODC + col0;
;         f32x4 gv[2][2];
; #pragma unroll
;         for (int bj = 0; bj < 2; ++bj)
; #pragma unroll
;             for (int n = 0; n < 2; ++n) gv[bj][n] = *(const f32x4*)(gp + bj * HALF + n * 4);
; #pragma unroll
;         for (int ai = 0; ai < 2; ++ai)
; #pragma unroll
;             for (int m = 0; m < 4; ++m) { const size_t ro = (size_t)(row0 + ai * HALF + m * 16) * DM + col0;
; #pragma unroll
;                 for (int bj = 0; bj < 2; ++bj) {
;                     const u32x4 q = *(const u32x4*)(xb + ro + bj * HALF);
;                     const f32x4 b0 = {bflo(q.x), bfhi(q.x), bflo(q.y), bfhi(q.y)}, b1 = {bflo(q.z), bfhi(q.z), bflo(q.w), bfhi(q.w)};
;                     const f32x4 x0 = b0 + gv[bj][0] * acc[ai][bj][m][0], x1 = b1 + gv[bj][1] * acc[ai][bj][m][1];
;                     u32x4 w; w.x = pk2(x0.x, x0.y); w.y = pk2(x0.z, x0.w); w.z = pk2(x1.x, x1.y); w.w = pk2(x1.z, x1.w);
;                     *(u32x4*)(xb + ro + bj * HALF) = w; } }
	s_waitcnt lgkmcnt(0)
	s_waitcnt lgkmcnt(0)
	v_mfma_f32_16x16x32_bf16 v[60:63], v[128:131], v[144:147], v[60:63]
	v_mfma_f32_16x16x32_bf16 v[56:59], v[136:139], v[144:147], v[56:59]
	v_mfma_f32_16x16x32_bf16 v[44:47], v[128:131], v[176:179], v[44:47]
	v_mfma_f32_16x16x32_bf16 v[40:43], v[136:139], v[176:179], v[40:43]
	v_mfma_f32_16x16x32_bf16 v[36:39], v[128:131], v[186:189], v[36:39]
	v_mfma_f32_16x16x32_bf16 v[32:35], v[136:139], v[186:189], v[32:35]
	v_mfma_f32_16x16x32_bf16 v[20:23], v[128:131], v[194:197], v[20:23]
	v_mfma_f32_16x16x32_bf16 v[16:19], v[136:139], v[194:197], v[16:19]
	v_mfma_f32_16x16x32_bf16 v[60:63], v[132:135], v[164:167], v[60:63]
	v_mfma_f32_16x16x32_bf16 v[56:59], v[140:143], v[164:167], v[56:59]
	v_mfma_f32_16x16x32_bf16 v[44:47], v[132:135], v[182:185], v[44:47]
	v_mfma_f32_16x16x32_bf16 v[40:43], v[140:143], v[182:185], v[40:43]
	v_mfma_f32_16x16x32_bf16 v[36:39], v[132:135], v[190:193], v[36:39]
	v_mfma_f32_16x16x32_bf16 v[32:35], v[140:143], v[190:193], v[32:35]
	v_mfma_f32_16x16x32_bf16 v[20:23], v[132:135], v[198:201], v[20:23]
	v_mfma_f32_16x16x32_bf16 v[16:19], v[140:143], v[198:201], v[16:19]
	s_barrier
	s_add_u32 s38, s38, 0xb0080
	s_addc_u32 s39, s39, 0
	s_add_i32 s40, s40, s48
	v_lshl_add_u64 v[128:129], s[38:39], 0, v[150:151]
	s_mov_b32 m0, s40
	s_nop 0
	global_load_lds_dwordx4 v[128:129], off
	v_lshl_add_u64 v[128:129], s[38:39], 0, v[154:155]
	s_add_i32 m0, s40, 0x2000
	s_nop 0
	global_load_lds_dwordx4 v[128:129], off
	s_waitcnt vmcnt(6)
	s_barrier
	v_mfma_f32_16x16x32_bf16 v[52:55], v[202:205], v[144:147], v[52:55]
	v_mfma_f32_16x16x32_bf16 v[48:51], v[210:213], v[144:147], v[48:51]
	v_mfma_f32_16x16x32_bf16 v[28:31], v[202:205], v[176:179], v[28:31]
	v_mfma_f32_16x16x32_bf16 v[24:27], v[210:213], v[176:179], v[24:27]
	v_mfma_f32_16x16x32_bf16 v[12:15], v[202:205], v[186:189], v[12:15]
	v_mfma_f32_16x16x32_bf16 v[8:11], v[210:213], v[186:189], v[8:11]
	v_mfma_f32_16x16x32_bf16 v[4:7], v[202:205], v[194:197], v[4:7]
	v_mfma_f32_16x16x32_bf16 v[0:3], v[210:213], v[194:197], v[0:3]
	v_mfma_f32_16x16x32_bf16 v[52:55], v[206:209], v[164:167], v[52:55]
	v_mfma_f32_16x16x32_bf16 v[48:51], v[214:217], v[164:167], v[48:51]
	v_mfma_f32_16x16x32_bf16 v[28:31], v[206:209], v[182:185], v[28:31]
	v_mfma_f32_16x16x32_bf16 v[24:27], v[214:217], v[182:185], v[24:27]
	v_mfma_f32_16x16x32_bf16 v[12:15], v[206:209], v[190:193], v[12:15]
	v_mfma_f32_16x16x32_bf16 v[8:11], v[214:217], v[190:193], v[8:11]
	v_mfma_f32_16x16x32_bf16 v[4:7], v[206:209], v[198:201], v[4:7]
	v_mfma_f32_16x16x32_bf16 v[0:3], v[214:217], v[198:201], v[0:3]
	s_add_i32 s73, s73, 2
	s_add_u32 s36, s36, 0x100
	s_addc_u32 s37, s37, 0
	s_add_u32 s71, s71, 0x100
	s_addc_u32 s72, s72, 0
	s_cmp_gt_u32 s73, 41
	s_barrier
	s_cbranch_scc0 .LBB0_928
	v_lshl_add_u32 v147, s67, 8, v170
	v_lshl_or_b32 v164, s70, 8, v172
	s_ashr_i32 s36, s67, 4
	s_mul_hi_i32 s37, s36, 0x6000
	s_mulk_i32 s36, 0x6000
	s_add_u32 s36, s54, s36
	s_addc_u32 s37, s55, s37
	v_lshlrev_b32_e32 v145, 2, v164
	v_lshlrev_b32_e32 v144, 11, v147
	global_load_dwordx4 v[128:131], v145, s[36:37]
	global_load_dwordx4 v[132:135], v145, s[36:37] offset:16
	global_load_dwordx4 v[136:139], v145, s[36:37] offset:512
	global_load_dwordx4 v[140:143], v145, s[36:37] offset:528
	v_lshl_add_u32 v144, v164, 1, v144
	s_mov_b32 s70, s65
	s_mov_b32 s67, s66
	s_mov_b64 s[38:39], s[8:9]
	s_mov_b64 s[36:37], s[6:7]
	global_load_dwordx4 v[184:187], v144, s[14:15]
	global_load_dwordx4 v[188:191], v144, s[14:15] offset:256
	v_add_u32_e32 v146, 0x8000, v144
	global_load_dwordx4 v[192:195], v146, s[14:15]
	global_load_dwordx4 v[196:199], v146, s[14:15] offset:256
	v_add_u32_e32 v146, 0x10000, v144
	global_load_dwordx4 v[200:203], v146, s[14:15]
	global_load_dwordx4 v[204:207], v146, s[14:15] offset:256
	v_add_u32_e32 v146, 0x18000, v144
	global_load_dwordx4 v[208:211], v146, s[14:15]
	global_load_dwordx4 v[212:215], v146, s[14:15] offset:256
	v_add_u32_e32 v146, 0x40000, v144
	global_load_dwordx4 v[216:219], v146, s[14:15]
	global_load_dwordx4 v[220:223], v146, s[14:15] offset:256
	v_add_u32_e32 v146, 0x48000, v144
	global_load_dwordx4 v[224:227], v146, s[14:15]
	global_load_dwordx4 v[228:231], v146, s[14:15] offset:256
	v_add_u32_e32 v146, 0x50000, v144
	global_load_dwordx4 v[232:235], v146, s[14:15]
	global_load_dwordx4 v[236:239], v146, s[14:15] offset:256
	v_add_u32_e32 v146, 0x58000, v144
	global_load_dwordx4 v[240:243], v146, s[14:15]
	global_load_dwordx4 v[244:247], v146, s[14:15] offset:256
	s_waitcnt vmcnt(15)
	v_lshlrev_b32_e32 v248, 16, v184
	v_and_b32_e32 v249, 0xffff0000, v184
	v_lshlrev_b32_e32 v250, 16, v185
	v_and_b32_e32 v251, 0xffff0000, v185
	v_lshlrev_b32_e32 v252, 16, v186
	v_and_b32_e32 v253, 0xffff0000, v186
	v_lshlrev_b32_e32 v254, 16, v187
	v_and_b32_e32 v255, 0xffff0000, v187
	v_pk_fma_f32 v[124:125], v[124:125], v[128:129], v[248:249]
	v_pk_fma_f32 v[126:127], v[126:127], v[130:131], v[250:251]
	v_pk_fma_f32 v[120:121], v[120:121], v[132:133], v[252:253]
	v_pk_fma_f32 v[122:123], v[122:123], v[134:135], v[254:255]
	v_cvt_pk_bf16_f32 v124, v124, v125
	v_cvt_pk_bf16_f32 v125, v126, v127
	v_cvt_pk_bf16_f32 v126, v120, v121
	v_cvt_pk_bf16_f32 v127, v122, v123
	global_store_dwordx4 v144, v[124:127], s[14:15]
	s_waitcnt vmcnt(15)
; DI unsigned pk2(float a, float b) { f32x2 v = {a, b}; bf16x2_t r = __builtin_convertvector(v, bf16x2_t); return __builtin_bit_cast(unsigned, r); }
; DI float bflo(unsigned u) { return __uint_as_float(u << 16); }
; DI float bfhi(unsigned u) { return __uint_as_float(u & 0xffff0000u); }
;     DI void operator()(const f32x4 (&acc)[2][2][4][2], const Unit& u, int wr, int wc, int fr, int fq) const {
;     ...
;         for (int ai = 0; ai < 2; ++ai)
; #pragma unroll
;             for (int m = 0; m < 4; ++m) { const size_t ro = (size_t)(row0 + ai * HALF + m * 16) * DM + col0;
; #pragma unroll
;                 for (int bj = 0; bj < 2; ++bj) {
;                     const u32x4 q = *(const u32x4*)(xb + ro + bj * HALF);
;                     const f32x4 b0 = {bflo(q.x), bfhi(q.x), bflo(q.y), bfhi(q.y)}, b1 = {bflo(q.z), bfhi(q.z), bflo(q.w), bfhi(q.w)};
;                     const f32x4 x0 = b0 + gv[bj][0] * acc[ai][bj][m][0], x1 = b1 + gv[bj][1] * acc[ai][bj][m][1];
;                     u32x4 w; w.x = pk2(x0.x, x0.y); w.y = pk2(x0.z, x0.w); w.z = pk2(x1.x, x1.y); w.w = pk2(x1.z, x1.w);
;                     *(u32x4*)(xb + ro + bj * HALF) = w; } }
	v_lshlrev_b32_e32 v248, 16, v188
	v_and_b32_e32 v249, 0xffff0000, v188
	v_lshlrev_b32_e32 v250, 16, v189
	v_and_b32_e32 v251, 0xffff0000, v189
	v_lshlrev_b32_e32 v252, 16, v190
	v_and_b32_e32 v253, 0xffff0000, v190
	v_lshlrev_b32_e32 v254, 16, v191
	v_and_b32_e32 v255, 0xffff0000, v191
	v_pk_fma_f32 v[112:113], v[112:113], v[136:137], v[248:249]
	v_pk_fma_f32 v[114:115], v[114:115], v[138:139], v[250:251]
	v_pk_fma_f32 v[104:105], v[104:105], v[140:141], v[252:253]
	v_pk_fma_f32 v[106:107], v[106:107], v[142:143], v[254:255]
	v_cvt_pk_bf16_f32 v112, v112, v113
	v_cvt_pk_bf16_f32 v113, v114, v115
	v_cvt_pk_bf16_f32 v114, v104, v105
	v_cvt_pk_bf16_f32 v115, v106, v107
	global_store_dwordx4 v144, v[112:115], s[14:15] offset:256
	s_waitcnt vmcnt(15)
	v_lshlrev_b32_e32 v248, 16, v192
	v_and_b32_e32 v249, 0xffff0000, v192
	v_lshlrev_b32_e32 v250, 16, v193
	v_and_b32_e32 v251, 0xffff0000, v193
	v_lshlrev_b32_e32 v252, 16, v194
	v_and_b32_e32 v253, 0xffff0000, v194
	v_lshlrev_b32_e32 v254, 16, v195
	v_and_b32_e32 v255, 0xffff0000, v195
	v_pk_fma_f32 v[116:117], v[116:117], v[128:129], v[248:249]
	v_pk_fma_f32 v[118:119], v[118:119], v[130:131], v[250:251]
	v_pk_fma_f32 v[108:109], v[108:109], v[132:133], v[252:253]
	v_pk_fma_f32 v[110:111], v[110:111], v[134:135], v[254:255]
	v_cvt_pk_bf16_f32 v116, v116, v117
	v_cvt_pk_bf16_f32 v117, v118, v119
	v_cvt_pk_bf16_f32 v118, v108, v109
	v_cvt_pk_bf16_f32 v119, v110, v111
	v_add_u32_e32 v146, 0x8000, v144
	global_store_dwordx4 v146, v[116:119], s[14:15]
	s_waitcnt vmcnt(15)
	v_lshlrev_b32_e32 v248, 16, v196
	v_and_b32_e32 v249, 0xffff0000, v196
	v_lshlrev_b32_e32 v250, 16, v197
	v_and_b32_e32 v251, 0xffff0000, v197
	v_lshlrev_b32_e32 v252, 16, v198
	v_and_b32_e32 v253, 0xffff0000, v198
	v_lshlrev_b32_e32 v254, 16, v199
	v_and_b32_e32 v255, 0xffff0000, v199
	v_pk_fma_f32 v[100:101], v[100:101], v[136:137], v[248:249]
	v_pk_fma_f32 v[102:103], v[102:103], v[138:139], v[250:251]
	v_pk_fma_f32 v[96:97], v[96:97], v[140:141], v[252:253]
	v_pk_fma_f32 v[98:99], v[98:99], v[142:143], v[254:255]
	v_cvt_pk_bf16_f32 v100, v100, v101
	v_cvt_pk_bf16_f32 v101, v102, v103
	v_cvt_pk_bf16_f32 v102, v96, v97
	v_cvt_pk_bf16_f32 v103, v98, v99
	v_add_u32_e32 v146, 0x8000, v144
	global_store_dwordx4 v146, v[100:103], s[14:15] offset:256
	s_waitcnt vmcnt(15)
	v_lshlrev_b32_e32 v248, 16, v200
	v_and_b32_e32 v249, 0xffff0000, v200
	v_lshlrev_b32_e32 v250, 16, v201
	v_and_b32_e32 v251, 0xffff0000, v201
	v_lshlrev_b32_e32 v252, 16, v202
	v_and_b32_e32 v253, 0xffff0000, v202
	v_lshlrev_b32_e32 v254, 16, v203
	v_and_b32_e32 v255, 0xffff0000, v203
	v_pk_fma_f32 v[92:93], v[92:93], v[128:129], v[248:249]
	v_pk_fma_f32 v[94:95], v[94:95], v[130:131], v[250:251]
	v_pk_fma_f32 v[88:89], v[88:89], v[132:133], v[252:253]
	v_pk_fma_f32 v[90:91], v[90:91], v[134:135], v[254:255]
	v_cvt_pk_bf16_f32 v92, v92, v93
	v_cvt_pk_bf16_f32 v93, v94, v95
	v_cvt_pk_bf16_f32 v94, v88, v89
	v_cvt_pk_bf16_f32 v95, v90, v91
	v_add_u32_e32 v146, 0x10000, v144
	global_store_dwordx4 v146, v[92:95], s[14:15]
	s_waitcnt vmcnt(15)
	v_lshlrev_b32_e32 v248, 16, v204
	v_and_b32_e32 v249, 0xffff0000, v204
	v_lshlrev_b32_e32 v250, 16, v205
	v_and_b32_e32 v251, 0xffff0000, v205
	v_lshlrev_b32_e32 v252, 16, v206
	v_and_b32_e32 v253, 0xffff0000, v206
	v_lshlrev_b32_e32 v254, 16, v207
	v_and_b32_e32 v255, 0xffff0000, v207
	v_pk_fma_f32 v[84:85], v[84:85], v[136:137], v[248:249]
	v_pk_fma_f32 v[86:87], v[86:87], v[138:139], v[250:251]
	v_pk_fma_f32 v[80:81], v[80:81], v[140:141], v[252:253]
	v_pk_fma_f32 v[82:83], v[82:83], v[142:143], v[254:255]
	v_cvt_pk_bf16_f32 v84, v84, v85
	v_cvt_pk_bf16_f32 v85, v86, v87
	v_cvt_pk_bf16_f32 v86, v80, v81
	v_cvt_pk_bf16_f32 v87, v82, v83
	v_add_u32_e32 v146, 0x10000, v144
	global_store_dwordx4 v146, v[84:87], s[14:15] offset:256
	s_waitcnt vmcnt(15)
	v_lshlrev_b32_e32 v248, 16, v208
	v_and_b32_e32 v249, 0xffff0000, v208
	v_lshlrev_b32_e32 v250, 16, v209
	v_and_b32_e32 v251, 0xffff0000, v209
	v_lshlrev_b32_e32 v252, 16, v210
	v_and_b32_e32 v253, 0xffff0000, v210
	v_lshlrev_b32_e32 v254, 16, v211
	v_and_b32_e32 v255, 0xffff0000, v211
	v_pk_fma_f32 v[76:77], v[76:77], v[128:129], v[248:249]
	v_pk_fma_f32 v[78:79], v[78:79], v[130:131], v[250:251]
	v_pk_fma_f32 v[72:73], v[72:73], v[132:133], v[252:253]
	v_pk_fma_f32 v[74:75], v[74:75], v[134:135], v[254:255]
	v_cvt_pk_bf16_f32 v76, v76, v77
	v_cvt_pk_bf16_f32 v77, v78, v79
	v_cvt_pk_bf16_f32 v78, v72, v73
	v_cvt_pk_bf16_f32 v79, v74, v75
	v_add_u32_e32 v146, 0x18000, v144
	global_store_dwordx4 v146, v[76:79], s[14:15]
	s_waitcnt vmcnt(15)
	v_lshlrev_b32_e32 v248, 16, v212
	v_and_b32_e32 v249, 0xffff0000, v212
	v_lshlrev_b32_e32 v250, 16, v213
	v_and_b32_e32 v251, 0xffff0000, v213
	v_lshlrev_b32_e32 v252, 16, v214
	v_and_b32_e32 v253, 0xffff0000, v214
	v_lshlrev_b32_e32 v254, 16, v215
	v_and_b32_e32 v255, 0xffff0000, v215
	v_pk_fma_f32 v[68:69], v[68:69], v[136:137], v[248:249]
	v_pk_fma_f32 v[70:71], v[70:71], v[138:139], v[250:251]
	v_pk_fma_f32 v[64:65], v[64:65], v[140:141], v[252:253]
	v_pk_fma_f32 v[66:67], v[66:67], v[142:143], v[254:255]
	v_cvt_pk_bf16_f32 v68, v68, v69
	v_cvt_pk_bf16_f32 v69, v70, v71
	v_cvt_pk_bf16_f32 v70, v64, v65
	v_cvt_pk_bf16_f32 v71, v66, v67
	v_add_u32_e32 v146, 0x18000, v144
	global_store_dwordx4 v146, v[68:71], s[14:15] offset:256
	s_waitcnt vmcnt(15)
; DI unsigned pk2(float a, float b) { f32x2 v = {a, b}; bf16x2_t r = __builtin_convertvector(v, bf16x2_t); return __builtin_bit_cast(unsigned, r); }
; DI float bflo(unsigned u) { return __uint_as_float(u << 16); }
; DI float bfhi(unsigned u) { return __uint_as_float(u & 0xffff0000u); }
; #define PG8_WAIT_V(n) asm volatile("s_waitcnt vmcnt(" #n ")" ::: "memory")
; #define PG8_BAR __builtin_amdgcn_s_barrier()
; template <class Epi>
; DI void gemm_phase(LAS unsigned char* lds, const Gemm g, const StaticOrder& S, const Epi& E) {
;     ...
;         E(acc, cur, wr, wc, fr, fq);
;         if (!has_next) break;
; #pragma unroll
;         for (int a = 0; a < 2; ++a)
; #pragma unroll
;             for (int b = 0; b < 2; ++b)
; #pragma unroll
;                 for (int m = 0; m < 4; ++m)
; #pragma unroll
;                     for (int n = 0; n < 2; ++n) acc[a][b][m][n] = (f32x4){0.f, 0.f, 0.f, 0.f};
;         cur = nxt; cA = nA; cB = nB; ++ui;
;     }
;     PG8_WAIT_V(0);
;     if (wr == 0) PG8_BAR;
;     PG8_BAR;
;     DI void operator()(const f32x4 (&acc)[2][2][4][2], const Unit& u, int wr, int wc, int fr, int fq) const {
;     ...
;         for (int ai = 0; ai < 2; ++ai)
; #pragma unroll
;             for (int m = 0; m < 4; ++m) { const size_t ro = (size_t)(row0 + ai * HALF + m * 16) * DM + col0;
; #pragma unroll
;                 for (int bj = 0; bj < 2; ++bj) {
;                     const u32x4 q = *(const u32x4*)(xb + ro + bj * HALF);
;                     const f32x4 b0 = {bflo(q.x), bfhi(q.x), bflo(q.y), bfhi(q.y)}, b1 = {bflo(q.z), bfhi(q.z), bflo(q.w), bfhi(q.w)};
;                     const f32x4 x0 = b0 + gv[bj][0] * acc[ai][bj][m][0], x1 = b1 + gv[bj][1] * acc[ai][bj][m][1];
;                     u32x4 w; w.x = pk2(x0.x, x0.y); w.y = pk2(x0.z, x0.w); w.z = pk2(x1.x, x1.y); w.w = pk2(x1.z, x1.w);
;                     *(u32x4*)(xb + ro + bj * HALF) = w; } }
	v_lshlrev_b32_e32 v248, 16, v216
	v_and_b32_e32 v249, 0xffff0000, v216
	v_lshlrev_b32_e32 v250, 16, v217
	v_and_b32_e32 v251, 0xffff0000, v217
	v_lshlrev_b32_e32 v252, 16, v218
	v_and_b32_e32 v253, 0xffff0000, v218
	v_lshlrev_b32_e32 v254, 16, v219
	v_and_b32_e32 v255, 0xffff0000, v219
	v_pk_fma_f32 v[60:61], v[60:61], v[128:129], v[248:249]
	v_pk_fma_f32 v[62:63], v[62:63], v[130:131], v[250:251]
	v_pk_fma_f32 v[56:57], v[56:57], v[132:133], v[252:253]
	v_pk_fma_f32 v[58:59], v[58:59], v[134:135], v[254:255]
	v_cvt_pk_bf16_f32 v60, v60, v61
	v_cvt_pk_bf16_f32 v61, v62, v63
	v_cvt_pk_bf16_f32 v62, v56, v57
	v_cvt_pk_bf16_f32 v63, v58, v59
	v_add_u32_e32 v146, 0x40000, v144
	global_store_dwordx4 v146, v[60:63], s[14:15]
	s_waitcnt vmcnt(15)
	v_lshlrev_b32_e32 v248, 16, v220
	v_and_b32_e32 v249, 0xffff0000, v220
	v_lshlrev_b32_e32 v250, 16, v221
	v_and_b32_e32 v251, 0xffff0000, v221
	v_lshlrev_b32_e32 v252, 16, v222
	v_and_b32_e32 v253, 0xffff0000, v222
	v_lshlrev_b32_e32 v254, 16, v223
	v_and_b32_e32 v255, 0xffff0000, v223
	v_pk_fma_f32 v[52:53], v[52:53], v[136:137], v[248:249]
	v_pk_fma_f32 v[54:55], v[54:55], v[138:139], v[250:251]
	v_pk_fma_f32 v[48:49], v[48:49], v[140:141], v[252:253]
	v_pk_fma_f32 v[50:51], v[50:51], v[142:143], v[254:255]
	v_cvt_pk_bf16_f32 v52, v52, v53
	v_cvt_pk_bf16_f32 v53, v54, v55
	v_cvt_pk_bf16_f32 v54, v48, v49
	v_cvt_pk_bf16_f32 v55, v50, v51
	v_add_u32_e32 v146, 0x40000, v144
	global_store_dwordx4 v146, v[52:55], s[14:15] offset:256
	s_waitcnt vmcnt(15)
	v_lshlrev_b32_e32 v248, 16, v224
	v_and_b32_e32 v249, 0xffff0000, v224
	v_lshlrev_b32_e32 v250, 16, v225
	v_and_b32_e32 v251, 0xffff0000, v225
	v_lshlrev_b32_e32 v252, 16, v226
	v_and_b32_e32 v253, 0xffff0000, v226
	v_lshlrev_b32_e32 v254, 16, v227
	v_and_b32_e32 v255, 0xffff0000, v227
	v_pk_fma_f32 v[44:45], v[44:45], v[128:129], v[248:249]
	v_pk_fma_f32 v[46:47], v[46:47], v[130:131], v[250:251]
	v_pk_fma_f32 v[40:41], v[40:41], v[132:133], v[252:253]
	v_pk_fma_f32 v[42:43], v[42:43], v[134:135], v[254:255]
	v_cvt_pk_bf16_f32 v44, v44, v45
	v_cvt_pk_bf16_f32 v45, v46, v47
	v_cvt_pk_bf16_f32 v46, v40, v41
	v_cvt_pk_bf16_f32 v47, v42, v43
	v_add_u32_e32 v146, 0x48000, v144
	global_store_dwordx4 v146, v[44:47], s[14:15]
	s_waitcnt vmcnt(15)
	v_lshlrev_b32_e32 v248, 16, v228
	v_and_b32_e32 v249, 0xffff0000, v228
	v_lshlrev_b32_e32 v250, 16, v229
	v_and_b32_e32 v251, 0xffff0000, v229
	v_lshlrev_b32_e32 v252, 16, v230
	v_and_b32_e32 v253, 0xffff0000, v230
	v_lshlrev_b32_e32 v254, 16, v231
	v_and_b32_e32 v255, 0xffff0000, v231
	v_pk_fma_f32 v[28:29], v[28:29], v[136:137], v[248:249]
	v_pk_fma_f32 v[30:31], v[30:31], v[138:139], v[250:251]
	v_pk_fma_f32 v[24:25], v[24:25], v[140:141], v[252:253]
	v_pk_fma_f32 v[26:27], v[26:27], v[142:143], v[254:255]
	v_cvt_pk_bf16_f32 v28, v28, v29
	v_cvt_pk_bf16_f32 v29, v30, v31
	v_cvt_pk_bf16_f32 v30, v24, v25
	v_cvt_pk_bf16_f32 v31, v26, v27
	v_add_u32_e32 v146, 0x48000, v144
	global_store_dwordx4 v146, v[28:31], s[14:15] offset:256
	s_waitcnt vmcnt(15)
	v_lshlrev_b32_e32 v248, 16, v232
	v_and_b32_e32 v249, 0xffff0000, v232
	v_lshlrev_b32_e32 v250, 16, v233
	v_and_b32_e32 v251, 0xffff0000, v233
	v_lshlrev_b32_e32 v252, 16, v234
	v_and_b32_e32 v253, 0xffff0000, v234
	v_lshlrev_b32_e32 v254, 16, v235
	v_and_b32_e32 v255, 0xffff0000, v235
	v_pk_fma_f32 v[36:37], v[36:37], v[128:129], v[248:249]
	v_pk_fma_f32 v[38:39], v[38:39], v[130:131], v[250:251]
	v_pk_fma_f32 v[32:33], v[32:33], v[132:133], v[252:253]
	v_pk_fma_f32 v[34:35], v[34:35], v[134:135], v[254:255]
	v_cvt_pk_bf16_f32 v36, v36, v37
	v_cvt_pk_bf16_f32 v37, v38, v39
	v_cvt_pk_bf16_f32 v38, v32, v33
	v_cvt_pk_bf16_f32 v39, v34, v35
	v_add_u32_e32 v146, 0x50000, v144
	global_store_dwordx4 v146, v[36:39], s[14:15]
	s_waitcnt vmcnt(15)
	v_lshlrev_b32_e32 v248, 16, v236
	v_and_b32_e32 v249, 0xffff0000, v236
	v_lshlrev_b32_e32 v250, 16, v237
	v_and_b32_e32 v251, 0xffff0000, v237
	v_lshlrev_b32_e32 v252, 16, v238
	v_and_b32_e32 v253, 0xffff0000, v238
	v_lshlrev_b32_e32 v254, 16, v239
	v_and_b32_e32 v255, 0xffff0000, v239
	v_pk_fma_f32 v[12:13], v[12:13], v[136:137], v[248:249]
	v_pk_fma_f32 v[14:15], v[14:15], v[138:139], v[250:251]
	v_pk_fma_f32 v[8:9], v[8:9], v[140:141], v[252:253]
	v_pk_fma_f32 v[10:11], v[10:11], v[142:143], v[254:255]
	v_cvt_pk_bf16_f32 v12, v12, v13
	v_cvt_pk_bf16_f32 v13, v14, v15
	v_cvt_pk_bf16_f32 v14, v8, v9
	v_cvt_pk_bf16_f32 v15, v10, v11
	v_add_u32_e32 v146, 0x50000, v144
	global_store_dwordx4 v146, v[12:15], s[14:15] offset:256
	s_waitcnt vmcnt(15)
	v_lshlrev_b32_e32 v248, 16, v240
	v_and_b32_e32 v249, 0xffff0000, v240
	v_lshlrev_b32_e32 v250, 16, v241
	v_and_b32_e32 v251, 0xffff0000, v241
	v_lshlrev_b32_e32 v252, 16, v242
	v_and_b32_e32 v253, 0xffff0000, v242
	v_lshlrev_b32_e32 v254, 16, v243
	v_and_b32_e32 v255, 0xffff0000, v243
	v_pk_fma_f32 v[20:21], v[20:21], v[128:129], v[248:249]
	v_pk_fma_f32 v[22:23], v[22:23], v[130:131], v[250:251]
	v_pk_fma_f32 v[16:17], v[16:17], v[132:133], v[252:253]
	v_pk_fma_f32 v[18:19], v[18:19], v[134:135], v[254:255]
	v_cvt_pk_bf16_f32 v20, v20, v21
	v_cvt_pk_bf16_f32 v21, v22, v23
	v_cvt_pk_bf16_f32 v22, v16, v17
	v_cvt_pk_bf16_f32 v23, v18, v19
	v_add_u32_e32 v146, 0x58000, v144
	global_store_dwordx4 v146, v[20:23], s[14:15]
	s_waitcnt vmcnt(15)
	v_lshlrev_b32_e32 v248, 16, v244
	v_and_b32_e32 v249, 0xffff0000, v244
	v_lshlrev_b32_e32 v250, 16, v245
	v_and_b32_e32 v251, 0xffff0000, v245
	v_lshlrev_b32_e32 v252, 16, v246
	v_and_b32_e32 v253, 0xffff0000, v246
	v_lshlrev_b32_e32 v254, 16, v247
	v_and_b32_e32 v255, 0xffff0000, v247
	v_pk_fma_f32 v[4:5], v[4:5], v[136:137], v[248:249]
	v_pk_fma_f32 v[6:7], v[6:7], v[138:139], v[250:251]
	v_pk_fma_f32 v[0:1], v[0:1], v[140:141], v[252:253]
	v_pk_fma_f32 v[2:3], v[2:3], v[142:143], v[254:255]
	v_cvt_pk_bf16_f32 v4, v4, v5
	v_cvt_pk_bf16_f32 v5, v6, v7
	v_cvt_pk_bf16_f32 v6, v0, v1
	v_cvt_pk_bf16_f32 v7, v2, v3
	v_add_u32_e32 v146, 0x58000, v144
	global_store_dwordx4 v146, v[4:7], s[14:15] offset:256
	s_and_b64 vcc, exec, s[4:5]
	s_cbranch_vccz .LBB0_917
	s_waitcnt vmcnt(0)
	s_cmpk_gt_u32 s42, 0xff
	s_cbranch_scc1 .LBB0_932
	s_barrier
